# m4 waitcnt fixes + GEMM compute blocks aligned to 64B fetch lines
# speedup vs baseline: 1.0118x; 1.0014x over previous
; #define PG8_STAGE(bufoff, gbase, voff) do { _Pragma("unroll") for (int _i = 0; _i < 2; ++_i) \
;         __builtin_amdgcn_global_load_lds((const unsigned*)((const char*)(gbase) + (voff)[_i]), (PG8_LAS unsigned*)(lds + (bufoff) + ldsw + _i * 8192), 16, 0, 0); } while (0)
; #define PG8_LDA(dst, b, h) do { _Pragma("unroll") for (int m = 0; m < 4; ++m) _Pragma("unroll") for (int k = 0; k < 2; ++k) dst[m][k] = *(const PG8_LAS bf16x8*)(lds + PG8_SA(b, h) + aoffk[k] + m * 2048); } while (0)
; #define PG8_LDB(dst, b, h) do { _Pragma("unroll") for (int n = 0; n < 2; ++n) _Pragma("unroll") for (int k = 0; k < 2; ++k) dst[n][k] = *(const PG8_LAS bf16x8*)(lds + PG8_SB(b, h) + boffk[k] + n * 2048); } while (0)
; #define PG8_MMA(ai, bj, At, Bt) do { __builtin_amdgcn_s_setprio(1); _Pragma("unroll") for (int m = 0; m < 4; ++m) _Pragma("unroll") for (int n = 0; n < 2; ++n) _Pragma("unroll") for (int k = 0; k < 2; ++k) \
;         acc[ai][bj][m][n] = __builtin_amdgcn_mfma_f32_16x16x32_bf16(Bt[n][k], At[m][k], acc[ai][bj][m][n], 0, 0, 0); __builtin_amdgcn_s_setprio(0); } while (0)
; #define PG8_WAIT_V(n) asm volatile("s_waitcnt vmcnt(" #n ")" ::: "memory")
; #define PG8_WAIT_L(n) asm volatile("s_waitcnt lgkmcnt(" #n ")" ::: "memory")
; #define PG8_BAR __builtin_amdgcn_s_barrier()
; template <class Epi, class Sched, bool ALIGN_EPI = false, bool SP2 = false>
; __device__ __forceinline__ void gemm_phase(PG8_LAS unsigned char* lds, const Gemm g, const Sched& S, const Epi& E) {
;     ...
;             const bool last = (t == nt - 2);
;             const char* a1 = cA + (size_t)(t + 1) * kstep;
;             const char* a2 = last ? nA : cA + (size_t)(t + 2) * kstep; const char* b2 = last ? nB : cB + (size_t)(t + 2) * kstep;
;             const char* a3 = a2 + kstep; const char* b3 = b2 + kstep;
;             if (last && has_next) S.a_ready(nxt);
;             if constexpr (SP2) {
;             PG8_LDB(B0, 0, 0); PG8_LDB(B1, 0, 1); PG8_SCHED; PG8_LDA(At, 0, 0); PG8_STAGE(PG8_SA(1, 1), a1 + hstepA, voffA);
;             PG8_WAIT_V(8); PG8_WAIT_L(0); PG8_BAR; PG8_MMA(0, 0, At, B0); PG8_MMA(0, 1, At, B1); PG8_BAR; PG8_SCHED;
;             PG8_LDA(At, 0, 1); PG8_STAGE(PG8_SB(0, 0), b2, voffB); PG8_STAGE(PG8_SB(0, 1), b2 + hstepB, voffB); PG8_STAGE(PG8_SA(0, 0), a2, voffA);
;             PG8_WAIT_V(8); PG8_WAIT_L(0); PG8_BAR; PG8_MMA(1, 0, At, B0); PG8_MMA(1, 1, At, B1); PG8_BAR; PG8_SCHED;
.LBB0_296:
	s_add_u32 s22, s20, 0xfff80080
	s_addc_u32 s23, s21, -1
	s_add_i32 s47, 0, 0x10000
	s_cmp_eq_u32 s46, 28
	s_cselect_b32 s25, s11, s23
	s_cselect_b32 s24, s33, s22
	s_cselect_b32 s23, s9, s45
	s_cselect_b32 s22, s43, s44
	s_add_i32 s50, 0, 0x14000
	v_add_u32_e32 v142, s47, v147
	v_add_u32_e32 v156, s47, v148
	v_add_u32_e32 v168, s50, v147
	v_add_u32_e32 v176, s50, v148
	ds_read_b128 v[142:145], v142
	ds_read_b128 v[156:159], v156
	ds_read_b128 v[160:163], v150
	ds_read_b128 v[164:167], v151
	ds_read_b128 v[172:175], v168
	ds_read_b128 v[176:179], v176
	ds_read_b128 v[180:183], v152
	ds_read_b128 v[184:187], v153
	v_lshl_add_u64 v[212:213], s[20:21], 0, v[138:139]
	s_add_i32 m0, s36, 0xc000
	ds_read_b128 v[188:191], v154
	ds_read_b128 v[192:195], v154 offset:1024
	ds_read_b128 v[196:199], v154 offset:2048
	ds_read_b128 v[200:203], v154 offset:3072
	ds_read_b128 v[204:207], v154 offset:4096
	ds_read_b128 v[208:211], v154 offset:5120
	ds_read_b128 v[226:229], v154 offset:6144
	ds_read_b128 v[230:233], v154 offset:7168
	global_load_lds_dwordx4 v[212:213], off
	v_lshl_add_u64 v[212:213], s[20:21], 0, v[140:141]
	s_add_i32 m0, s36, 0xe000
	s_nop 0
	global_load_lds_dwordx4 v[212:213], off
	s_nop 0
	s_waitcnt vmcnt(8)
	s_waitcnt lgkmcnt(0)
	s_barrier
	v_mfma_f32_16x16x32_bf16 v[128:131], v[142:145], v[188:191], v[128:131]
	v_mfma_f32_16x16x32_bf16 v[120:123], v[160:163], v[188:191], v[120:123]
	v_mfma_f32_16x16x32_bf16 v[112:115], v[142:145], v[196:199], v[112:115]
	v_mfma_f32_16x16x32_bf16 v[104:107], v[160:163], v[196:199], v[104:107]
	v_mfma_f32_16x16x32_bf16 v[96:99], v[142:145], v[204:207], v[96:99]
	v_mfma_f32_16x16x32_bf16 v[88:91], v[160:163], v[204:207], v[88:91]
	v_mfma_f32_16x16x32_bf16 v[80:83], v[142:145], v[226:229], v[80:83]
	v_mfma_f32_16x16x32_bf16 v[72:75], v[160:163], v[226:229], v[72:75]
	v_mfma_f32_16x16x32_bf16 v[128:131], v[156:159], v[192:195], v[128:131]
	v_mfma_f32_16x16x32_bf16 v[120:123], v[164:167], v[192:195], v[120:123]
	v_mfma_f32_16x16x32_bf16 v[112:115], v[156:159], v[200:203], v[112:115]
	v_mfma_f32_16x16x32_bf16 v[104:107], v[164:167], v[200:203], v[104:107]
	v_mfma_f32_16x16x32_bf16 v[96:99], v[156:159], v[208:211], v[96:99]
	v_mfma_f32_16x16x32_bf16 v[88:91], v[164:167], v[208:211], v[88:91]
	v_mfma_f32_16x16x32_bf16 v[80:83], v[156:159], v[230:233], v[80:83]
	v_mfma_f32_16x16x32_bf16 v[72:75], v[164:167], v[230:233], v[72:75]
	v_mfma_f32_16x16x32_bf16 v[124:127], v[172:175], v[188:191], v[124:127]
	v_mfma_f32_16x16x32_bf16 v[116:119], v[180:183], v[188:191], v[116:119]
	v_mfma_f32_16x16x32_bf16 v[108:111], v[172:175], v[196:199], v[108:111]
	v_mfma_f32_16x16x32_bf16 v[100:103], v[180:183], v[196:199], v[100:103]
	v_mfma_f32_16x16x32_bf16 v[92:95], v[172:175], v[204:207], v[92:95]
	v_mfma_f32_16x16x32_bf16 v[84:87], v[180:183], v[204:207], v[84:87]
	v_mfma_f32_16x16x32_bf16 v[76:79], v[172:175], v[226:229], v[76:79]
	v_mfma_f32_16x16x32_bf16 v[68:71], v[180:183], v[226:229], v[68:71]
	v_mfma_f32_16x16x32_bf16 v[124:127], v[176:179], v[192:195], v[124:127]
	v_mfma_f32_16x16x32_bf16 v[116:119], v[184:187], v[192:195], v[116:119]
	v_mfma_f32_16x16x32_bf16 v[108:111], v[176:179], v[200:203], v[108:111]
	v_mfma_f32_16x16x32_bf16 v[100:103], v[184:187], v[200:203], v[100:103]
	v_mfma_f32_16x16x32_bf16 v[92:95], v[176:179], v[208:211], v[92:95]
	v_mfma_f32_16x16x32_bf16 v[84:87], v[184:187], v[208:211], v[84:87]
	v_mfma_f32_16x16x32_bf16 v[76:79], v[176:179], v[230:233], v[76:79]
	v_mfma_f32_16x16x32_bf16 v[68:71], v[184:187], v[230:233], v[68:71]
	s_barrier
	s_add_i32 s47, s47, s34
	v_lshl_add_u64 v[212:213], s[22:23], 0, v[2:3]
	s_mov_b32 m0, s47
	ds_read_b128 v[188:191], v154 offset:16384
	ds_read_b128 v[192:195], v154 offset:17408
	ds_read_b128 v[196:199], v154 offset:18432
	ds_read_b128 v[200:203], v154 offset:19456
	ds_read_b128 v[204:207], v154 offset:20480
	ds_read_b128 v[208:211], v154 offset:21504
	ds_read_b128 v[226:229], v154 offset:22528
	ds_read_b128 v[230:233], v154 offset:23552
	global_load_lds_dwordx4 v[212:213], off
	s_add_i32 m0, s47, 0x2000
	s_add_u32 s48, s22, 0x80000
	v_lshl_add_u64 v[234:235], s[22:23], 0, v[132:133]
	s_addc_u32 s49, s23, 0
	s_add_i32 s47, s50, s34
	global_load_lds_dwordx4 v[234:235], off
	v_lshl_add_u64 v[236:237], s[48:49], 0, v[2:3]
	s_mov_b32 m0, s47
	v_lshl_add_u64 v[238:239], s[24:25], 0, v[134:135]
	global_load_lds_dwordx4 v[236:237], off
	v_lshl_add_u64 v[236:237], s[48:49], 0, v[132:133]
	s_add_i32 m0, s47, 0x2000
	s_nop 0
	global_load_lds_dwordx4 v[236:237], off
	v_lshl_add_u64 v[236:237], s[24:25], 0, v[136:137]
	s_mov_b32 m0, s36
	s_nop 0
	global_load_lds_dwordx4 v[236:237], off
	s_mov_b32 m0, s37
	s_nop 0
	global_load_lds_dwordx4 v[238:239], off
	s_nop 0
	s_nop 0
	s_nop 0
	s_nop 0
	s_waitcnt vmcnt(8)
	s_waitcnt lgkmcnt(0)
	s_barrier
; #define PG8_STAGE(bufoff, gbase, voff) do { _Pragma("unroll") for (int _i = 0; _i < 2; ++_i) \
;         __builtin_amdgcn_global_load_lds((const unsigned*)((const char*)(gbase) + (voff)[_i]), (PG8_LAS unsigned*)(lds + (bufoff) + ldsw + _i * 8192), 16, 0, 0); } while (0)
; #define PG8_LDA(dst, b, h) do { _Pragma("unroll") for (int m = 0; m < 4; ++m) _Pragma("unroll") for (int k = 0; k < 2; ++k) dst[m][k] = *(const PG8_LAS bf16x8*)(lds + PG8_SA(b, h) + aoffk[k] + m * 2048); } while (0)
; #define PG8_LDB(dst, b, h) do { _Pragma("unroll") for (int n = 0; n < 2; ++n) _Pragma("unroll") for (int k = 0; k < 2; ++k) dst[n][k] = *(const PG8_LAS bf16x8*)(lds + PG8_SB(b, h) + boffk[k] + n * 2048); } while (0)
; #define PG8_MMA(ai, bj, At, Bt) do { __builtin_amdgcn_s_setprio(1); _Pragma("unroll") for (int m = 0; m < 4; ++m) _Pragma("unroll") for (int n = 0; n < 2; ++n) _Pragma("unroll") for (int k = 0; k < 2; ++k) \
;         acc[ai][bj][m][n] = __builtin_amdgcn_mfma_f32_16x16x32_bf16(Bt[n][k], At[m][k], acc[ai][bj][m][n], 0, 0, 0); __builtin_amdgcn_s_setprio(0); } while (0)
; #define PG8_WAIT_V(n) asm volatile("s_waitcnt vmcnt(" #n ")" ::: "memory")
; #define PG8_WAIT_L(n) asm volatile("s_waitcnt lgkmcnt(" #n ")" ::: "memory")
; #define PG8_BAR __builtin_amdgcn_s_barrier()
; #define PG8_SCHED __builtin_amdgcn_sched_barrier(0)
; template <class Epi, class Sched, bool ALIGN_EPI = false, bool SP2 = false>
; __device__ __forceinline__ void gemm_phase(PG8_LAS unsigned char* lds, const Gemm g, const Sched& S, const Epi& E) {
;     ...
;             PG8_WAIT_V(8); PG8_WAIT_L(0); PG8_BAR; PG8_MMA(1, 0, At, B0); PG8_MMA(1, 1, At, B1); PG8_BAR; PG8_SCHED;
;             PG8_LDB(B0, 1, 0); PG8_LDB(B1, 1, 1); PG8_SCHED; PG8_LDA(At, 1, 0); PG8_STAGE(PG8_SA(0, 1), a2 + hstepA, voffA);
;             PG8_WAIT_V(8); PG8_WAIT_L(0); PG8_BAR; PG8_MMA(0, 0, At, B0); PG8_MMA(0, 1, At, B1); PG8_BAR; PG8_SCHED;
	v_mfma_f32_16x16x32_bf16 v[64:67], v[142:145], v[188:191], v[64:67]
	v_mfma_f32_16x16x32_bf16 v[56:59], v[160:163], v[188:191], v[56:59]
	v_mfma_f32_16x16x32_bf16 v[48:51], v[142:145], v[196:199], v[48:51]
	v_mfma_f32_16x16x32_bf16 v[40:43], v[160:163], v[196:199], v[40:43]
	v_mfma_f32_16x16x32_bf16 v[32:35], v[142:145], v[204:207], v[32:35]
	v_mfma_f32_16x16x32_bf16 v[24:27], v[160:163], v[204:207], v[24:27]
	v_mfma_f32_16x16x32_bf16 v[16:19], v[142:145], v[226:229], v[16:19]
	v_mfma_f32_16x16x32_bf16 v[8:11], v[160:163], v[226:229], v[8:11]
	v_mfma_f32_16x16x32_bf16 v[64:67], v[156:159], v[192:195], v[64:67]
	v_mfma_f32_16x16x32_bf16 v[56:59], v[164:167], v[192:195], v[56:59]
	v_mfma_f32_16x16x32_bf16 v[48:51], v[156:159], v[200:203], v[48:51]
	v_mfma_f32_16x16x32_bf16 v[40:43], v[164:167], v[200:203], v[40:43]
	v_mfma_f32_16x16x32_bf16 v[32:35], v[156:159], v[208:211], v[32:35]
	v_mfma_f32_16x16x32_bf16 v[24:27], v[164:167], v[208:211], v[24:27]
	v_mfma_f32_16x16x32_bf16 v[16:19], v[156:159], v[230:233], v[16:19]
	v_mfma_f32_16x16x32_bf16 v[8:11], v[164:167], v[230:233], v[8:11]
	v_mfma_f32_16x16x32_bf16 v[60:63], v[172:175], v[188:191], v[60:63]
	v_mfma_f32_16x16x32_bf16 v[52:55], v[180:183], v[188:191], v[52:55]
	v_mfma_f32_16x16x32_bf16 v[44:47], v[172:175], v[196:199], v[44:47]
	v_mfma_f32_16x16x32_bf16 v[36:39], v[180:183], v[196:199], v[36:39]
	v_mfma_f32_16x16x32_bf16 v[28:31], v[172:175], v[204:207], v[28:31]
	v_mfma_f32_16x16x32_bf16 v[20:23], v[180:183], v[204:207], v[20:23]
	v_mfma_f32_16x16x32_bf16 v[12:15], v[172:175], v[226:229], v[12:15]
	v_mfma_f32_16x16x32_bf16 v[4:7], v[180:183], v[226:229], v[4:7]
	v_mfma_f32_16x16x32_bf16 v[60:63], v[176:179], v[192:195], v[60:63]
	v_mfma_f32_16x16x32_bf16 v[52:55], v[184:187], v[192:195], v[52:55]
	v_mfma_f32_16x16x32_bf16 v[44:47], v[176:179], v[200:203], v[44:47]
	v_mfma_f32_16x16x32_bf16 v[36:39], v[184:187], v[200:203], v[36:39]
	v_mfma_f32_16x16x32_bf16 v[28:31], v[176:179], v[208:211], v[28:31]
	v_mfma_f32_16x16x32_bf16 v[20:23], v[184:187], v[208:211], v[20:23]
	v_mfma_f32_16x16x32_bf16 v[12:15], v[176:179], v[230:233], v[12:15]
	v_mfma_f32_16x16x32_bf16 v[4:7], v[184:187], v[230:233], v[4:7]
	s_barrier
	s_add_i32 s47, 0, 0x18000
	s_add_i32 s48, 0, 0x1c000
	v_add_u32_e32 v142, s47, v147
	v_add_u32_e32 v156, s47, v148
	v_add_u32_e32 v164, s52, v148
	v_add_u32_e32 v168, s48, v147
	v_add_u32_e32 v176, s48, v148
	ds_read_b128 v[142:145], v142
	ds_read_b128 v[156:159], v156
	ds_read_b128 v[160:163], v155
	ds_read_b128 v[164:167], v164
	ds_read_b128 v[172:175], v168
	ds_read_b128 v[176:179], v176
	v_add_u32_e32 v168, s53, v147
	v_add_u32_e32 v184, s53, v148
	ds_read_b128 v[180:183], v168
	ds_read_b128 v[184:187], v184
	s_add_u32 s24, s24, 0x80000
	s_addc_u32 s25, s25, 0
	s_mov_b32 m0, s38
	v_lshl_add_u64 v[240:241], s[24:25], 0, v[136:137]
	ds_read_b128 v[188:191], v154 offset:32768
	ds_read_b128 v[192:195], v154 offset:33792
	ds_read_b128 v[196:199], v154 offset:34816
	ds_read_b128 v[200:203], v154 offset:35840
	ds_read_b128 v[204:207], v154 offset:36864
	ds_read_b128 v[208:211], v154 offset:37888
	ds_read_b128 v[226:229], v154 offset:38912
	ds_read_b128 v[230:233], v154 offset:39936
	global_load_lds_dwordx4 v[240:241], off
	v_lshl_add_u64 v[240:241], s[24:25], 0, v[134:135]
	s_mov_b32 m0, s39
	s_nop 0
	global_load_lds_dwordx4 v[240:241], off
	s_nop 0
	s_nop 0
	s_nop 0
	s_waitcnt vmcnt(8)
	s_waitcnt lgkmcnt(0)
	s_barrier
	v_mfma_f32_16x16x32_bf16 v[128:131], v[142:145], v[188:191], v[128:131]
	v_mfma_f32_16x16x32_bf16 v[120:123], v[160:163], v[188:191], v[120:123]
	v_mfma_f32_16x16x32_bf16 v[112:115], v[142:145], v[196:199], v[112:115]
	v_mfma_f32_16x16x32_bf16 v[104:107], v[160:163], v[196:199], v[104:107]
	v_mfma_f32_16x16x32_bf16 v[96:99], v[142:145], v[204:207], v[96:99]
	v_mfma_f32_16x16x32_bf16 v[88:91], v[160:163], v[204:207], v[88:91]
	v_mfma_f32_16x16x32_bf16 v[80:83], v[142:145], v[226:229], v[80:83]
	v_mfma_f32_16x16x32_bf16 v[72:75], v[160:163], v[226:229], v[72:75]
	v_mfma_f32_16x16x32_bf16 v[128:131], v[156:159], v[192:195], v[128:131]
	v_mfma_f32_16x16x32_bf16 v[120:123], v[164:167], v[192:195], v[120:123]
	v_mfma_f32_16x16x32_bf16 v[112:115], v[156:159], v[200:203], v[112:115]
	v_mfma_f32_16x16x32_bf16 v[104:107], v[164:167], v[200:203], v[104:107]
	v_mfma_f32_16x16x32_bf16 v[96:99], v[156:159], v[208:211], v[96:99]
	v_mfma_f32_16x16x32_bf16 v[88:91], v[164:167], v[208:211], v[88:91]
	v_mfma_f32_16x16x32_bf16 v[80:83], v[156:159], v[230:233], v[80:83]
	v_mfma_f32_16x16x32_bf16 v[72:75], v[164:167], v[230:233], v[72:75]
	v_mfma_f32_16x16x32_bf16 v[124:127], v[172:175], v[188:191], v[124:127]
	v_mfma_f32_16x16x32_bf16 v[116:119], v[180:183], v[188:191], v[116:119]
	v_mfma_f32_16x16x32_bf16 v[108:111], v[172:175], v[196:199], v[108:111]
	v_mfma_f32_16x16x32_bf16 v[100:103], v[180:183], v[196:199], v[100:103]
	v_mfma_f32_16x16x32_bf16 v[92:95], v[172:175], v[204:207], v[92:95]
	v_mfma_f32_16x16x32_bf16 v[84:87], v[180:183], v[204:207], v[84:87]
	v_mfma_f32_16x16x32_bf16 v[76:79], v[172:175], v[226:229], v[76:79]
	v_mfma_f32_16x16x32_bf16 v[68:71], v[180:183], v[226:229], v[68:71]
	v_mfma_f32_16x16x32_bf16 v[124:127], v[176:179], v[192:195], v[124:127]
	v_mfma_f32_16x16x32_bf16 v[116:119], v[184:187], v[192:195], v[116:119]
	v_mfma_f32_16x16x32_bf16 v[108:111], v[176:179], v[200:203], v[108:111]
	v_mfma_f32_16x16x32_bf16 v[100:103], v[184:187], v[200:203], v[100:103]
	v_mfma_f32_16x16x32_bf16 v[92:95], v[176:179], v[208:211], v[92:95]
	v_mfma_f32_16x16x32_bf16 v[84:87], v[184:187], v[208:211], v[84:87]
	v_mfma_f32_16x16x32_bf16 v[76:79], v[176:179], v[230:233], v[76:79]
	v_mfma_f32_16x16x32_bf16 v[68:71], v[184:187], v[230:233], v[68:71]
	s_barrier
; #define PG8_STAGE(bufoff, gbase, voff) do { _Pragma("unroll") for (int _i = 0; _i < 2; ++_i) \
;         __builtin_amdgcn_global_load_lds((const unsigned*)((const char*)(gbase) + (voff)[_i]), (PG8_LAS unsigned*)(lds + (bufoff) + ldsw + _i * 8192), 16, 0, 0); } while (0)
; #define PG8_LDA(dst, b, h) do { _Pragma("unroll") for (int m = 0; m < 4; ++m) _Pragma("unroll") for (int k = 0; k < 2; ++k) dst[m][k] = *(const PG8_LAS bf16x8*)(lds + PG8_SA(b, h) + aoffk[k] + m * 2048); } while (0)
; #define PG8_MMA(ai, bj, At, Bt) do { __builtin_amdgcn_s_setprio(1); _Pragma("unroll") for (int m = 0; m < 4; ++m) _Pragma("unroll") for (int n = 0; n < 2; ++n) _Pragma("unroll") for (int k = 0; k < 2; ++k) \
;         acc[ai][bj][m][n] = __builtin_amdgcn_mfma_f32_16x16x32_bf16(Bt[n][k], At[m][k], acc[ai][bj][m][n], 0, 0, 0); __builtin_amdgcn_s_setprio(0); } while (0)
; #define PG8_WAIT_V(n) asm volatile("s_waitcnt vmcnt(" #n ")" ::: "memory")
; #define PG8_WAIT_L(n) asm volatile("s_waitcnt lgkmcnt(" #n ")" ::: "memory")
; #define PG8_BAR __builtin_amdgcn_s_barrier()
; #define PG8_SCHED __builtin_amdgcn_sched_barrier(0)
; template <class Epi, class Sched, bool ALIGN_EPI = false, bool SP2 = false>
; __device__ __forceinline__ void gemm_phase(PG8_LAS unsigned char* lds, const Gemm g, const Sched& S, const Epi& E) {
;     ...
;             PG8_LDA(At, 1, 1); PG8_STAGE(PG8_SB(1, 0), b3, voffB); PG8_STAGE(PG8_SB(1, 1), b3 + hstepB, voffB); PG8_STAGE(PG8_SA(1, 0), a3, voffA);
;             PG8_WAIT_V(8); PG8_WAIT_L(0); PG8_BAR; PG8_MMA(1, 0, At, B0); PG8_MMA(1, 1, At, B1); PG8_BAR; PG8_SCHED;
	s_add_i32 s24, s47, s34
	v_lshl_add_u64 v[212:213], v[212:213], 0, s[56:57]
	s_mov_b32 m0, s24
	ds_read_b128 v[188:191], v154 offset:49152
	ds_read_b128 v[192:195], v154 offset:50176
	ds_read_b128 v[196:199], v154 offset:51200
	ds_read_b128 v[200:203], v154 offset:52224
	ds_read_b128 v[204:207], v154 offset:53248
	ds_read_b128 v[208:211], v154 offset:54272
	ds_read_b128 v[226:229], v154 offset:55296
	ds_read_b128 v[230:233], v154 offset:56320
	global_load_lds_dwordx4 v[212:213], off
	s_add_i32 m0, s24, 0x2000
	s_add_u32 s22, s22, 0x80080
	v_lshl_add_u64 v[212:213], v[234:235], 0, s[56:57]
	s_addc_u32 s23, s23, 0
	s_add_i32 s24, s48, s34
	global_load_lds_dwordx4 v[212:213], off
	v_lshl_add_u64 v[212:213], s[22:23], 0, v[2:3]
	s_mov_b32 m0, s24
	s_nop 0
	global_load_lds_dwordx4 v[212:213], off
	v_lshl_add_u64 v[212:213], s[22:23], 0, v[132:133]
	s_add_i32 m0, s24, 0x2000
	s_nop 0
	global_load_lds_dwordx4 v[212:213], off
	v_lshl_add_u64 v[212:213], v[236:237], 0, s[56:57]
	s_mov_b32 m0, s40
	s_nop 0
	global_load_lds_dwordx4 v[212:213], off
	v_lshl_add_u64 v[212:213], v[238:239], 0, s[56:57]
	s_mov_b32 m0, s41
	s_nop 0
	global_load_lds_dwordx4 v[212:213], off
	s_nop 0
	s_nop 0
	s_nop 0
	s_waitcnt vmcnt(8)
	s_waitcnt lgkmcnt(0)
	s_barrier
	v_mfma_f32_16x16x32_bf16 v[64:67], v[142:145], v[188:191], v[64:67]
	v_mfma_f32_16x16x32_bf16 v[56:59], v[160:163], v[188:191], v[56:59]
	v_mfma_f32_16x16x32_bf16 v[48:51], v[142:145], v[196:199], v[48:51]
	v_mfma_f32_16x16x32_bf16 v[40:43], v[160:163], v[196:199], v[40:43]
	v_mfma_f32_16x16x32_bf16 v[32:35], v[142:145], v[204:207], v[32:35]
	v_mfma_f32_16x16x32_bf16 v[24:27], v[160:163], v[204:207], v[24:27]
	v_mfma_f32_16x16x32_bf16 v[16:19], v[142:145], v[226:229], v[16:19]
	v_mfma_f32_16x16x32_bf16 v[8:11], v[160:163], v[226:229], v[8:11]
	v_mfma_f32_16x16x32_bf16 v[64:67], v[156:159], v[192:195], v[64:67]
	v_mfma_f32_16x16x32_bf16 v[56:59], v[164:167], v[192:195], v[56:59]
	v_mfma_f32_16x16x32_bf16 v[48:51], v[156:159], v[200:203], v[48:51]
	v_mfma_f32_16x16x32_bf16 v[40:43], v[164:167], v[200:203], v[40:43]
	v_mfma_f32_16x16x32_bf16 v[32:35], v[156:159], v[208:211], v[32:35]
	v_mfma_f32_16x16x32_bf16 v[24:27], v[164:167], v[208:211], v[24:27]
	v_mfma_f32_16x16x32_bf16 v[16:19], v[156:159], v[230:233], v[16:19]
	v_mfma_f32_16x16x32_bf16 v[8:11], v[164:167], v[230:233], v[8:11]
	v_mfma_f32_16x16x32_bf16 v[60:63], v[172:175], v[188:191], v[60:63]
	v_mfma_f32_16x16x32_bf16 v[52:55], v[180:183], v[188:191], v[52:55]
	v_mfma_f32_16x16x32_bf16 v[44:47], v[172:175], v[196:199], v[44:47]
	v_mfma_f32_16x16x32_bf16 v[36:39], v[180:183], v[196:199], v[36:39]
	v_mfma_f32_16x16x32_bf16 v[28:31], v[172:175], v[204:207], v[28:31]
	v_mfma_f32_16x16x32_bf16 v[20:23], v[180:183], v[204:207], v[20:23]
	v_mfma_f32_16x16x32_bf16 v[12:15], v[172:175], v[226:229], v[12:15]
	v_mfma_f32_16x16x32_bf16 v[4:7], v[180:183], v[226:229], v[4:7]
	v_mfma_f32_16x16x32_bf16 v[60:63], v[176:179], v[192:195], v[60:63]
	v_mfma_f32_16x16x32_bf16 v[52:55], v[184:187], v[192:195], v[52:55]
	v_mfma_f32_16x16x32_bf16 v[44:47], v[176:179], v[200:203], v[44:47]
	v_mfma_f32_16x16x32_bf16 v[36:39], v[184:187], v[200:203], v[36:39]
	v_mfma_f32_16x16x32_bf16 v[28:31], v[176:179], v[208:211], v[28:31]
	v_mfma_f32_16x16x32_bf16 v[20:23], v[184:187], v[208:211], v[20:23]
	v_mfma_f32_16x16x32_bf16 v[12:15], v[176:179], v[230:233], v[12:15]
	v_mfma_f32_16x16x32_bf16 v[4:7], v[184:187], v[230:233], v[4:7]
	s_barrier
	s_add_i32 s46, s46, 2
	s_add_u32 s20, s20, 0x100
	s_addc_u32 s21, s21, 0
	s_add_u32 s44, s44, 0x100
	s_addc_u32 s45, s45, 0
	s_cmp_gt_u32 s46, 29
	s_cbranch_scc0 .LBB0_296
	s_and_b64 vcc, exec, s[6:7]
	s_cbranch_vccz .LBB0_299
	s_barrier

; #define PG8_STAGE(bufoff, gbase, voff) do { _Pragma("unroll") for (int _i = 0; _i < 2; ++_i) \
;         __builtin_amdgcn_global_load_lds((const unsigned*)((const char*)(gbase) + (voff)[_i]), (PG8_LAS unsigned*)(lds + (bufoff) + ldsw + _i * 8192), 16, 0, 0); } while (0)
; #define PG8_LDA(dst, b, h) do { _Pragma("unroll") for (int m = 0; m < 4; ++m) _Pragma("unroll") for (int k = 0; k < 2; ++k) dst[m][k] = *(const PG8_LAS bf16x8*)(lds + PG8_SA(b, h) + aoffk[k] + m * 2048); } while (0)
; #define PG8_LDB(dst, b, h) do { _Pragma("unroll") for (int n = 0; n < 2; ++n) _Pragma("unroll") for (int k = 0; k < 2; ++k) dst[n][k] = *(const PG8_LAS bf16x8*)(lds + PG8_SB(b, h) + boffk[k] + n * 2048); } while (0)
; #define PG8_MMA(ai, bj, At, Bt) do { __builtin_amdgcn_s_setprio(1); _Pragma("unroll") for (int m = 0; m < 4; ++m) _Pragma("unroll") for (int n = 0; n < 2; ++n) _Pragma("unroll") for (int k = 0; k < 2; ++k) \
;         acc[ai][bj][m][n] = __builtin_amdgcn_mfma_f32_16x16x32_bf16(Bt[n][k], At[m][k], acc[ai][bj][m][n], 0, 0, 0); __builtin_amdgcn_s_setprio(0); } while (0)
; #define PG8_WAIT_V(n) asm volatile("s_waitcnt vmcnt(" #n ")" ::: "memory")
; #define PG8_WAIT_L(n) asm volatile("s_waitcnt lgkmcnt(" #n ")" ::: "memory")
; #define PG8_BAR __builtin_amdgcn_s_barrier()
; template <class Epi, class Sched, bool ALIGN_EPI = false, bool SP2 = false>
; __device__ __forceinline__ void gemm_phase(PG8_LAS unsigned char* lds, const Gemm g, const Sched& S, const Epi& E) {
;     ...
;             const bool last = (t == nt - 2);
;             const char* a1 = cA + (size_t)(t + 1) * kstep;
;             const char* a2 = last ? nA : cA + (size_t)(t + 2) * kstep; const char* b2 = last ? nB : cB + (size_t)(t + 2) * kstep;
;             const char* a3 = a2 + kstep; const char* b3 = b2 + kstep;
;             if (last && has_next) S.a_ready(nxt);
;             if constexpr (SP2) {
;             PG8_LDB(B0, 0, 0); PG8_LDB(B1, 0, 1); PG8_SCHED; PG8_LDA(At, 0, 0); PG8_STAGE(PG8_SA(1, 1), a1 + hstepA, voffA);
;             PG8_WAIT_V(8); PG8_WAIT_L(0); PG8_BAR; PG8_MMA(0, 0, At, B0); PG8_MMA(0, 1, At, B1); PG8_BAR; PG8_SCHED;
;             PG8_LDA(At, 0, 1); PG8_STAGE(PG8_SB(0, 0), b2, voffB); PG8_STAGE(PG8_SB(0, 1), b2 + hstepB, voffB); PG8_STAGE(PG8_SA(0, 0), a2, voffA);
;             PG8_WAIT_V(8); PG8_WAIT_L(0); PG8_BAR; PG8_MMA(1, 0, At, B0); PG8_MMA(1, 1, At, B1); PG8_BAR; PG8_SCHED;
.LBB0_430:
	s_add_i32 s51, s18, 2
	s_add_u32 s16, s14, 0x100
	s_addc_u32 s17, s15, 0
	s_add_i32 s52, 0, 0x10000
	s_cmp_eq_u32 s9, s18
	v_add_u32_e32 v142, s52, v145
	s_cselect_b32 s21, s11, s17
	s_cselect_b32 s20, s10, s16
	v_add_u32_e32 v143, s52, v146
	ds_read_b128 v[150:153], v142
	ds_read_b128 v[154:157], v143
	v_add_u32_e32 v142, s54, v145
	s_cselect_b32 s19, s13, s50
	s_cselect_b32 s18, s12, s49
	s_add_i32 s53, 0, 0x14000
	v_add_u32_e32 v143, s54, v146
	ds_read_b128 v[158:161], v142
	ds_read_b128 v[162:165], v143
	v_add_u32_e32 v142, s53, v145
	v_add_u32_e32 v143, s53, v146
	ds_read_b128 v[172:175], v142
	ds_read_b128 v[176:179], v143
	v_add_u32_e32 v142, s55, v145
	v_add_u32_e32 v143, s55, v146
	ds_read_b128 v[180:183], v142
	ds_read_b128 v[184:187], v143
	v_lshl_add_u64 v[142:143], s[14:15], 0, v[138:139]
	s_add_i32 m0, s28, 0xc000
	ds_read_b128 v[188:191], v148
	ds_read_b128 v[192:195], v148 offset:1024
	ds_read_b128 v[196:199], v148 offset:2048
	ds_read_b128 v[200:203], v148 offset:3072
	ds_read_b128 v[204:207], v148 offset:4096
	ds_read_b128 v[208:211], v148 offset:5120
	ds_read_b128 v[226:229], v148 offset:6144
	ds_read_b128 v[230:233], v148 offset:7168
	global_load_lds_dwordx4 v[142:143], off
	v_lshl_add_u64 v[142:143], s[14:15], 0, v[140:141]
	s_add_i32 m0, s28, 0xe000
	s_nop 0
	global_load_lds_dwordx4 v[142:143], off
	s_nop 0
	s_nop 0
	s_nop 0
	s_nop 0
	s_nop 0
	s_nop 0
	s_nop 0
	s_nop 0
	s_waitcnt vmcnt(8)
	s_waitcnt lgkmcnt(0)
	s_barrier
	v_mfma_f32_16x16x32_bf16 v[128:131], v[150:153], v[188:191], v[128:131]
	v_mfma_f32_16x16x32_bf16 v[124:127], v[158:161], v[188:191], v[124:127]
	v_mfma_f32_16x16x32_bf16 v[120:123], v[150:153], v[196:199], v[120:123]
	v_mfma_f32_16x16x32_bf16 v[112:115], v[158:161], v[196:199], v[112:115]
	v_mfma_f32_16x16x32_bf16 v[104:107], v[150:153], v[204:207], v[104:107]
	v_mfma_f32_16x16x32_bf16 v[96:99], v[158:161], v[204:207], v[96:99]
	v_mfma_f32_16x16x32_bf16 v[88:91], v[150:153], v[226:229], v[88:91]
	v_mfma_f32_16x16x32_bf16 v[80:83], v[158:161], v[226:229], v[80:83]
	v_mfma_f32_16x16x32_bf16 v[128:131], v[154:157], v[192:195], v[128:131]
	v_mfma_f32_16x16x32_bf16 v[124:127], v[162:165], v[192:195], v[124:127]
	v_mfma_f32_16x16x32_bf16 v[120:123], v[154:157], v[200:203], v[120:123]
	v_mfma_f32_16x16x32_bf16 v[112:115], v[162:165], v[200:203], v[112:115]
	v_mfma_f32_16x16x32_bf16 v[104:107], v[154:157], v[208:211], v[104:107]
	v_mfma_f32_16x16x32_bf16 v[96:99], v[162:165], v[208:211], v[96:99]
	v_mfma_f32_16x16x32_bf16 v[88:91], v[154:157], v[230:233], v[88:91]
	v_mfma_f32_16x16x32_bf16 v[80:83], v[162:165], v[230:233], v[80:83]
	v_mfma_f32_16x16x32_bf16 v[116:119], v[172:175], v[188:191], v[116:119]
	v_mfma_f32_16x16x32_bf16 v[108:111], v[180:183], v[188:191], v[108:111]
	v_mfma_f32_16x16x32_bf16 v[100:103], v[172:175], v[196:199], v[100:103]
	v_mfma_f32_16x16x32_bf16 v[92:95], v[180:183], v[196:199], v[92:95]
	v_mfma_f32_16x16x32_bf16 v[84:87], v[172:175], v[204:207], v[84:87]
	v_mfma_f32_16x16x32_bf16 v[76:79], v[180:183], v[204:207], v[76:79]
	v_mfma_f32_16x16x32_bf16 v[72:75], v[172:175], v[226:229], v[72:75]
	v_mfma_f32_16x16x32_bf16 v[68:71], v[180:183], v[226:229], v[68:71]
	v_mfma_f32_16x16x32_bf16 v[116:119], v[176:179], v[192:195], v[116:119]
	v_mfma_f32_16x16x32_bf16 v[108:111], v[184:187], v[192:195], v[108:111]
	v_mfma_f32_16x16x32_bf16 v[100:103], v[176:179], v[200:203], v[100:103]
	v_mfma_f32_16x16x32_bf16 v[92:95], v[184:187], v[200:203], v[92:95]
	v_mfma_f32_16x16x32_bf16 v[84:87], v[176:179], v[208:211], v[84:87]
	v_mfma_f32_16x16x32_bf16 v[76:79], v[184:187], v[208:211], v[76:79]
	v_mfma_f32_16x16x32_bf16 v[72:75], v[176:179], v[230:233], v[72:75]
	v_mfma_f32_16x16x32_bf16 v[68:71], v[184:187], v[230:233], v[68:71]
	s_barrier
	s_add_i32 s14, s52, s27
	v_lshl_add_u64 v[142:143], s[18:19], 0, v[2:3]
	s_mov_b32 m0, s14
	ds_read_b128 v[188:191], v148 offset:16384
	ds_read_b128 v[192:195], v148 offset:17408
	ds_read_b128 v[196:199], v148 offset:18432
	ds_read_b128 v[200:203], v148 offset:19456
	ds_read_b128 v[204:207], v148 offset:20480
	ds_read_b128 v[208:211], v148 offset:21504
	ds_read_b128 v[226:229], v148 offset:22528
	ds_read_b128 v[230:233], v148 offset:23552
	global_load_lds_dwordx4 v[142:143], off
	s_add_i32 m0, s14, 0x2000
	s_add_u32 s14, s18, 0x160000
	v_lshl_add_u64 v[166:167], s[18:19], 0, v[136:137]
	s_addc_u32 s15, s19, 0
	s_add_i32 s52, s53, s27
	global_load_lds_dwordx4 v[166:167], off
	v_lshl_add_u64 v[212:213], s[14:15], 0, v[2:3]
	s_mov_b32 m0, s52
	v_lshl_add_u64 v[234:235], s[20:21], 0, v[134:135]
	global_load_lds_dwordx4 v[212:213], off
	v_lshl_add_u64 v[212:213], s[14:15], 0, v[136:137]
	s_add_i32 m0, s52, 0x2000
	s_nop 0
	global_load_lds_dwordx4 v[212:213], off
	v_lshl_add_u64 v[212:213], s[20:21], 0, v[132:133]
	s_mov_b32 m0, s28
	s_nop 0
	global_load_lds_dwordx4 v[212:213], off
	s_mov_b32 m0, s29
	s_nop 0
	global_load_lds_dwordx4 v[234:235], off
	s_nop 0
	s_nop 0
	s_nop 0
	s_nop 0
	s_waitcnt vmcnt(8)
	s_waitcnt lgkmcnt(0)
	s_barrier
; #define PG8_STAGE(bufoff, gbase, voff) do { _Pragma("unroll") for (int _i = 0; _i < 2; ++_i) \
;         __builtin_amdgcn_global_load_lds((const unsigned*)((const char*)(gbase) + (voff)[_i]), (PG8_LAS unsigned*)(lds + (bufoff) + ldsw + _i * 8192), 16, 0, 0); } while (0)
; #define PG8_LDA(dst, b, h) do { _Pragma("unroll") for (int m = 0; m < 4; ++m) _Pragma("unroll") for (int k = 0; k < 2; ++k) dst[m][k] = *(const PG8_LAS bf16x8*)(lds + PG8_SA(b, h) + aoffk[k] + m * 2048); } while (0)
; #define PG8_LDB(dst, b, h) do { _Pragma("unroll") for (int n = 0; n < 2; ++n) _Pragma("unroll") for (int k = 0; k < 2; ++k) dst[n][k] = *(const PG8_LAS bf16x8*)(lds + PG8_SB(b, h) + boffk[k] + n * 2048); } while (0)
; #define PG8_MMA(ai, bj, At, Bt) do { __builtin_amdgcn_s_setprio(1); _Pragma("unroll") for (int m = 0; m < 4; ++m) _Pragma("unroll") for (int n = 0; n < 2; ++n) _Pragma("unroll") for (int k = 0; k < 2; ++k) \
;         acc[ai][bj][m][n] = __builtin_amdgcn_mfma_f32_16x16x32_bf16(Bt[n][k], At[m][k], acc[ai][bj][m][n], 0, 0, 0); __builtin_amdgcn_s_setprio(0); } while (0)
; #define PG8_WAIT_V(n) asm volatile("s_waitcnt vmcnt(" #n ")" ::: "memory")
; #define PG8_WAIT_L(n) asm volatile("s_waitcnt lgkmcnt(" #n ")" ::: "memory")
; #define PG8_BAR __builtin_amdgcn_s_barrier()
; #define PG8_SCHED __builtin_amdgcn_sched_barrier(0)
; template <class Epi, class Sched, bool ALIGN_EPI = false, bool SP2 = false>
; __device__ __forceinline__ void gemm_phase(PG8_LAS unsigned char* lds, const Gemm g, const Sched& S, const Epi& E) {
;     ...
;             PG8_WAIT_V(8); PG8_WAIT_L(0); PG8_BAR; PG8_MMA(1, 0, At, B0); PG8_MMA(1, 1, At, B1); PG8_BAR; PG8_SCHED;
;             PG8_LDB(B0, 1, 0); PG8_LDB(B1, 1, 1); PG8_SCHED; PG8_LDA(At, 1, 0); PG8_STAGE(PG8_SA(0, 1), a2 + hstepA, voffA);
;             PG8_WAIT_V(8); PG8_WAIT_L(0); PG8_BAR; PG8_MMA(0, 0, At, B0); PG8_MMA(0, 1, At, B1); PG8_BAR; PG8_SCHED;
	v_mfma_f32_16x16x32_bf16 v[64:67], v[150:153], v[188:191], v[64:67]
	v_mfma_f32_16x16x32_bf16 v[60:63], v[158:161], v[188:191], v[60:63]
	v_mfma_f32_16x16x32_bf16 v[56:59], v[150:153], v[196:199], v[56:59]
	v_mfma_f32_16x16x32_bf16 v[48:51], v[158:161], v[196:199], v[48:51]
	v_mfma_f32_16x16x32_bf16 v[40:43], v[150:153], v[204:207], v[40:43]
	v_mfma_f32_16x16x32_bf16 v[32:35], v[158:161], v[204:207], v[32:35]
	v_mfma_f32_16x16x32_bf16 v[24:27], v[150:153], v[226:229], v[24:27]
	v_mfma_f32_16x16x32_bf16 v[16:19], v[158:161], v[226:229], v[16:19]
	v_mfma_f32_16x16x32_bf16 v[64:67], v[154:157], v[192:195], v[64:67]
	v_mfma_f32_16x16x32_bf16 v[60:63], v[162:165], v[192:195], v[60:63]
	v_mfma_f32_16x16x32_bf16 v[56:59], v[154:157], v[200:203], v[56:59]
	v_mfma_f32_16x16x32_bf16 v[48:51], v[162:165], v[200:203], v[48:51]
	v_mfma_f32_16x16x32_bf16 v[40:43], v[154:157], v[208:211], v[40:43]
	v_mfma_f32_16x16x32_bf16 v[32:35], v[162:165], v[208:211], v[32:35]
	v_mfma_f32_16x16x32_bf16 v[24:27], v[154:157], v[230:233], v[24:27]
	v_mfma_f32_16x16x32_bf16 v[16:19], v[162:165], v[230:233], v[16:19]
	v_mfma_f32_16x16x32_bf16 v[52:55], v[172:175], v[188:191], v[52:55]
	v_mfma_f32_16x16x32_bf16 v[44:47], v[180:183], v[188:191], v[44:47]
	v_mfma_f32_16x16x32_bf16 v[36:39], v[172:175], v[196:199], v[36:39]
	v_mfma_f32_16x16x32_bf16 v[28:31], v[180:183], v[196:199], v[28:31]
	v_mfma_f32_16x16x32_bf16 v[20:23], v[172:175], v[204:207], v[20:23]
	v_mfma_f32_16x16x32_bf16 v[12:15], v[180:183], v[204:207], v[12:15]
	v_mfma_f32_16x16x32_bf16 v[8:11], v[172:175], v[226:229], v[8:11]
	v_mfma_f32_16x16x32_bf16 v[4:7], v[180:183], v[226:229], v[4:7]
	v_mfma_f32_16x16x32_bf16 v[52:55], v[176:179], v[192:195], v[52:55]
	v_mfma_f32_16x16x32_bf16 v[44:47], v[184:187], v[192:195], v[44:47]
	v_mfma_f32_16x16x32_bf16 v[36:39], v[176:179], v[200:203], v[36:39]
	v_mfma_f32_16x16x32_bf16 v[28:31], v[184:187], v[200:203], v[28:31]
	v_mfma_f32_16x16x32_bf16 v[20:23], v[176:179], v[208:211], v[20:23]
	v_mfma_f32_16x16x32_bf16 v[12:15], v[184:187], v[208:211], v[12:15]
	v_mfma_f32_16x16x32_bf16 v[8:11], v[176:179], v[230:233], v[8:11]
	v_mfma_f32_16x16x32_bf16 v[4:7], v[184:187], v[230:233], v[4:7]
	s_barrier
	s_add_i32 s52, 0, 0x18000
	v_add_u32_e32 v149, s52, v145
	v_add_u32_e32 v154, s52, v146
	ds_read_b128 v[150:153], v149
	ds_read_b128 v[154:157], v154
	v_add_u32_e32 v149, s56, v145
	v_add_u32_e32 v162, s56, v146
	s_add_i32 s53, 0, 0x1c000
	ds_read_b128 v[158:161], v149
	ds_read_b128 v[162:165], v162
	v_add_u32_e32 v149, s53, v145
	v_add_u32_e32 v168, s53, v146
	ds_read_b128 v[172:175], v149
	ds_read_b128 v[176:179], v168
	v_add_u32_e32 v149, s57, v145
	v_add_u32_e32 v168, s57, v146
	ds_read_b128 v[180:183], v149
	ds_read_b128 v[184:187], v168
	s_add_u32 s14, s20, 0x160000
	s_addc_u32 s15, s21, 0
	s_mov_b32 m0, s30
	v_lshl_add_u64 v[236:237], s[14:15], 0, v[132:133]
	ds_read_b128 v[188:191], v148 offset:32768
	ds_read_b128 v[192:195], v148 offset:33792
	ds_read_b128 v[196:199], v148 offset:34816
	ds_read_b128 v[200:203], v148 offset:35840
	ds_read_b128 v[204:207], v148 offset:36864
	ds_read_b128 v[208:211], v148 offset:37888
	ds_read_b128 v[226:229], v148 offset:38912
	ds_read_b128 v[230:233], v148 offset:39936
	global_load_lds_dwordx4 v[236:237], off
	v_lshl_add_u64 v[236:237], s[14:15], 0, v[134:135]
	s_mov_b32 m0, s31
	s_nop 0
	global_load_lds_dwordx4 v[236:237], off
	s_nop 0
	s_nop 0
	s_waitcnt vmcnt(8)
	s_waitcnt lgkmcnt(0)
	s_barrier
	v_mfma_f32_16x16x32_bf16 v[128:131], v[150:153], v[188:191], v[128:131]
	v_mfma_f32_16x16x32_bf16 v[124:127], v[158:161], v[188:191], v[124:127]
	v_mfma_f32_16x16x32_bf16 v[120:123], v[150:153], v[196:199], v[120:123]
	v_mfma_f32_16x16x32_bf16 v[112:115], v[158:161], v[196:199], v[112:115]
	v_mfma_f32_16x16x32_bf16 v[104:107], v[150:153], v[204:207], v[104:107]
	v_mfma_f32_16x16x32_bf16 v[96:99], v[158:161], v[204:207], v[96:99]
	v_mfma_f32_16x16x32_bf16 v[88:91], v[150:153], v[226:229], v[88:91]
	v_mfma_f32_16x16x32_bf16 v[80:83], v[158:161], v[226:229], v[80:83]
	v_mfma_f32_16x16x32_bf16 v[128:131], v[154:157], v[192:195], v[128:131]
	v_mfma_f32_16x16x32_bf16 v[124:127], v[162:165], v[192:195], v[124:127]
	v_mfma_f32_16x16x32_bf16 v[120:123], v[154:157], v[200:203], v[120:123]
	v_mfma_f32_16x16x32_bf16 v[112:115], v[162:165], v[200:203], v[112:115]
	v_mfma_f32_16x16x32_bf16 v[104:107], v[154:157], v[208:211], v[104:107]
	v_mfma_f32_16x16x32_bf16 v[96:99], v[162:165], v[208:211], v[96:99]
	v_mfma_f32_16x16x32_bf16 v[88:91], v[154:157], v[230:233], v[88:91]
	v_mfma_f32_16x16x32_bf16 v[80:83], v[162:165], v[230:233], v[80:83]
	v_mfma_f32_16x16x32_bf16 v[116:119], v[172:175], v[188:191], v[116:119]
	v_mfma_f32_16x16x32_bf16 v[108:111], v[180:183], v[188:191], v[108:111]
	v_mfma_f32_16x16x32_bf16 v[100:103], v[172:175], v[196:199], v[100:103]
	v_mfma_f32_16x16x32_bf16 v[92:95], v[180:183], v[196:199], v[92:95]
	v_mfma_f32_16x16x32_bf16 v[84:87], v[172:175], v[204:207], v[84:87]
	v_mfma_f32_16x16x32_bf16 v[76:79], v[180:183], v[204:207], v[76:79]
	v_mfma_f32_16x16x32_bf16 v[72:75], v[172:175], v[226:229], v[72:75]
	v_mfma_f32_16x16x32_bf16 v[68:71], v[180:183], v[226:229], v[68:71]
	v_mfma_f32_16x16x32_bf16 v[116:119], v[176:179], v[192:195], v[116:119]
	v_mfma_f32_16x16x32_bf16 v[108:111], v[184:187], v[192:195], v[108:111]
	v_mfma_f32_16x16x32_bf16 v[100:103], v[176:179], v[200:203], v[100:103]
	v_mfma_f32_16x16x32_bf16 v[92:95], v[184:187], v[200:203], v[92:95]
	v_mfma_f32_16x16x32_bf16 v[84:87], v[176:179], v[208:211], v[84:87]
	v_mfma_f32_16x16x32_bf16 v[76:79], v[184:187], v[208:211], v[76:79]
	v_mfma_f32_16x16x32_bf16 v[72:75], v[176:179], v[230:233], v[72:75]
	v_mfma_f32_16x16x32_bf16 v[68:71], v[184:187], v[230:233], v[68:71]
	s_barrier
; #define PG8_STAGE(bufoff, gbase, voff) do { _Pragma("unroll") for (int _i = 0; _i < 2; ++_i) \
;         __builtin_amdgcn_global_load_lds((const unsigned*)((const char*)(gbase) + (voff)[_i]), (PG8_LAS unsigned*)(lds + (bufoff) + ldsw + _i * 8192), 16, 0, 0); } while (0)
; #define PG8_LDA(dst, b, h) do { _Pragma("unroll") for (int m = 0; m < 4; ++m) _Pragma("unroll") for (int k = 0; k < 2; ++k) dst[m][k] = *(const PG8_LAS bf16x8*)(lds + PG8_SA(b, h) + aoffk[k] + m * 2048); } while (0)
; #define PG8_MMA(ai, bj, At, Bt) do { __builtin_amdgcn_s_setprio(1); _Pragma("unroll") for (int m = 0; m < 4; ++m) _Pragma("unroll") for (int n = 0; n < 2; ++n) _Pragma("unroll") for (int k = 0; k < 2; ++k) \
;         acc[ai][bj][m][n] = __builtin_amdgcn_mfma_f32_16x16x32_bf16(Bt[n][k], At[m][k], acc[ai][bj][m][n], 0, 0, 0); __builtin_amdgcn_s_setprio(0); } while (0)
; #define PG8_WAIT_V(n) asm volatile("s_waitcnt vmcnt(" #n ")" ::: "memory")
; #define PG8_WAIT_L(n) asm volatile("s_waitcnt lgkmcnt(" #n ")" ::: "memory")
; #define PG8_BAR __builtin_amdgcn_s_barrier()
; #define PG8_SCHED __builtin_amdgcn_sched_barrier(0)
; template <class Epi, class Sched, bool ALIGN_EPI = false, bool SP2 = false>
; __device__ __forceinline__ void gemm_phase(PG8_LAS unsigned char* lds, const Gemm g, const Sched& S, const Epi& E) {
;     ...
;             PG8_LDA(At, 1, 1); PG8_STAGE(PG8_SB(1, 0), b3, voffB); PG8_STAGE(PG8_SB(1, 1), b3 + hstepB, voffB); PG8_STAGE(PG8_SA(1, 0), a3, voffA);
;             PG8_WAIT_V(8); PG8_WAIT_L(0); PG8_BAR; PG8_MMA(1, 0, At, B0); PG8_MMA(1, 1, At, B1); PG8_BAR; PG8_SCHED;
	s_add_i32 s14, s52, s27
	v_lshl_add_u64 v[142:143], v[142:143], 0, s[58:59]
	s_mov_b32 m0, s14
	ds_read_b128 v[188:191], v148 offset:49152
	ds_read_b128 v[192:195], v148 offset:50176
	ds_read_b128 v[196:199], v148 offset:51200
	ds_read_b128 v[200:203], v148 offset:52224
	ds_read_b128 v[204:207], v148 offset:53248
	ds_read_b128 v[208:211], v148 offset:54272
	ds_read_b128 v[226:229], v148 offset:55296
	ds_read_b128 v[230:233], v148 offset:56320
	global_load_lds_dwordx4 v[142:143], off
	s_add_i32 m0, s14, 0x2000
	s_add_u32 s14, s18, 0x160080
	v_lshl_add_u64 v[142:143], v[166:167], 0, s[58:59]
	s_addc_u32 s15, s19, 0
	s_add_i32 s18, s53, s27
	global_load_lds_dwordx4 v[142:143], off
	v_lshl_add_u64 v[142:143], s[14:15], 0, v[2:3]
	s_mov_b32 m0, s18
	s_nop 0
	global_load_lds_dwordx4 v[142:143], off
	v_lshl_add_u64 v[142:143], s[14:15], 0, v[136:137]
	s_add_i32 m0, s18, 0x2000
	s_nop 0
	global_load_lds_dwordx4 v[142:143], off
	v_lshl_add_u64 v[142:143], v[212:213], 0, s[58:59]
	s_mov_b32 m0, s38
	s_nop 0
	global_load_lds_dwordx4 v[142:143], off
	v_lshl_add_u64 v[142:143], v[234:235], 0, s[58:59]
	s_mov_b32 m0, s39
	s_nop 0
	global_load_lds_dwordx4 v[142:143], off
	s_nop 0
	s_nop 0
	s_nop 0
	s_waitcnt vmcnt(8)
	s_waitcnt lgkmcnt(0)
	s_barrier
	v_mfma_f32_16x16x32_bf16 v[64:67], v[150:153], v[188:191], v[64:67]
	v_mfma_f32_16x16x32_bf16 v[60:63], v[158:161], v[188:191], v[60:63]
	v_mfma_f32_16x16x32_bf16 v[56:59], v[150:153], v[196:199], v[56:59]
	v_mfma_f32_16x16x32_bf16 v[48:51], v[158:161], v[196:199], v[48:51]
	v_mfma_f32_16x16x32_bf16 v[40:43], v[150:153], v[204:207], v[40:43]
	v_mfma_f32_16x16x32_bf16 v[32:35], v[158:161], v[204:207], v[32:35]
	v_mfma_f32_16x16x32_bf16 v[24:27], v[150:153], v[226:229], v[24:27]
	v_mfma_f32_16x16x32_bf16 v[16:19], v[158:161], v[226:229], v[16:19]
	v_mfma_f32_16x16x32_bf16 v[64:67], v[154:157], v[192:195], v[64:67]
	v_mfma_f32_16x16x32_bf16 v[60:63], v[162:165], v[192:195], v[60:63]
	v_mfma_f32_16x16x32_bf16 v[56:59], v[154:157], v[200:203], v[56:59]
	v_mfma_f32_16x16x32_bf16 v[48:51], v[162:165], v[200:203], v[48:51]
	v_mfma_f32_16x16x32_bf16 v[40:43], v[154:157], v[208:211], v[40:43]
	v_mfma_f32_16x16x32_bf16 v[32:35], v[162:165], v[208:211], v[32:35]
	v_mfma_f32_16x16x32_bf16 v[24:27], v[154:157], v[230:233], v[24:27]
	v_mfma_f32_16x16x32_bf16 v[16:19], v[162:165], v[230:233], v[16:19]
	v_mfma_f32_16x16x32_bf16 v[52:55], v[172:175], v[188:191], v[52:55]
	v_mfma_f32_16x16x32_bf16 v[44:47], v[180:183], v[188:191], v[44:47]
	v_mfma_f32_16x16x32_bf16 v[36:39], v[172:175], v[196:199], v[36:39]
	v_mfma_f32_16x16x32_bf16 v[28:31], v[180:183], v[196:199], v[28:31]
	v_mfma_f32_16x16x32_bf16 v[20:23], v[172:175], v[204:207], v[20:23]
	v_mfma_f32_16x16x32_bf16 v[12:15], v[180:183], v[204:207], v[12:15]
	v_mfma_f32_16x16x32_bf16 v[8:11], v[172:175], v[226:229], v[8:11]
	v_mfma_f32_16x16x32_bf16 v[4:7], v[180:183], v[226:229], v[4:7]
	v_mfma_f32_16x16x32_bf16 v[52:55], v[176:179], v[192:195], v[52:55]
	v_mfma_f32_16x16x32_bf16 v[44:47], v[184:187], v[192:195], v[44:47]
	v_mfma_f32_16x16x32_bf16 v[36:39], v[176:179], v[200:203], v[36:39]
	v_mfma_f32_16x16x32_bf16 v[28:31], v[184:187], v[200:203], v[28:31]
	v_mfma_f32_16x16x32_bf16 v[20:23], v[176:179], v[208:211], v[20:23]
	v_mfma_f32_16x16x32_bf16 v[12:15], v[184:187], v[208:211], v[12:15]
	v_mfma_f32_16x16x32_bf16 v[8:11], v[176:179], v[230:233], v[8:11]
	v_mfma_f32_16x16x32_bf16 v[4:7], v[184:187], v[230:233], v[4:7]
	s_barrier
	s_add_u32 s49, s49, 0x100
	s_addc_u32 s50, s50, 0
	s_cmp_ge_i32 s51, s44
	s_mov_b64 s[14:15], s[16:17]
	s_mov_b32 s18, s51
	s_cbranch_scc0 .LBB0_430
	s_and_b64 vcc, exec, s[6:7]
	s_cbranch_vccz .LBB0_433
	s_barrier

; #define PG8_STAGE(bufoff, gbase, voff) do { _Pragma("unroll") for (int _i = 0; _i < 2; ++_i) \
;         __builtin_amdgcn_global_load_lds((const unsigned*)((const char*)(gbase) + (voff)[_i]), (PG8_LAS unsigned*)(lds + (bufoff) + ldsw + _i * 8192), 16, 0, 0); } while (0)
; #define PG8_LDA(dst, b, h) do { _Pragma("unroll") for (int m = 0; m < 4; ++m) _Pragma("unroll") for (int k = 0; k < 2; ++k) dst[m][k] = *(const PG8_LAS bf16x8*)(lds + PG8_SA(b, h) + aoffk[k] + m * 2048); } while (0)
; #define PG8_LDB(dst, b, h) do { _Pragma("unroll") for (int n = 0; n < 2; ++n) _Pragma("unroll") for (int k = 0; k < 2; ++k) dst[n][k] = *(const PG8_LAS bf16x8*)(lds + PG8_SB(b, h) + boffk[k] + n * 2048); } while (0)
; #define PG8_MMA(ai, bj, At, Bt) do { __builtin_amdgcn_s_setprio(1); _Pragma("unroll") for (int m = 0; m < 4; ++m) _Pragma("unroll") for (int n = 0; n < 2; ++n) _Pragma("unroll") for (int k = 0; k < 2; ++k) \
;         acc[ai][bj][m][n] = __builtin_amdgcn_mfma_f32_16x16x32_bf16(Bt[n][k], At[m][k], acc[ai][bj][m][n], 0, 0, 0); __builtin_amdgcn_s_setprio(0); } while (0)
; #define PG8_WAIT_V(n) asm volatile("s_waitcnt vmcnt(" #n ")" ::: "memory")
; #define PG8_WAIT_L(n) asm volatile("s_waitcnt lgkmcnt(" #n ")" ::: "memory")
; #define PG8_BAR __builtin_amdgcn_s_barrier()
; template <class Epi, class Sched, bool ALIGN_EPI = false, bool SP2 = false>
; __device__ __forceinline__ void gemm_phase(PG8_LAS unsigned char* lds, const Gemm g, const Sched& S, const Epi& E) {
;     ...
;             const bool last = (t == nt - 2);
;             const char* a1 = cA + (size_t)(t + 1) * kstep;
;             const char* a2 = last ? nA : cA + (size_t)(t + 2) * kstep; const char* b2 = last ? nB : cB + (size_t)(t + 2) * kstep;
;             const char* a3 = a2 + kstep; const char* b3 = b2 + kstep;
;             if (last && has_next) S.a_ready(nxt);
;             if constexpr (SP2) {
;             PG8_LDB(B0, 0, 0); PG8_LDB(B1, 0, 1); PG8_SCHED; PG8_LDA(At, 0, 0); PG8_STAGE(PG8_SA(1, 1), a1 + hstepA, voffA);
;             PG8_WAIT_V(8); PG8_WAIT_L(0); PG8_BAR; PG8_MMA(0, 0, At, B0); PG8_MMA(0, 1, At, B1); PG8_BAR; PG8_SCHED;
;             PG8_LDA(At, 0, 1); PG8_STAGE(PG8_SB(0, 0), b2, voffB); PG8_STAGE(PG8_SB(0, 1), b2 + hstepB, voffB); PG8_STAGE(PG8_SA(0, 0), a2, voffA);
;             PG8_WAIT_V(8); PG8_WAIT_L(0); PG8_BAR; PG8_MMA(1, 0, At, B0); PG8_MMA(1, 1, At, B1); PG8_BAR; PG8_SCHED;
.LBB0_663:
	s_add_u32 s20, s18, 0xfff80080
	s_addc_u32 s21, s19, -1
	s_add_i32 s45, 0, 0x10000
	s_cmp_eq_u32 s44, 28
	v_add_u32_e32 v142, s45, v147
	v_add_u32_e32 v151, s45, v148
	s_cselect_b32 s23, s9, s21
	s_cselect_b32 s22, s40, s20
	ds_read_b128 v[142:145], v142
	ds_read_b128 v[152:155], v151
	v_add_u32_e32 v151, s49, v147
	v_add_u32_e32 v160, s49, v148
	s_cselect_b32 s21, s7, s43
	s_cselect_b32 s20, s41, s42
	s_add_i32 s48, 0, 0x14000
	ds_read_b128 v[156:159], v151
	ds_read_b128 v[160:163], v160
	v_add_u32_e32 v151, s48, v147
	v_add_u32_e32 v168, s48, v148
	ds_read_b128 v[164:167], v151
	ds_read_b128 v[172:175], v168
	v_add_u32_e32 v151, s50, v147
	v_add_u32_e32 v168, s50, v148
	ds_read_b128 v[176:179], v151
	ds_read_b128 v[180:183], v168
	v_lshl_add_u64 v[212:213], s[18:19], 0, v[138:139]
	s_add_i32 m0, s33, 0xc000
	ds_read_b128 v[184:187], v150
	ds_read_b128 v[188:191], v150 offset:1024
	ds_read_b128 v[192:195], v150 offset:2048
	ds_read_b128 v[196:199], v150 offset:3072
	ds_read_b128 v[200:203], v150 offset:4096
	ds_read_b128 v[204:207], v150 offset:5120
	ds_read_b128 v[208:211], v150 offset:6144
	ds_read_b128 v[226:229], v150 offset:7168
	global_load_lds_dwordx4 v[212:213], off
	v_lshl_add_u64 v[212:213], s[18:19], 0, v[140:141]
	s_add_i32 m0, s33, 0xe000
	s_nop 0
	global_load_lds_dwordx4 v[212:213], off
	s_nop 0
	s_nop 0
	s_nop 0
	s_nop 0
	s_nop 0
	s_nop 0
	s_nop 0
	s_nop 0
	s_nop 0
	s_nop 0
	s_waitcnt vmcnt(8)
	s_waitcnt lgkmcnt(0)
	s_barrier
	v_mfma_f32_16x16x32_bf16 v[128:131], v[142:145], v[184:187], v[128:131]
	v_mfma_f32_16x16x32_bf16 v[124:127], v[156:159], v[184:187], v[124:127]
	v_mfma_f32_16x16x32_bf16 v[120:123], v[142:145], v[192:195], v[120:123]
	v_mfma_f32_16x16x32_bf16 v[112:115], v[156:159], v[192:195], v[112:115]
	v_mfma_f32_16x16x32_bf16 v[104:107], v[142:145], v[200:203], v[104:107]
	v_mfma_f32_16x16x32_bf16 v[96:99], v[156:159], v[200:203], v[96:99]
	v_mfma_f32_16x16x32_bf16 v[88:91], v[142:145], v[208:211], v[88:91]
	v_mfma_f32_16x16x32_bf16 v[80:83], v[156:159], v[208:211], v[80:83]
	v_mfma_f32_16x16x32_bf16 v[128:131], v[152:155], v[188:191], v[128:131]
	v_mfma_f32_16x16x32_bf16 v[124:127], v[160:163], v[188:191], v[124:127]
	v_mfma_f32_16x16x32_bf16 v[120:123], v[152:155], v[196:199], v[120:123]
	v_mfma_f32_16x16x32_bf16 v[112:115], v[160:163], v[196:199], v[112:115]
	v_mfma_f32_16x16x32_bf16 v[104:107], v[152:155], v[204:207], v[104:107]
	v_mfma_f32_16x16x32_bf16 v[96:99], v[160:163], v[204:207], v[96:99]
	v_mfma_f32_16x16x32_bf16 v[88:91], v[152:155], v[226:229], v[88:91]
	v_mfma_f32_16x16x32_bf16 v[80:83], v[160:163], v[226:229], v[80:83]
	v_mfma_f32_16x16x32_bf16 v[116:119], v[164:167], v[184:187], v[116:119]
	v_mfma_f32_16x16x32_bf16 v[108:111], v[176:179], v[184:187], v[108:111]
	v_mfma_f32_16x16x32_bf16 v[100:103], v[164:167], v[192:195], v[100:103]
	v_mfma_f32_16x16x32_bf16 v[92:95], v[176:179], v[192:195], v[92:95]
	v_mfma_f32_16x16x32_bf16 v[84:87], v[164:167], v[200:203], v[84:87]
	v_mfma_f32_16x16x32_bf16 v[76:79], v[176:179], v[200:203], v[76:79]
	v_mfma_f32_16x16x32_bf16 v[72:75], v[164:167], v[208:211], v[72:75]
	v_mfma_f32_16x16x32_bf16 v[68:71], v[176:179], v[208:211], v[68:71]
	v_mfma_f32_16x16x32_bf16 v[116:119], v[172:175], v[188:191], v[116:119]
	v_mfma_f32_16x16x32_bf16 v[108:111], v[180:183], v[188:191], v[108:111]
	v_mfma_f32_16x16x32_bf16 v[100:103], v[172:175], v[196:199], v[100:103]
	v_mfma_f32_16x16x32_bf16 v[92:95], v[180:183], v[196:199], v[92:95]
	v_mfma_f32_16x16x32_bf16 v[84:87], v[172:175], v[204:207], v[84:87]
	v_mfma_f32_16x16x32_bf16 v[76:79], v[180:183], v[204:207], v[76:79]
	v_mfma_f32_16x16x32_bf16 v[72:75], v[172:175], v[226:229], v[72:75]
	v_mfma_f32_16x16x32_bf16 v[68:71], v[180:183], v[226:229], v[68:71]
	s_barrier
	s_add_i32 s45, s45, s30
	v_lshl_add_u64 v[212:213], s[20:21], 0, v[2:3]
	s_mov_b32 m0, s45
	ds_read_b128 v[184:187], v150 offset:16384
	ds_read_b128 v[188:191], v150 offset:17408
	ds_read_b128 v[192:195], v150 offset:18432
	ds_read_b128 v[196:199], v150 offset:19456
	ds_read_b128 v[200:203], v150 offset:20480
	ds_read_b128 v[204:207], v150 offset:21504
	ds_read_b128 v[208:211], v150 offset:22528
	ds_read_b128 v[226:229], v150 offset:23552
	global_load_lds_dwordx4 v[212:213], off
	s_add_i32 m0, s45, 0x2000
	s_add_u32 s46, s20, 0x80000
	v_lshl_add_u64 v[230:231], s[20:21], 0, v[132:133]
	s_addc_u32 s47, s21, 0
	s_add_i32 s45, s48, s30
	global_load_lds_dwordx4 v[230:231], off
	v_lshl_add_u64 v[232:233], s[46:47], 0, v[2:3]
	s_mov_b32 m0, s45
	v_lshl_add_u64 v[234:235], s[22:23], 0, v[134:135]
	global_load_lds_dwordx4 v[232:233], off
	v_lshl_add_u64 v[232:233], s[46:47], 0, v[132:133]
	s_add_i32 m0, s45, 0x2000
	s_nop 0
	global_load_lds_dwordx4 v[232:233], off
	v_lshl_add_u64 v[232:233], s[22:23], 0, v[136:137]
	s_mov_b32 m0, s33
	s_nop 0
	global_load_lds_dwordx4 v[232:233], off
	s_mov_b32 m0, s34
	s_nop 0
	global_load_lds_dwordx4 v[234:235], off
	s_nop 0
	s_nop 0
	s_nop 0
	s_nop 0
	s_waitcnt vmcnt(8)
	s_waitcnt lgkmcnt(0)
	s_barrier
; #define PG8_STAGE(bufoff, gbase, voff) do { _Pragma("unroll") for (int _i = 0; _i < 2; ++_i) \
;         __builtin_amdgcn_global_load_lds((const unsigned*)((const char*)(gbase) + (voff)[_i]), (PG8_LAS unsigned*)(lds + (bufoff) + ldsw + _i * 8192), 16, 0, 0); } while (0)
; #define PG8_LDA(dst, b, h) do { _Pragma("unroll") for (int m = 0; m < 4; ++m) _Pragma("unroll") for (int k = 0; k < 2; ++k) dst[m][k] = *(const PG8_LAS bf16x8*)(lds + PG8_SA(b, h) + aoffk[k] + m * 2048); } while (0)
; #define PG8_LDB(dst, b, h) do { _Pragma("unroll") for (int n = 0; n < 2; ++n) _Pragma("unroll") for (int k = 0; k < 2; ++k) dst[n][k] = *(const PG8_LAS bf16x8*)(lds + PG8_SB(b, h) + boffk[k] + n * 2048); } while (0)
; #define PG8_MMA(ai, bj, At, Bt) do { __builtin_amdgcn_s_setprio(1); _Pragma("unroll") for (int m = 0; m < 4; ++m) _Pragma("unroll") for (int n = 0; n < 2; ++n) _Pragma("unroll") for (int k = 0; k < 2; ++k) \
;         acc[ai][bj][m][n] = __builtin_amdgcn_mfma_f32_16x16x32_bf16(Bt[n][k], At[m][k], acc[ai][bj][m][n], 0, 0, 0); __builtin_amdgcn_s_setprio(0); } while (0)
; #define PG8_WAIT_V(n) asm volatile("s_waitcnt vmcnt(" #n ")" ::: "memory")
; #define PG8_WAIT_L(n) asm volatile("s_waitcnt lgkmcnt(" #n ")" ::: "memory")
; #define PG8_BAR __builtin_amdgcn_s_barrier()
; #define PG8_SCHED __builtin_amdgcn_sched_barrier(0)
; template <class Epi, class Sched, bool ALIGN_EPI = false, bool SP2 = false>
; __device__ __forceinline__ void gemm_phase(PG8_LAS unsigned char* lds, const Gemm g, const Sched& S, const Epi& E) {
;     ...
;             PG8_WAIT_V(8); PG8_WAIT_L(0); PG8_BAR; PG8_MMA(1, 0, At, B0); PG8_MMA(1, 1, At, B1); PG8_BAR; PG8_SCHED;
;             PG8_LDB(B0, 1, 0); PG8_LDB(B1, 1, 1); PG8_SCHED; PG8_LDA(At, 1, 0); PG8_STAGE(PG8_SA(0, 1), a2 + hstepA, voffA);
;             PG8_WAIT_V(8); PG8_WAIT_L(0); PG8_BAR; PG8_MMA(0, 0, At, B0); PG8_MMA(0, 1, At, B1); PG8_BAR; PG8_SCHED;
	v_mfma_f32_16x16x32_bf16 v[64:67], v[142:145], v[184:187], v[64:67]
	v_mfma_f32_16x16x32_bf16 v[60:63], v[156:159], v[184:187], v[60:63]
	v_mfma_f32_16x16x32_bf16 v[56:59], v[142:145], v[192:195], v[56:59]
	v_mfma_f32_16x16x32_bf16 v[48:51], v[156:159], v[192:195], v[48:51]
	v_mfma_f32_16x16x32_bf16 v[40:43], v[142:145], v[200:203], v[40:43]
	v_mfma_f32_16x16x32_bf16 v[32:35], v[156:159], v[200:203], v[32:35]
	v_mfma_f32_16x16x32_bf16 v[24:27], v[142:145], v[208:211], v[24:27]
	v_mfma_f32_16x16x32_bf16 v[16:19], v[156:159], v[208:211], v[16:19]
	v_mfma_f32_16x16x32_bf16 v[64:67], v[152:155], v[188:191], v[64:67]
	v_mfma_f32_16x16x32_bf16 v[60:63], v[160:163], v[188:191], v[60:63]
	v_mfma_f32_16x16x32_bf16 v[56:59], v[152:155], v[196:199], v[56:59]
	v_mfma_f32_16x16x32_bf16 v[48:51], v[160:163], v[196:199], v[48:51]
	v_mfma_f32_16x16x32_bf16 v[40:43], v[152:155], v[204:207], v[40:43]
	v_mfma_f32_16x16x32_bf16 v[32:35], v[160:163], v[204:207], v[32:35]
	v_mfma_f32_16x16x32_bf16 v[24:27], v[152:155], v[226:229], v[24:27]
	v_mfma_f32_16x16x32_bf16 v[16:19], v[160:163], v[226:229], v[16:19]
	v_mfma_f32_16x16x32_bf16 v[52:55], v[164:167], v[184:187], v[52:55]
	v_mfma_f32_16x16x32_bf16 v[44:47], v[176:179], v[184:187], v[44:47]
	v_mfma_f32_16x16x32_bf16 v[36:39], v[164:167], v[192:195], v[36:39]
	v_mfma_f32_16x16x32_bf16 v[28:31], v[176:179], v[192:195], v[28:31]
	v_mfma_f32_16x16x32_bf16 v[20:23], v[164:167], v[200:203], v[20:23]
	v_mfma_f32_16x16x32_bf16 v[12:15], v[176:179], v[200:203], v[12:15]
	v_mfma_f32_16x16x32_bf16 v[8:11], v[164:167], v[208:211], v[8:11]
	v_mfma_f32_16x16x32_bf16 v[4:7], v[176:179], v[208:211], v[4:7]
	v_mfma_f32_16x16x32_bf16 v[52:55], v[172:175], v[188:191], v[52:55]
	v_mfma_f32_16x16x32_bf16 v[44:47], v[180:183], v[188:191], v[44:47]
	v_mfma_f32_16x16x32_bf16 v[36:39], v[172:175], v[196:199], v[36:39]
	v_mfma_f32_16x16x32_bf16 v[28:31], v[180:183], v[196:199], v[28:31]
	v_mfma_f32_16x16x32_bf16 v[20:23], v[172:175], v[204:207], v[20:23]
	v_mfma_f32_16x16x32_bf16 v[12:15], v[180:183], v[204:207], v[12:15]
	v_mfma_f32_16x16x32_bf16 v[8:11], v[172:175], v[226:229], v[8:11]
	v_mfma_f32_16x16x32_bf16 v[4:7], v[180:183], v[226:229], v[4:7]
	s_barrier
	s_add_i32 s45, 0, 0x18000
	v_add_u32_e32 v142, s45, v147
	v_add_u32_e32 v151, s45, v148
	ds_read_b128 v[142:145], v142
	ds_read_b128 v[152:155], v151
	v_add_u32_e32 v151, s51, v147
	v_add_u32_e32 v160, s51, v148
	s_add_i32 s46, 0, 0x1c000
	ds_read_b128 v[156:159], v151
	ds_read_b128 v[160:163], v160
	v_add_u32_e32 v151, s46, v147
	v_add_u32_e32 v168, s46, v148
	ds_read_b128 v[164:167], v151
	ds_read_b128 v[172:175], v168
	v_add_u32_e32 v151, s52, v147
	v_add_u32_e32 v168, s52, v148
	ds_read_b128 v[176:179], v151
	ds_read_b128 v[180:183], v168
	s_add_u32 s22, s22, 0x80000
	s_addc_u32 s23, s23, 0
	s_mov_b32 m0, s35
	v_lshl_add_u64 v[236:237], s[22:23], 0, v[136:137]
	ds_read_b128 v[184:187], v150 offset:32768
	ds_read_b128 v[188:191], v150 offset:33792
	ds_read_b128 v[192:195], v150 offset:34816
	ds_read_b128 v[196:199], v150 offset:35840
	ds_read_b128 v[200:203], v150 offset:36864
	ds_read_b128 v[204:207], v150 offset:37888
	ds_read_b128 v[208:211], v150 offset:38912
	ds_read_b128 v[226:229], v150 offset:39936
	global_load_lds_dwordx4 v[236:237], off
	v_lshl_add_u64 v[236:237], s[22:23], 0, v[134:135]
	s_mov_b32 m0, s36
	s_nop 0
	global_load_lds_dwordx4 v[236:237], off
	s_nop 0
	s_nop 0
	s_waitcnt vmcnt(8)
	s_waitcnt lgkmcnt(0)
	s_barrier
	v_mfma_f32_16x16x32_bf16 v[128:131], v[142:145], v[184:187], v[128:131]
	v_mfma_f32_16x16x32_bf16 v[124:127], v[156:159], v[184:187], v[124:127]
	v_mfma_f32_16x16x32_bf16 v[120:123], v[142:145], v[192:195], v[120:123]
	v_mfma_f32_16x16x32_bf16 v[112:115], v[156:159], v[192:195], v[112:115]
	v_mfma_f32_16x16x32_bf16 v[104:107], v[142:145], v[200:203], v[104:107]
	v_mfma_f32_16x16x32_bf16 v[96:99], v[156:159], v[200:203], v[96:99]
	v_mfma_f32_16x16x32_bf16 v[88:91], v[142:145], v[208:211], v[88:91]
	v_mfma_f32_16x16x32_bf16 v[80:83], v[156:159], v[208:211], v[80:83]
	v_mfma_f32_16x16x32_bf16 v[128:131], v[152:155], v[188:191], v[128:131]
	v_mfma_f32_16x16x32_bf16 v[124:127], v[160:163], v[188:191], v[124:127]
	v_mfma_f32_16x16x32_bf16 v[120:123], v[152:155], v[196:199], v[120:123]
	v_mfma_f32_16x16x32_bf16 v[112:115], v[160:163], v[196:199], v[112:115]
	v_mfma_f32_16x16x32_bf16 v[104:107], v[152:155], v[204:207], v[104:107]
	v_mfma_f32_16x16x32_bf16 v[96:99], v[160:163], v[204:207], v[96:99]
	v_mfma_f32_16x16x32_bf16 v[88:91], v[152:155], v[226:229], v[88:91]
	v_mfma_f32_16x16x32_bf16 v[80:83], v[160:163], v[226:229], v[80:83]
	v_mfma_f32_16x16x32_bf16 v[116:119], v[164:167], v[184:187], v[116:119]
	v_mfma_f32_16x16x32_bf16 v[108:111], v[176:179], v[184:187], v[108:111]
	v_mfma_f32_16x16x32_bf16 v[100:103], v[164:167], v[192:195], v[100:103]
	v_mfma_f32_16x16x32_bf16 v[92:95], v[176:179], v[192:195], v[92:95]
	v_mfma_f32_16x16x32_bf16 v[84:87], v[164:167], v[200:203], v[84:87]
	v_mfma_f32_16x16x32_bf16 v[76:79], v[176:179], v[200:203], v[76:79]
	v_mfma_f32_16x16x32_bf16 v[72:75], v[164:167], v[208:211], v[72:75]
	v_mfma_f32_16x16x32_bf16 v[68:71], v[176:179], v[208:211], v[68:71]
	v_mfma_f32_16x16x32_bf16 v[116:119], v[172:175], v[188:191], v[116:119]
	v_mfma_f32_16x16x32_bf16 v[108:111], v[180:183], v[188:191], v[108:111]
	v_mfma_f32_16x16x32_bf16 v[100:103], v[172:175], v[196:199], v[100:103]
	v_mfma_f32_16x16x32_bf16 v[92:95], v[180:183], v[196:199], v[92:95]
	v_mfma_f32_16x16x32_bf16 v[84:87], v[172:175], v[204:207], v[84:87]
	v_mfma_f32_16x16x32_bf16 v[76:79], v[180:183], v[204:207], v[76:79]
	v_mfma_f32_16x16x32_bf16 v[72:75], v[172:175], v[226:229], v[72:75]
	v_mfma_f32_16x16x32_bf16 v[68:71], v[180:183], v[226:229], v[68:71]
	s_barrier
; #define PG8_STAGE(bufoff, gbase, voff) do { _Pragma("unroll") for (int _i = 0; _i < 2; ++_i) \
;         __builtin_amdgcn_global_load_lds((const unsigned*)((const char*)(gbase) + (voff)[_i]), (PG8_LAS unsigned*)(lds + (bufoff) + ldsw + _i * 8192), 16, 0, 0); } while (0)
; #define PG8_LDA(dst, b, h) do { _Pragma("unroll") for (int m = 0; m < 4; ++m) _Pragma("unroll") for (int k = 0; k < 2; ++k) dst[m][k] = *(const PG8_LAS bf16x8*)(lds + PG8_SA(b, h) + aoffk[k] + m * 2048); } while (0)
; #define PG8_MMA(ai, bj, At, Bt) do { __builtin_amdgcn_s_setprio(1); _Pragma("unroll") for (int m = 0; m < 4; ++m) _Pragma("unroll") for (int n = 0; n < 2; ++n) _Pragma("unroll") for (int k = 0; k < 2; ++k) \
;         acc[ai][bj][m][n] = __builtin_amdgcn_mfma_f32_16x16x32_bf16(Bt[n][k], At[m][k], acc[ai][bj][m][n], 0, 0, 0); __builtin_amdgcn_s_setprio(0); } while (0)
; #define PG8_WAIT_V(n) asm volatile("s_waitcnt vmcnt(" #n ")" ::: "memory")
; #define PG8_WAIT_L(n) asm volatile("s_waitcnt lgkmcnt(" #n ")" ::: "memory")
; #define PG8_BAR __builtin_amdgcn_s_barrier()
; #define PG8_SCHED __builtin_amdgcn_sched_barrier(0)
; template <class Epi, class Sched, bool ALIGN_EPI = false, bool SP2 = false>
; __device__ __forceinline__ void gemm_phase(PG8_LAS unsigned char* lds, const Gemm g, const Sched& S, const Epi& E) {
;     ...
;             PG8_LDA(At, 1, 1); PG8_STAGE(PG8_SB(1, 0), b3, voffB); PG8_STAGE(PG8_SB(1, 1), b3 + hstepB, voffB); PG8_STAGE(PG8_SA(1, 0), a3, voffA);
;             PG8_WAIT_V(8); PG8_WAIT_L(0); PG8_BAR; PG8_MMA(1, 0, At, B0); PG8_MMA(1, 1, At, B1); PG8_BAR; PG8_SCHED;
;     ...
;         if constexpr (ALIGN_EPI) { if (wr == 0) PG8_BAR; }
	s_add_i32 s22, s45, s30
	v_lshl_add_u64 v[212:213], v[212:213], 0, s[56:57]
	s_mov_b32 m0, s22
	ds_read_b128 v[184:187], v150 offset:49152
	ds_read_b128 v[188:191], v150 offset:50176
	ds_read_b128 v[192:195], v150 offset:51200
	ds_read_b128 v[196:199], v150 offset:52224
	ds_read_b128 v[200:203], v150 offset:53248
	ds_read_b128 v[204:207], v150 offset:54272
	ds_read_b128 v[208:211], v150 offset:55296
	ds_read_b128 v[226:229], v150 offset:56320
	global_load_lds_dwordx4 v[212:213], off
	s_add_i32 m0, s22, 0x2000
	s_add_u32 s20, s20, 0x80080
	v_lshl_add_u64 v[212:213], v[230:231], 0, s[56:57]
	s_addc_u32 s21, s21, 0
	s_add_i32 s22, s46, s30
	global_load_lds_dwordx4 v[212:213], off
	v_lshl_add_u64 v[212:213], s[20:21], 0, v[2:3]
	s_mov_b32 m0, s22
	s_nop 0
	global_load_lds_dwordx4 v[212:213], off
	v_lshl_add_u64 v[212:213], s[20:21], 0, v[132:133]
	s_add_i32 m0, s22, 0x2000
	s_nop 0
	global_load_lds_dwordx4 v[212:213], off
	v_lshl_add_u64 v[212:213], v[232:233], 0, s[56:57]
	s_mov_b32 m0, s37
	s_nop 0
	global_load_lds_dwordx4 v[212:213], off
	v_lshl_add_u64 v[212:213], v[234:235], 0, s[56:57]
	s_mov_b32 m0, s38
	s_nop 0
	global_load_lds_dwordx4 v[212:213], off
	s_nop 0
	s_nop 0
	s_nop 0
	s_waitcnt vmcnt(8)
	s_waitcnt lgkmcnt(0)
	s_barrier
	v_mfma_f32_16x16x32_bf16 v[64:67], v[142:145], v[184:187], v[64:67]
	v_mfma_f32_16x16x32_bf16 v[60:63], v[156:159], v[184:187], v[60:63]
	v_mfma_f32_16x16x32_bf16 v[56:59], v[142:145], v[192:195], v[56:59]
	v_mfma_f32_16x16x32_bf16 v[48:51], v[156:159], v[192:195], v[48:51]
	v_mfma_f32_16x16x32_bf16 v[40:43], v[142:145], v[200:203], v[40:43]
	v_mfma_f32_16x16x32_bf16 v[32:35], v[156:159], v[200:203], v[32:35]
	v_mfma_f32_16x16x32_bf16 v[24:27], v[142:145], v[208:211], v[24:27]
	v_mfma_f32_16x16x32_bf16 v[16:19], v[156:159], v[208:211], v[16:19]
	v_mfma_f32_16x16x32_bf16 v[64:67], v[152:155], v[188:191], v[64:67]
	v_mfma_f32_16x16x32_bf16 v[60:63], v[160:163], v[188:191], v[60:63]
	v_mfma_f32_16x16x32_bf16 v[56:59], v[152:155], v[196:199], v[56:59]
	v_mfma_f32_16x16x32_bf16 v[48:51], v[160:163], v[196:199], v[48:51]
	v_mfma_f32_16x16x32_bf16 v[40:43], v[152:155], v[204:207], v[40:43]
	v_mfma_f32_16x16x32_bf16 v[32:35], v[160:163], v[204:207], v[32:35]
	v_mfma_f32_16x16x32_bf16 v[24:27], v[152:155], v[226:229], v[24:27]
	v_mfma_f32_16x16x32_bf16 v[16:19], v[160:163], v[226:229], v[16:19]
	v_mfma_f32_16x16x32_bf16 v[52:55], v[164:167], v[184:187], v[52:55]
	v_mfma_f32_16x16x32_bf16 v[44:47], v[176:179], v[184:187], v[44:47]
	v_mfma_f32_16x16x32_bf16 v[36:39], v[164:167], v[192:195], v[36:39]
	v_mfma_f32_16x16x32_bf16 v[28:31], v[176:179], v[192:195], v[28:31]
	v_mfma_f32_16x16x32_bf16 v[20:23], v[164:167], v[200:203], v[20:23]
	v_mfma_f32_16x16x32_bf16 v[12:15], v[176:179], v[200:203], v[12:15]
	v_mfma_f32_16x16x32_bf16 v[8:11], v[164:167], v[208:211], v[8:11]
	v_mfma_f32_16x16x32_bf16 v[4:7], v[176:179], v[208:211], v[4:7]
	v_mfma_f32_16x16x32_bf16 v[52:55], v[172:175], v[188:191], v[52:55]
	v_mfma_f32_16x16x32_bf16 v[44:47], v[180:183], v[188:191], v[44:47]
	v_mfma_f32_16x16x32_bf16 v[36:39], v[172:175], v[196:199], v[36:39]
	v_mfma_f32_16x16x32_bf16 v[28:31], v[180:183], v[196:199], v[28:31]
	v_mfma_f32_16x16x32_bf16 v[20:23], v[172:175], v[204:207], v[20:23]
	v_mfma_f32_16x16x32_bf16 v[12:15], v[180:183], v[204:207], v[12:15]
	v_mfma_f32_16x16x32_bf16 v[8:11], v[172:175], v[226:229], v[8:11]
	v_mfma_f32_16x16x32_bf16 v[4:7], v[180:183], v[226:229], v[4:7]
	s_barrier
	s_add_i32 s44, s44, 2
	s_add_u32 s18, s18, 0x100
	s_addc_u32 s19, s19, 0
	s_add_u32 s42, s42, 0x100
	s_addc_u32 s43, s43, 0
	s_cmp_gt_u32 s44, 29
	s_cbranch_scc0 .LBB0_663
	s_and_b64 vcc, exec, s[4:5]
	s_cbranch_vccz .LBB0_666
	s_barrier

; __device__ __forceinline__ int launder(int x) { asm volatile("" : "+v"(x)); return x; }
; __device__ __forceinline__ const float* inp(int i) { const __attribute__((address_space(4))) Args* ka = (const __attribute__((address_space(4))) Args*)__builtin_amdgcn_kernarg_segment_ptr(); return ka->in[opaque_s(i)]; }
; __device__ __forceinline__ bf16* wsb(const Frame& F, size_t off) { return (bf16*)(F.ws + ((size_t)(unsigned)opaque_s((int)(off >> 20)) << 20)); }
; __device__ __forceinline__ void m4_ret_unit(Frame& F, int layer, int cr, int h) {
;     const int tid = launder(F.tid), lane = tid & 63, w = __builtin_amdgcn_readfirstlane(tid >> 6), r = lane & 15, g = lane >> 4, i = 16 * w + r;
;     const bf16* const pYR = wsb(F, WS_YR); const bf16* const pRSB = wsb(F, WS_RSB); bf16* const pA = wsb(F, WS_A); const bf16* const pP = wsb(F, WS_PH);
;     const size_t m = (size_t)cr * 128 + i;
;     const float scale = 0.08838834764831845f;
;     ldsp T0 = F.lds, T1 = F.lds + 128 * TSR;
;     Stage<128, 128> s0, s1; s0.load(pRSB + ((size_t)(cr * 4 + h) * 2 + 0) * 16384, 128, tid); s1.load(pRSB + ((size_t)(cr * 4 + h) * 2 + 1) * 16384, 128, tid);
;     bf16x8 qf[4];
; #pragma unroll
;     for (int ks = 0; ks < 4; ++ks) qf[ks] = *(const bf16x8*)(pP + m * INP + PC_RQ + h * 128 + 32 * ks + 8 * g);
;     unsigned long long yq[8], gq[8];
; #pragma unroll
;     for (int mt = 0; mt < 8; ++mt) { yq[mt] = *(const unsigned long long*)(pYR + m * 512 + h * 128 + 16 * mt + 4 * g); gq[mt] = *(const unsigned long long*)(pP + m * INP + PC_RG + h * 128 + 16 * mt + 4 * g); }
;     const float lgf = -fabsf(inp(I_RDEC)[layer * 8 + h]), lgb = -fabsf(inp(I_RDEC)[layer * 8 + 4 + h]);
;     __syncthreads();
.LBB0_1175:
	v_mov_b32_e32 v98, v0
	s_movk_i32 s92, 0x2a1
	s_waitcnt lgkmcnt(0)
	s_lshl_b64 s[6:7], s[92:93], 20
	s_movk_i32 s92, 0x3f4
	v_readfirstlane_b32 s3, v98
	s_ashr_i32 s16, s2, 2
	s_and_b32 s14, s2, 3
	s_ashr_i32 s3, s3, 2
	s_lshl_b64 s[8:9], s[92:93], 20
	s_movk_i32 s92, 0xb9
	s_add_u32 s15, s78, s8
	s_addc_u32 s19, s79, s9
	s_lshl_b64 s[8:9], s[92:93], 20
	s_movk_i32 s92, 0xfd
	s_lshl_b64 s[10:11], s[92:93], 20
	v_ashrrev_i32_e32 v2, 31, v98
	s_add_u32 s10, s78, s10
	v_lshrrev_b32_e32 v2, 28, v2
	v_bfi_b32 v52, -16, s3, v98
	s_addc_u32 s11, s79, s11
	s_ashr_i32 s17, s16, 31
	v_add_u32_e32 v2, v98, v2
	s_lshl_b64 s[16:17], s[16:17], 7
	v_ashrrev_i32_e32 v53, 31, v52
	v_ashrrev_i32_e32 v66, 4, v2
	v_and_b32_e32 v2, -16, v2
	v_lshl_add_u64 v[44:45], s[16:17], 0, v[52:53]
	v_sub_u32_e32 v53, v98, v2
	v_add_u32_e32 v2, 0x200, v98
	v_ashrrev_i32_e32 v10, 31, v2
	v_lshrrev_b32_e32 v10, 28, v10
	s_ashr_i32 s3, s2, 31
	v_add_u32_e32 v10, v2, v10
	s_lshl_b64 s[16:17], s[2:3], 16
	v_ashrrev_i32_e32 v67, 31, v66
	v_ashrrev_i32_e32 v92, 4, v10
	v_and_b32_e32 v10, -16, v10
	s_add_u32 s16, s15, s16
	v_lshlrev_b64 v[4:5], 8, v[66:67]
	v_lshlrev_b32_e32 v8, 3, v53
	v_sub_u32_e32 v67, v2, v10
	s_addc_u32 s17, s19, s17
	v_ashrrev_i32_e32 v9, 31, v8
	v_ashrrev_i32_e32 v93, 31, v92
	v_lshlrev_b32_e32 v14, 3, v67
	v_lshl_add_u64 v[6:7], s[16:17], 0, v[4:5]
	v_lshlrev_b64 v[8:9], 1, v[8:9]
	v_lshlrev_b64 v[10:11], 8, v[92:93]
	v_ashrrev_i32_e32 v15, 31, v14
	v_lshl_add_u64 v[6:7], v[6:7], 0, v[8:9]
	v_lshl_add_u64 v[12:13], s[16:17], 0, v[10:11]
	v_lshlrev_b64 v[16:17], 1, v[14:15]
	v_add_u32_e32 v2, 0x400, v98
	v_lshl_add_u64 v[18:19], v[12:13], 0, v[16:17]
	global_load_dwordx4 v[12:15], v[6:7], off
	global_load_dwordx4 v[20:23], v[18:19], off
	v_ashrrev_i32_e32 v6, 31, v2
	v_lshrrev_b32_e32 v6, 28, v6
	v_add_u32_e32 v6, v2, v6
	v_ashrrev_i32_e32 v94, 4, v6
	v_and_b32_e32 v6, -16, v6
	v_sub_u32_e32 v93, v2, v6
	v_add_u32_e32 v2, 0x600, v98
	v_ashrrev_i32_e32 v26, 31, v2
	v_lshrrev_b32_e32 v26, 28, v26
	v_add_u32_e32 v26, v2, v26
	v_ashrrev_i32_e32 v96, 4, v26
	v_ashrrev_i32_e32 v95, 31, v94
	v_and_b32_e32 v26, -16, v26
	v_ashrrev_i32_e32 v97, 31, v96
	v_lshlrev_b64 v[6:7], 8, v[94:95]
	v_sub_u32_e32 v95, v2, v26
	v_lshlrev_b64 v[26:27], 8, v[96:97]
	v_lshl_add_u64 v[18:19], s[16:17], 0, v[6:7]
	v_lshlrev_b32_e32 v24, 3, v93
	v_lshl_add_u64 v[28:29], s[16:17], 0, v[26:27]
	s_add_u32 s16, s16, 0x8000
	v_ashrrev_i32_e32 v25, 31, v24
	v_lshlrev_b32_e32 v30, 3, v95
	s_addc_u32 s17, s17, 0
	v_lshlrev_b64 v[24:25], 1, v[24:25]
	v_ashrrev_i32_e32 v31, 31, v30
	v_lshl_add_u64 v[4:5], s[16:17], 0, v[4:5]
	v_lshl_add_u64 v[18:19], v[18:19], 0, v[24:25]
	v_lshlrev_b64 v[32:33], 1, v[30:31]
	v_lshl_add_u64 v[4:5], v[4:5], 0, v[8:9]
	v_lshl_add_u64 v[8:9], s[16:17], 0, v[10:11]
	v_lshl_add_u64 v[34:35], v[28:29], 0, v[32:33]
	global_load_dwordx4 v[28:31], v[18:19], off
	global_load_dwordx4 v[70:73], v[34:35], off
	v_lshl_add_u64 v[8:9], v[8:9], 0, v[16:17]
	global_load_dwordx4 v[76:79], v[4:5], off
	global_load_dwordx4 v[80:83], v[8:9], off
	v_lshl_add_u64 v[4:5], s[16:17], 0, v[6:7]
	v_lshl_add_u64 v[4:5], v[4:5], 0, v[24:25]
	v_lshl_add_u64 v[6:7], s[16:17], 0, v[26:27]
	s_lshl_b32 s92, s14, 8
	v_lshl_add_u64 v[6:7], v[6:7], 0, v[32:33]
	global_load_dwordx4 v[84:87], v[4:5], off
	global_load_dwordx4 v[88:91], v[6:7], off
	v_mov_b64_e32 v[4:5], s[10:11]
	s_add_u32 s6, s78, s6
	v_mad_u64_u32 v[4:5], s[10:11], v44, s22, v[4:5]
	s_addc_u32 s7, s79, s7
	v_lshlrev_b64 v[36:37], 10, v[44:45]
	v_mad_i32_i24 v5, v45, s22, v5
	v_lshrrev_b32_e32 v2, 1, v98
	v_lshl_add_u64 v[36:37], s[6:7], 0, v[36:37]
	v_lshl_add_u64 v[34:35], v[4:5], 0, s[92:93]
	v_and_b32_e32 v2, 24, v2
	v_and_b32_e32 v32, 48, v98
	v_mov_b32_e32 v33, v3
	v_lshl_add_u64 v[36:37], v[36:37], 0, s[92:93]
	v_lshl_add_u64 v[4:5], v[34:35], 0, v[32:33]
	s_add_u32 s3, s78, s8
	v_lshl_add_u64 v[36:37], v[36:37], 0, v[2:3]
	v_lshl_add_u64 v[34:35], v[34:35], 0, v[2:3]
	s_mov_b32 s6, 13
	global_load_dwordx4 v[24:27], v[4:5], off
	global_load_dwordx4 v[16:19], v[4:5], off offset:64
	global_load_dwordx4 v[8:11], v[4:5], off offset:128
	s_nop 0
	global_load_dwordx4 v[4:7], v[4:5], off offset:192
	s_addc_u32 s8, s79, s9
	global_load_dwordx2 v[62:63], v[36:37], off
	global_load_dwordx2 v[58:59], v[36:37], off offset:32
	global_load_dwordx2 v[56:57], v[36:37], off offset:64
	global_load_dwordx2 v[54:55], v[36:37], off offset:96
	global_load_dwordx2 v[50:51], v[34:35], off offset:3072
	global_load_dwordx2 v[48:49], v[34:35], off offset:3104
	global_load_dwordx2 v[46:47], v[34:35], off offset:3136
	global_load_dwordx2 v[42:43], v[34:35], off offset:3168
	global_load_dwordx2 v[74:75], v[36:37], off offset:128
	global_load_dwordx2 v[68:69], v[36:37], off offset:160
	global_load_dwordx2 v[64:65], v[36:37], off offset:192
	global_load_dwordx2 v[60:61], v[36:37], off offset:224
	global_load_dwordx2 v[40:41], v[34:35], off offset:3200
	global_load_dwordx2 v[38:39], v[34:35], off offset:3232
	s_nop 0
	global_load_dwordx2 v[36:37], v[34:35], off offset:3264
	s_nop 0
	global_load_dwordx2 v[34:35], v[34:35], off offset:3296
	s_ashr_i32 s7, s6, 31
	s_lshl_b64 s[6:7], s[6:7], 3
	s_add_u32 s6, s20, s6
	s_addc_u32 s7, s21, s7
	s_load_dwordx2 s[6:7], s[6:7], 0x0
	s_or_b32 s10, s14, s12
	s_mov_b32 s11, s93
	s_lshl_b64 s[10:11], s[10:11], 2
	v_mul_lo_u32 v66, v66, s72
	s_waitcnt lgkmcnt(0)
	s_add_u32 s6, s6, s10
	s_addc_u32 s7, s7, s11
	global_load_dword v33, v3, s[6:7]
	s_mov_b32 s6, 13
	s_ashr_i32 s7, s6, 31
	s_lshl_b64 s[6:7], s[6:7], 3
	s_add_u32 s6, s20, s6
	s_addc_u32 s7, s21, s7
	s_load_dwordx2 s[6:7], s[6:7], 0x0
	v_lshlrev_b32_e32 v53, 4, v53
	v_add3_u32 v53, 0, v66, v53
	v_and_b32_e32 v97, 15, v98
	s_waitcnt lgkmcnt(0)
	s_add_u32 s6, s6, s10
	s_addc_u32 s7, s7, s11
	global_load_dword v156, v3, s[6:7] offset:16
	s_waitcnt vmcnt(0)
	s_barrier
; #define MFMA16(a, b, c) __builtin_amdgcn_mfma_f32_16x16x32_bf16(a, b, c, 0, 0, 0)
; #define SCHED_FENCE() __builtin_amdgcn_sched_barrier(0)
; template <int MT> __device__ __forceinline__ void mma_xt(f32x4 (&acc)[MT], ldsp t, int ts, const bf16x8 (&own)[4], int lane) {
;     bf16x8 a[MT];
; #pragma unroll
;     for (int mt = 0; mt < MT; ++mt) a[mt] = row_frag(t, ts, 16 * mt, 0, lane);
; #pragma unroll
;     for (int ks = 0; ks < 4; ++ks) { bf16x8 an[MT];
;         if (ks < 3) {
; #pragma unroll
;             for (int mt = 0; mt < MT; ++mt) an[mt] = row_frag(t, ts, 16 * mt, ks + 1, lane); }
; #pragma unroll
;         for (int mt = 0; mt < MT; ++mt) acc[mt] = MFMA16(a[mt], own[ks], acc[mt]);
;         SCHED_FENCE();
;         if (ks < 3) {
; #pragma unroll
;             for (int mt = 0; mt < MT; ++mt) a[mt] = an[mt]; }
;     }
; }
; __device__ __forceinline__ void m4_ret_unit(Frame& F, int layer, int cr, int h) {
;     ...
;     s0.store(T0, TSR, tid); s1.store(T1, TSR, tid);
;     __syncthreads();
;     f32x4 af[8], ab[8]; zero_acc(af); zero_acc(ab);
;     mma_xt<8>(af, T0, TSR, qf, lane); mma_xt<8>(ab, T1, TSR, qf, lane);
	ds_write_b128 v53, v[12:15]
	v_mul_lo_u32 v12, v92, s72
	v_lshlrev_b32_e32 v13, 4, v67
	v_add3_u32 v12, 0, v12, v13
	v_mul_lo_u32 v13, v94, s72
	v_lshlrev_b32_e32 v14, 4, v93
	v_add3_u32 v13, 0, v13, v14
	v_mul_lo_u32 v14, v96, s72
	v_lshlrev_b32_e32 v15, 4, v95
	v_add3_u32 v14, 0, v14, v15
	v_and_b32_e32 v67, 63, v98
	ds_write_b128 v12, v[20:23]
	v_mul_u32_u24_e32 v92, 0x110, v97
	v_add3_u32 v157, 0, v92, v32
	ds_write_b128 v13, v[28:31]
	ds_write_b128 v14, v[70:73]
	ds_write_b128 v53, v[76:79] offset:34816
	ds_write_b128 v12, v[80:83] offset:34816
	ds_write_b128 v13, v[84:87] offset:34816
	ds_write_b128 v14, v[88:91] offset:34816
	v_add_u32_e32 v53, 0, v32
	v_or_b32_e32 v76, 48, v67
	v_or_b32_e32 v67, 0x70, v67
	v_mad_u32_u24 v66, v97, s72, v53
	v_mad_u32_u24 v128, v76, s72, v53
	v_mad_u32_u24 v53, v67, s72, v53
	s_waitcnt lgkmcnt(0)
	s_barrier
	ds_read_b128 v[12:15], v66
	ds_read_b128 v[20:23], v66 offset:4352
	ds_read_b128 v[28:31], v66 offset:8704
	ds_read_b128 v[70:73], v128
	v_mul_u32_u24_e32 v100, 0x110, v76
	ds_read_b128 v[76:79], v66 offset:17408
	ds_read_b128 v[80:83], v66 offset:21760
	ds_read_b128 v[84:87], v53
	ds_read_b128 v[88:91], v66 offset:26112
	ds_read_b128 v[92:95], v157 offset:64
	ds_read_b128 v[96:99], v157 offset:4416
	v_add3_u32 v158, 0, v100, v32
	ds_read_b128 v[100:103], v157 offset:8768
	ds_read_b128 v[104:107], v157 offset:17472
	ds_read_b128 v[108:111], v157 offset:21824
	ds_read_b128 v[112:115], v157 offset:26176
	v_mul_u32_u24_e32 v67, 0x110, v67
	v_add3_u32 v67, 0, v67, v32
	ds_read_b128 v[116:119], v158 offset:64
	ds_read_b128 v[120:123], v67 offset:64
	s_waitcnt lgkmcnt(14)
	v_mfma_f32_16x16x32_bf16 v[12:15], v[12:15], v[24:27], 0
	v_mfma_f32_16x16x32_bf16 v[20:23], v[20:23], v[24:27], 0
	s_waitcnt lgkmcnt(13)
	v_mfma_f32_16x16x32_bf16 v[28:31], v[28:31], v[24:27], 0
	s_waitcnt lgkmcnt(12)
	v_mfma_f32_16x16x32_bf16 v[70:73], v[70:73], v[24:27], 0
	s_waitcnt lgkmcnt(11)
	v_mfma_f32_16x16x32_bf16 v[76:79], v[76:79], v[24:27], 0
	s_waitcnt lgkmcnt(10)
	v_mfma_f32_16x16x32_bf16 v[80:83], v[80:83], v[24:27], 0
	s_waitcnt lgkmcnt(8)
	v_mfma_f32_16x16x32_bf16 v[88:91], v[88:91], v[24:27], 0
	v_mfma_f32_16x16x32_bf16 v[84:87], v[84:87], v[24:27], 0
	s_waitcnt lgkmcnt(7)
	v_mfma_f32_16x16x32_bf16 v[12:15], v[92:95], v[16:19], v[12:15]
	s_waitcnt lgkmcnt(6)
	v_mfma_f32_16x16x32_bf16 v[20:23], v[96:99], v[16:19], v[20:23]
	s_waitcnt lgkmcnt(5)
	v_mfma_f32_16x16x32_bf16 v[28:31], v[100:103], v[16:19], v[28:31]
	s_waitcnt lgkmcnt(1)
	v_mfma_f32_16x16x32_bf16 v[70:73], v[116:119], v[16:19], v[70:73]
	v_mfma_f32_16x16x32_bf16 v[76:79], v[104:107], v[16:19], v[76:79]
	ds_read_b128 v[92:95], v157 offset:128
	ds_read_b128 v[96:99], v157 offset:4480
	ds_read_b128 v[100:103], v157 offset:8832
	ds_read_b128 v[104:107], v157 offset:17536
	v_mfma_f32_16x16x32_bf16 v[80:83], v[108:111], v[16:19], v[80:83]
	v_mfma_f32_16x16x32_bf16 v[88:91], v[112:115], v[16:19], v[88:91]
	ds_read_b128 v[108:111], v157 offset:21888
	ds_read_b128 v[112:115], v157 offset:26240
	ds_read_b128 v[116:119], v158 offset:128
	ds_read_b128 v[124:127], v67 offset:128
	s_waitcnt lgkmcnt(8)
	v_mfma_f32_16x16x32_bf16 v[84:87], v[120:123], v[16:19], v[84:87]
	s_waitcnt lgkmcnt(7)
	v_mfma_f32_16x16x32_bf16 v[12:15], v[92:95], v[8:11], v[12:15]
	s_waitcnt lgkmcnt(6)
	v_mfma_f32_16x16x32_bf16 v[20:23], v[96:99], v[8:11], v[20:23]
	s_waitcnt lgkmcnt(5)
	v_mfma_f32_16x16x32_bf16 v[28:31], v[100:103], v[8:11], v[28:31]
	s_waitcnt lgkmcnt(1)
	v_mfma_f32_16x16x32_bf16 v[70:73], v[116:119], v[8:11], v[70:73]
	v_mfma_f32_16x16x32_bf16 v[76:79], v[104:107], v[8:11], v[76:79]
	ds_read_b128 v[92:95], v157 offset:192
	ds_read_b128 v[96:99], v157 offset:4544
	ds_read_b128 v[100:103], v157 offset:8896
	ds_read_b128 v[104:107], v157 offset:17600
	v_mfma_f32_16x16x32_bf16 v[80:83], v[108:111], v[8:11], v[80:83]
	v_mfma_f32_16x16x32_bf16 v[88:91], v[112:115], v[8:11], v[88:91]
	ds_read_b128 v[108:111], v157 offset:21952
	ds_read_b128 v[112:115], v157 offset:26304
	ds_read_b128 v[116:119], v158 offset:192
	ds_read_b128 v[120:123], v67 offset:192
	s_waitcnt lgkmcnt(8)
	v_mfma_f32_16x16x32_bf16 v[84:87], v[124:127], v[8:11], v[84:87]
	s_waitcnt lgkmcnt(7)
	v_mfma_f32_16x16x32_bf16 v[92:95], v[92:95], v[4:7], v[12:15]
	s_waitcnt lgkmcnt(6)
	v_mfma_f32_16x16x32_bf16 v[96:99], v[96:99], v[4:7], v[20:23]
	s_waitcnt lgkmcnt(5)
	v_mfma_f32_16x16x32_bf16 v[100:103], v[100:103], v[4:7], v[28:31]
	s_waitcnt lgkmcnt(1)
	v_mfma_f32_16x16x32_bf16 v[116:119], v[116:119], v[4:7], v[70:73]
	v_mfma_f32_16x16x32_bf16 v[76:79], v[104:107], v[4:7], v[76:79]
	v_mfma_f32_16x16x32_bf16 v[28:31], v[108:111], v[4:7], v[80:83]
	v_mfma_f32_16x16x32_bf16 v[20:23], v[112:115], v[4:7], v[88:91]
	s_waitcnt lgkmcnt(0)
	v_mfma_f32_16x16x32_bf16 v[12:15], v[120:123], v[4:7], v[84:87]
	ds_read_b128 v[70:73], v66 offset:34816
	ds_read_b128 v[80:83], v66 offset:39168
	s_nop 0
	ds_read_b128 v[84:87], v66 offset:43520
	ds_read_b128 v[88:91], v66 offset:52224
	ds_read_b128 v[104:107], v128 offset:34816
	ds_read_b128 v[108:111], v53 offset:34816
	ds_read_b128 v[112:115], v66 offset:56576
	ds_read_b128 v[120:123], v66 offset:60928
	ds_read_b128 v[124:127], v157 offset:34880
	ds_read_b128 v[128:131], v157 offset:39232
	ds_read_b128 v[132:135], v157 offset:43584
	ds_read_b128 v[136:139], v157 offset:52288
	ds_read_b128 v[140:143], v157 offset:56640
	ds_read_b128 v[144:147], v157 offset:60992
	ds_read_b128 v[148:151], v158 offset:34880
	ds_read_b128 v[152:155], v67 offset:34880
	s_waitcnt lgkmcnt(14)
	v_mfma_f32_16x16x32_bf16 v[70:73], v[70:73], v[24:27], 0
	v_mfma_f32_16x16x32_bf16 v[80:83], v[80:83], v[24:27], 0
	s_waitcnt lgkmcnt(13)
; __device__ __forceinline__ void m4_ret_unit(Frame& F, int layer, int cr, int h) {
;     ...
;     mma_xt<8>(af, T0, TSR, qf, lane); mma_xt<8>(ab, T1, TSR, qf, lane);
;     const float qfac = __expf(lgf * (float)(i + 1)) * scale, qbac = __expf(lgb * (float)(128 - i)) * scale;
;     f32x4 y[8]; float sm = 0.f;
; #pragma unroll
;     for (int mt = 0; mt < 8; ++mt) { const unsigned long long yw = yq[mt]; const unsigned y0 = (unsigned)yw, y1 = (unsigned)(yw >> 32);
;         y[mt] = (f32x4){bflo(y0), bfhi(y0), bflo(y1), bfhi(y1)} + af[mt] * qfac + ab[mt] * qbac; sm += (y[mt][0] + y[mt][1]) + (y[mt][2] + y[mt][3]); }
;     sm += __shfl_xor(sm, 16); sm += __shfl_xor(sm, 32);
;     const float mu = sm * (1.0f / 128.0f); float vs = 0.f;
; #pragma unroll
;     for (int mt = 0; mt < 8; ++mt) { y[mt] = y[mt] - mu; vs += (y[mt][0] * y[mt][0] + y[mt][1] * y[mt][1]) + (y[mt][2] * y[mt][2] + y[mt][3] * y[mt][3]); }
	v_mfma_f32_16x16x32_bf16 v[84:87], v[84:87], v[24:27], 0
	s_waitcnt lgkmcnt(11)
	v_mfma_f32_16x16x32_bf16 v[104:107], v[104:107], v[24:27], 0
	v_mfma_f32_16x16x32_bf16 v[88:91], v[88:91], v[24:27], 0
	s_waitcnt lgkmcnt(9)
	v_mfma_f32_16x16x32_bf16 v[112:115], v[112:115], v[24:27], 0
	s_waitcnt lgkmcnt(8)
	v_mfma_f32_16x16x32_bf16 v[120:123], v[120:123], v[24:27], 0
	v_mfma_f32_16x16x32_bf16 v[24:27], v[108:111], v[24:27], 0
	s_waitcnt lgkmcnt(7)
	v_mfma_f32_16x16x32_bf16 v[70:73], v[124:127], v[16:19], v[70:73]
	s_waitcnt lgkmcnt(6)
	v_mfma_f32_16x16x32_bf16 v[80:83], v[128:131], v[16:19], v[80:83]
	s_waitcnt lgkmcnt(5)
	v_mfma_f32_16x16x32_bf16 v[84:87], v[132:135], v[16:19], v[84:87]
	s_waitcnt lgkmcnt(1)
	v_mfma_f32_16x16x32_bf16 v[104:107], v[148:151], v[16:19], v[104:107]
	v_mfma_f32_16x16x32_bf16 v[88:91], v[136:139], v[16:19], v[88:91]
	v_mfma_f32_16x16x32_bf16 v[108:111], v[140:143], v[16:19], v[112:115]
	s_nop 2
	ds_read_b128 v[112:115], v157 offset:34944
	ds_read_b128 v[124:127], v157 offset:39296
	ds_read_b128 v[128:131], v157 offset:43648
	ds_read_b128 v[132:135], v157 offset:52352
	v_mfma_f32_16x16x32_bf16 v[120:123], v[144:147], v[16:19], v[120:123]
	ds_read_b128 v[136:139], v157 offset:56704
	ds_read_b128 v[140:143], v157 offset:61056
	ds_read_b128 v[144:147], v158 offset:34944
	ds_read_b128 v[148:151], v67 offset:34944
	s_waitcnt lgkmcnt(8)
	v_mfma_f32_16x16x32_bf16 v[16:19], v[152:155], v[16:19], v[24:27]
	s_waitcnt lgkmcnt(7)
	v_mfma_f32_16x16x32_bf16 v[24:27], v[112:115], v[8:11], v[70:73]
	s_waitcnt lgkmcnt(6)
	v_mfma_f32_16x16x32_bf16 v[70:73], v[124:127], v[8:11], v[80:83]
	s_waitcnt lgkmcnt(5)
	v_mfma_f32_16x16x32_bf16 v[80:83], v[128:131], v[8:11], v[84:87]
	s_waitcnt lgkmcnt(1)
	v_mfma_f32_16x16x32_bf16 v[84:87], v[144:147], v[8:11], v[104:107]
	v_mfma_f32_16x16x32_bf16 v[88:91], v[132:135], v[8:11], v[88:91]
	v_mfma_f32_16x16x32_bf16 v[104:107], v[136:139], v[8:11], v[108:111]
	s_nop 2
	ds_read_b128 v[108:111], v157 offset:35008
	ds_read_b128 v[112:115], v157 offset:39360
	ds_read_b128 v[124:127], v157 offset:43712
	ds_read_b128 v[128:131], v157 offset:52416
	v_mfma_f32_16x16x32_bf16 v[120:123], v[140:143], v[8:11], v[120:123]
	ds_read_b128 v[132:135], v157 offset:56768
	ds_read_b128 v[136:139], v157 offset:61120
	ds_read_b128 v[140:143], v158 offset:35008
	ds_read_b128 v[144:147], v67 offset:35008
	s_waitcnt lgkmcnt(8)
	v_mfma_f32_16x16x32_bf16 v[8:11], v[148:151], v[8:11], v[16:19]
	s_waitcnt lgkmcnt(7)
	v_mfma_f32_16x16x32_bf16 v[16:19], v[108:111], v[4:7], v[24:27]
	s_waitcnt lgkmcnt(6)
	v_mfma_f32_16x16x32_bf16 v[24:27], v[112:115], v[4:7], v[70:73]
	s_waitcnt lgkmcnt(5)
	v_mfma_f32_16x16x32_bf16 v[80:83], v[124:127], v[4:7], v[80:83]
	s_waitcnt lgkmcnt(1)
	v_mfma_f32_16x16x32_bf16 v[84:87], v[140:143], v[4:7], v[84:87]
	v_mfma_f32_16x16x32_bf16 v[88:91], v[128:131], v[4:7], v[88:91]
	v_mfma_f32_16x16x32_bf16 v[104:107], v[132:135], v[4:7], v[104:107]
	v_mfma_f32_16x16x32_bf16 v[108:111], v[136:139], v[4:7], v[120:123]
	s_waitcnt lgkmcnt(0)
	v_mfma_f32_16x16x32_bf16 v[112:115], v[144:147], v[4:7], v[8:11]
	v_add_u32_e32 v4, 1, v52
	v_cvt_f32_i32_e32 v4, v4
	v_sub_u32_e32 v5, 0x80, v52
	v_cvt_f32_i32_e32 v5, v5
	v_lshlrev_b32_e32 v8, 16, v62
	v_mul_f32_e64 v4, v4, |v33|
	v_mul_f32_e32 v4, 0xbfb8aa3b, v4
	v_mul_f32_e64 v5, v5, |v156|
	v_exp_f32_e32 v4, v4
	v_mul_f32_e32 v5, 0xbfb8aa3b, v5
	v_exp_f32_e32 v5, v5
	v_and_b32_e32 v9, 0xffff0000, v62
	v_mul_f32_e32 v4, 0x3db504f3, v4
	v_lshlrev_b32_e32 v10, 16, v63
	v_mul_f32_e32 v6, 0x3db504f3, v5
	v_and_b32_e32 v11, 0xffff0000, v63
	v_pk_fma_f32 v[8:9], v[4:5], v[92:93], v[8:9] op_sel_hi:[0,1,1]
	v_pk_fma_f32 v[10:11], v[4:5], v[94:95], v[10:11] op_sel_hi:[0,1,1]
	v_pk_fma_f32 v[72:73], v[6:7], v[16:17], v[8:9] op_sel_hi:[0,1,1]
	v_lshlrev_b32_e32 v8, 16, v58
	v_and_b32_e32 v9, 0xffff0000, v58
	v_pk_fma_f32 v[70:71], v[6:7], v[18:19], v[10:11] op_sel_hi:[0,1,1]
	v_lshlrev_b32_e32 v10, 16, v59
	v_and_b32_e32 v11, 0xffff0000, v59
	v_pk_fma_f32 v[8:9], v[4:5], v[96:97], v[8:9] op_sel_hi:[0,1,1]
	v_pk_fma_f32 v[10:11], v[4:5], v[98:99], v[10:11] op_sel_hi:[0,1,1]
	v_pk_fma_f32 v[66:67], v[6:7], v[24:25], v[8:9] op_sel_hi:[0,1,1]
	v_pk_fma_f32 v[62:63], v[6:7], v[26:27], v[10:11] op_sel_hi:[0,1,1]
	v_mov_b32_e32 v8, v72
	v_mov_b32_e32 v9, v66
	v_mov_b32_e32 v10, v73
	v_mov_b32_e32 v11, v67
	v_pk_add_f32 v[8:9], v[8:9], v[10:11]
	v_mov_b32_e32 v10, v70
	v_mov_b32_e32 v11, v62
	v_mov_b32_e32 v16, v71
	v_mov_b32_e32 v17, v63
	v_pk_add_f32 v[10:11], v[10:11], v[16:17]
	v_lshlrev_b32_e32 v16, 16, v57
	v_pk_add_f32 v[8:9], v[8:9], v[10:11]
	v_lshlrev_b32_e32 v10, 16, v56
	v_add_f32_e32 v5, 0, v8
	v_and_b32_e32 v11, 0xffff0000, v56
	v_and_b32_e32 v17, 0xffff0000, v57
	v_pk_fma_f32 v[16:17], v[4:5], v[102:103], v[16:17] op_sel_hi:[0,1,1]
	v_pk_fma_f32 v[10:11], v[4:5], v[100:101], v[10:11] op_sel_hi:[0,1,1]
	v_pk_fma_f32 v[56:57], v[6:7], v[82:83], v[16:17] op_sel_hi:[0,1,1]
	v_pk_fma_f32 v[58:59], v[6:7], v[80:81], v[10:11] op_sel_hi:[0,1,1]
	v_pk_mov_b32 v[10:11], v[58:59], v[56:57] op_sel:[1,0]
	v_mov_b32_e32 v16, v58
	v_mov_b32_e32 v17, v57
	v_pk_add_f32 v[10:11], v[10:11], v[16:17]
	v_lshlrev_b32_e32 v16, 16, v54
	v_and_b32_e32 v17, 0xffff0000, v54
	v_lshlrev_b32_e32 v18, 16, v55
	v_and_b32_e32 v19, 0xffff0000, v55
	v_lshlrev_b32_e32 v24, 16, v74
	v_and_b32_e32 v25, 0xffff0000, v74
	v_lshlrev_b32_e32 v26, 16, v75
	v_and_b32_e32 v27, 0xffff0000, v75
	v_pk_fma_f32 v[18:19], v[4:5], v[118:119], v[18:19] op_sel_hi:[0,1,1]
	v_pk_fma_f32 v[16:17], v[4:5], v[116:117], v[16:17] op_sel_hi:[0,1,1]
	v_pk_fma_f32 v[26:27], v[4:5], v[78:79], v[26:27] op_sel_hi:[0,1,1]
; __device__ __forceinline__ float rsq(float x) { return __builtin_amdgcn_rsqf(x); }
; __device__ __forceinline__ const float* inp(int i) { const __attribute__((address_space(4))) Args* ka = (const __attribute__((address_space(4))) Args*)__builtin_amdgcn_kernarg_segment_ptr(); return ka->in[opaque_s(i)]; }
; #define nw (inp(I_NORMW) + (size_t)layer * 6 * D)
; __device__ __forceinline__ void m4_ret_unit(Frame& F, int layer, int cr, int h) {
;     ...
;     const float qfac = __expf(lgf * (float)(i + 1)) * scale, qbac = __expf(lgb * (float)(128 - i)) * scale;
;     f32x4 y[8]; float sm = 0.f;
; #pragma unroll
;     for (int mt = 0; mt < 8; ++mt) { const unsigned long long yw = yq[mt]; const unsigned y0 = (unsigned)yw, y1 = (unsigned)(yw >> 32);
;         y[mt] = (f32x4){bflo(y0), bfhi(y0), bflo(y1), bfhi(y1)} + af[mt] * qfac + ab[mt] * qbac; sm += (y[mt][0] + y[mt][1]) + (y[mt][2] + y[mt][3]); }
;     sm += __shfl_xor(sm, 16); sm += __shfl_xor(sm, 32);
;     const float mu = sm * (1.0f / 128.0f); float vs = 0.f;
; #pragma unroll
;     for (int mt = 0; mt < 8; ++mt) { y[mt] = y[mt] - mu; vs += (y[mt][0] * y[mt][0] + y[mt][1] * y[mt][1]) + (y[mt][2] * y[mt][2] + y[mt][3] * y[mt][3]); }
;     vs += __shfl_xor(vs, 16); vs += __shfl_xor(vs, 32);
;     const float rstd = rsq(vs * (1.0f / 128.0f) + EPS);
;     const float* nw = inp(I_RNW) + layer * 512 + h * 128;
; #pragma unroll
;     for (int mt = 0; mt < 8; ++mt) { const int e = 16 * mt + 4 * g; const f32x4 wv = *(const f32x4*)(nw + e);
	v_pk_fma_f32 v[74:75], v[4:5], v[76:77], v[24:25] op_sel_hi:[0,1,1]
	v_pk_add_f32 v[10:11], v[10:11], v[10:11] op_sel:[0,1] op_sel_hi:[1,0]
	v_pk_fma_f32 v[52:53], v[6:7], v[86:87], v[18:19] op_sel_hi:[0,1,1]
	v_pk_fma_f32 v[54:55], v[6:7], v[84:85], v[16:17] op_sel_hi:[0,1,1]
	v_pk_fma_f32 v[24:25], v[6:7], v[90:91], v[26:27] op_sel_hi:[0,1,1]
	v_pk_fma_f32 v[26:27], v[6:7], v[88:89], v[74:75] op_sel_hi:[0,1,1]
	v_add_f32_e32 v8, v5, v9
	v_add_f32_e32 v16, v54, v55
	v_add_f32_e32 v18, v52, v53
	v_mov_b32_e32 v9, v26
	v_mov_b32_e32 v11, v27
	v_mov_b32_e32 v17, v24
	v_mov_b32_e32 v19, v25
	v_pk_add_f32 v[8:9], v[8:9], v[10:11]
	v_pk_add_f32 v[10:11], v[16:17], v[18:19]
	s_mov_b32 s6, 14
	v_pk_add_f32 v[8:9], v[8:9], v[10:11]
	v_lshlrev_b32_e32 v10, 16, v69
	v_pk_add_f32 v[74:75], v[8:9], v[8:9] op_sel:[0,1] op_sel_hi:[1,0]
	v_lshlrev_b32_e32 v8, 16, v68
	v_and_b32_e32 v9, 0xffff0000, v68
	v_and_b32_e32 v11, 0xffff0000, v69
	v_pk_fma_f32 v[10:11], v[4:5], v[30:31], v[10:11] op_sel_hi:[0,1,1]
	v_pk_fma_f32 v[8:9], v[4:5], v[28:29], v[8:9] op_sel_hi:[0,1,1]
	v_pk_fma_f32 v[16:17], v[6:7], v[106:107], v[10:11] op_sel_hi:[0,1,1]
	v_pk_fma_f32 v[18:19], v[6:7], v[104:105], v[8:9] op_sel_hi:[0,1,1]
	v_pk_mov_b32 v[8:9], v[18:19], v[16:17] op_sel:[1,0]
	v_mov_b32_e32 v10, v18
	v_mov_b32_e32 v11, v17
	v_pk_add_f32 v[8:9], v[8:9], v[10:11]
	v_lshlrev_b32_e32 v10, 16, v65
	v_pk_add_f32 v[28:29], v[8:9], v[8:9] op_sel:[0,1] op_sel_hi:[1,0]
	v_lshlrev_b32_e32 v8, 16, v64
	v_and_b32_e32 v9, 0xffff0000, v64
	v_and_b32_e32 v11, 0xffff0000, v65
	v_lshlrev_b32_e32 v30, 16, v60
	v_and_b32_e32 v31, 0xffff0000, v60
	v_lshlrev_b32_e32 v60, 16, v61
	v_and_b32_e32 v61, 0xffff0000, v61
	v_pk_fma_f32 v[10:11], v[4:5], v[22:23], v[10:11] op_sel_hi:[0,1,1]
	v_pk_fma_f32 v[20:21], v[4:5], v[20:21], v[8:9] op_sel_hi:[0,1,1]
	v_pk_fma_f32 v[14:15], v[4:5], v[14:15], v[60:61] op_sel_hi:[0,1,1]
	v_pk_fma_f32 v[12:13], v[4:5], v[12:13], v[30:31] op_sel_hi:[0,1,1]
	v_pk_fma_f32 v[8:9], v[6:7], v[110:111], v[10:11] op_sel_hi:[0,1,1]
	v_pk_fma_f32 v[10:11], v[6:7], v[108:109], v[20:21] op_sel_hi:[0,1,1]
	v_pk_fma_f32 v[4:5], v[6:7], v[114:115], v[14:15] op_sel_hi:[0,1,1]
	v_pk_fma_f32 v[6:7], v[6:7], v[112:113], v[12:13] op_sel_hi:[0,1,1]
	v_add_f32_e32 v20, v10, v11
	v_add_f32_e32 v22, v8, v9
	v_mov_b32_e32 v75, v6
	v_mov_b32_e32 v29, v7
	v_mov_b32_e32 v21, v4
	v_mov_b32_e32 v23, v5
	v_pk_add_f32 v[12:13], v[74:75], v[28:29]
	v_pk_add_f32 v[14:15], v[20:21], v[22:23]
	s_ashr_i32 s7, s6, 31
	v_pk_add_f32 v[12:13], v[12:13], v[14:15]
	v_and_b32_e32 v14, 64, v216
	v_add_f32_e32 v12, v12, v13
	v_xor_b32_e32 v13, 16, v216
	v_add_u32_e32 v14, 64, v14
	v_cmp_lt_i32_e32 vcc, v13, v14
	s_lshl_b64 s[6:7], s[6:7], 3
	s_add_u32 s6, s20, s6
	v_cndmask_b32_e32 v13, v216, v13, vcc
	v_lshlrev_b32_e32 v33, 2, v13
	ds_bpermute_b32 v13, v33, v12
	s_addc_u32 s7, s21, s7
	s_load_dwordx2 s[6:7], s[6:7], 0x0
	s_waitcnt lgkmcnt(0)
	v_add_f32_e32 v12, v12, v13
	v_xor_b32_e32 v13, 32, v216
	v_cmp_lt_i32_e32 vcc, v13, v14
	s_add_u32 s6, s6, s4
	s_addc_u32 s7, s7, s5
	v_cndmask_b32_e32 v13, v216, v13, vcc
	v_lshlrev_b32_e32 v60, 2, v13
	ds_bpermute_b32 v13, v60, v12
	s_lshl_b32 s9, s14, 9
	s_add_u32 s6, s6, s9
	s_addc_u32 s7, s7, 0
	s_add_u32 s10, s3, s92
	s_waitcnt lgkmcnt(0)
	v_add_f32_e32 v61, v12, v13
	v_fmamk_f32 v73, v61, 0xbc000000, v73
	v_fmamk_f32 v67, v61, 0xbc000000, v67
	v_fmamk_f32 v71, v61, 0xbc000000, v71
	v_fmac_f32_e32 v72, 0xbc000000, v61
	v_fmamk_f32 v63, v61, 0xbc000000, v63
	v_fmac_f32_e32 v66, 0xbc000000, v61
	v_mov_b32_e32 v14, v73
	v_mov_b32_e32 v15, v67
	v_fmac_f32_e32 v70, 0xbc000000, v61
	v_fmac_f32_e32 v62, 0xbc000000, v61
	v_mov_b32_e32 v12, v72
	v_mov_b32_e32 v13, v66
	v_pk_mul_f32 v[14:15], v[14:15], v[14:15]
	v_mov_b32_e32 v20, v71
	v_mov_b32_e32 v21, v63
	v_pk_fma_f32 v[12:13], v[12:13], v[12:13], v[14:15]
	v_mov_b32_e32 v14, v70
	v_mov_b32_e32 v15, v62
	v_pk_mul_f32 v[20:21], v[20:21], v[20:21]
	v_fmamk_f32 v59, v61, 0xbc000000, v59
	v_pk_fma_f32 v[14:15], v[14:15], v[14:15], v[20:21]
	global_load_dwordx4 v[20:23], v32, s[6:7]
	global_load_dwordx4 v[176:179], v32, s[6:7] offset:64
	global_load_dwordx4 v[180:183], v32, s[6:7] offset:128
	global_load_dwordx4 v[184:187], v32, s[6:7] offset:192
	global_load_dwordx4 v[188:191], v32, s[6:7] offset:256
	global_load_dwordx4 v[192:195], v32, s[6:7] offset:320
	global_load_dwordx4 v[196:199], v32, s[6:7] offset:384
	global_load_dwordx4 v[200:203], v32, s[6:7] offset:448
	v_pk_add_f32 v[12:13], v[12:13], v[14:15]
	v_fmac_f32_e32 v58, 0xbc000000, v61
	v_fmamk_f32 v57, v61, 0xbc000000, v57
	v_fmac_f32_e32 v56, 0xbc000000, v61
	v_pk_add_f32 v[12:13], v[12:13], v[12:13] op_sel_hi:[0,1]
	v_pk_mul_f32 v[14:15], v[56:57], v[56:57]
	v_pk_mul_f32 v[28:29], v[58:59], v[58:59]
	v_fmac_f32_e32 v54, 0xbc000000, v61
	v_pk_mov_b32 v[30:31], v[28:29], v[14:15] op_sel:[1,0]
	v_mov_b32_e32 v29, v15
	v_fmamk_f32 v55, v61, 0xbc000000, v55
	v_fmac_f32_e32 v52, 0xbc000000, v61
	v_mul_f32_e32 v12, v54, v54
	v_pk_add_f32 v[14:15], v[30:31], v[28:29]
	v_fmamk_f32 v53, v61, 0xbc000000, v53
	v_pk_fma_f32 v[28:29], v[54:55], v[54:55], v[12:13] op_sel_hi:[1,1,0]
	v_mul_f32_e32 v12, v52, v52
	v_pk_add_f32 v[14:15], v[14:15], v[14:15] op_sel_hi:[0,1]
	v_pk_fma_f32 v[30:31], v[52:53], v[52:53], v[12:13] op_sel_hi:[1,1,0]
	v_fmamk_f32 v25, v61, 0xbc000000, v25
	v_fmac_f32_e32 v24, 0xbc000000, v61
	v_fmamk_f32 v27, v61, 0xbc000000, v27
	v_fmac_f32_e32 v26, 0xbc000000, v61
	v_mul_f32_e32 v28, v26, v26
	v_mul_f32_e32 v30, v27, v27
	v_mul_f32_e32 v14, v24, v24
	v_mul_f32_e32 v12, v25, v25
	v_pk_add_f32 v[28:29], v[28:29], v[30:31]
	v_pk_add_f32 v[12:13], v[14:15], v[12:13]
; __device__ __forceinline__ unsigned pk2(float lo, float hi) { return cvtpk(lo, hi); }
; __device__ __forceinline__ float silu(float x) { return x * __builtin_amdgcn_rcpf(1.0f + __builtin_amdgcn_exp2f(x * -1.44269504089f)); }
; __device__ __forceinline__ float rsq(float x) { return __builtin_amdgcn_rsqf(x); }
; __device__ __forceinline__ const float* inp(int i) { const __attribute__((address_space(4))) Args* ka = (const __attribute__((address_space(4))) Args*)__builtin_amdgcn_kernarg_segment_ptr(); return ka->in[opaque_s(i)]; }
; #define nw (inp(I_NORMW) + (size_t)layer * 6 * D)
; __device__ __forceinline__ void m4_ret_unit(Frame& F, int layer, int cr, int h) {
;     ...
;     vs += __shfl_xor(vs, 16); vs += __shfl_xor(vs, 32);
;     const float rstd = rsq(vs * (1.0f / 128.0f) + EPS);
;     const float* nw = inp(I_RNW) + layer * 512 + h * 128;
; #pragma unroll
;     for (int mt = 0; mt < 8; ++mt) { const int e = 16 * mt + 4 * g; const f32x4 wv = *(const f32x4*)(nw + e);
;         const unsigned long long gt = gq[mt]; const unsigned g0 = (unsigned)gt, g1 = (unsigned)(gt >> 32);
;         const f32x4 o = y[mt] * rstd * wv;
;         *(unsigned long long*)(pA + m * D + h * 128 + e) = (unsigned long long)pk2(o[0] * silu(bflo(g0)), o[1] * silu(bfhi(g0))) | ((unsigned long long)pk2(o[2] * silu(bflo(g1)), o[3] * silu(bfhi(g1))) << 32); }
	v_fmamk_f32 v19, v61, 0xbc000000, v19
	v_pk_add_f32 v[12:13], v[28:29], v[12:13]
	v_fmac_f32_e32 v18, 0xbc000000, v61
	v_fmamk_f32 v17, v61, 0xbc000000, v17
	v_fmac_f32_e32 v16, 0xbc000000, v61
	v_pk_add_f32 v[12:13], v[12:13], v[12:13] op_sel_hi:[0,1]
	v_pk_mul_f32 v[14:15], v[16:17], v[16:17]
	v_pk_mul_f32 v[28:29], v[18:19], v[18:19]
	v_fmac_f32_e32 v10, 0xbc000000, v61
	v_pk_mov_b32 v[30:31], v[28:29], v[14:15] op_sel:[1,0]
	v_mov_b32_e32 v29, v15
	v_fmamk_f32 v11, v61, 0xbc000000, v11
	v_fmac_f32_e32 v8, 0xbc000000, v61
	v_mul_f32_e32 v12, v10, v10
	v_pk_add_f32 v[14:15], v[30:31], v[28:29]
	v_fmamk_f32 v9, v61, 0xbc000000, v9
	v_pk_fma_f32 v[28:29], v[10:11], v[10:11], v[12:13] op_sel_hi:[1,1,0]
	v_mul_f32_e32 v12, v8, v8
	v_pk_add_f32 v[14:15], v[14:15], v[14:15] op_sel_hi:[0,1]
	v_pk_fma_f32 v[30:31], v[8:9], v[8:9], v[12:13] op_sel_hi:[1,1,0]
	v_fmamk_f32 v5, v61, 0xbc000000, v5
	v_fmac_f32_e32 v4, 0xbc000000, v61
	v_fmamk_f32 v7, v61, 0xbc000000, v7
	v_fmac_f32_e32 v6, 0xbc000000, v61
	v_mul_f32_e32 v28, v6, v6
	v_mul_f32_e32 v30, v7, v7
	v_mul_f32_e32 v14, v4, v4
	v_mul_f32_e32 v12, v5, v5
	v_pk_add_f32 v[28:29], v[28:29], v[30:31]
	v_pk_add_f32 v[12:13], v[14:15], v[12:13]
	v_lshlrev_b64 v[14:15], 12, v[44:45]
	v_pk_add_f32 v[12:13], v[28:29], v[12:13]
	v_and_b32_e32 v44, 0xffff0000, v50
	v_add_f32_e32 v12, v12, v13
	ds_bpermute_b32 v13, v33, v12
	v_mul_f32_e32 v45, 0xbfb8aa3b, v44
	v_exp_f32_e32 v45, v45
	s_addc_u32 s11, s8, 0
	v_lshl_add_u64 v[14:15], s[10:11], 0, v[14:15]
	s_waitcnt lgkmcnt(0)
	v_add_f32_e32 v12, v12, v13
	ds_bpermute_b32 v13, v60, v12
	v_lshl_add_u64 v[14:15], v[14:15], 0, v[2:3]
	v_lshlrev_b32_e32 v2, 16, v48
	s_add_i32 s2, s2, s13
	s_cmp_lt_i32 s2, s1
	s_waitcnt lgkmcnt(0)
	v_add_f32_e32 v12, v12, v13
	v_fmamk_f32 v12, v12, 0x3c000000, v214
	v_rsq_f32_e32 v12, v12
	s_nop 0
	v_pk_mul_f32 v[28:29], v[72:73], v[12:13] op_sel_hi:[1,0]
	v_pk_mul_f32 v[30:31], v[70:71], v[12:13] op_sel_hi:[1,0]
	v_lshlrev_b32_e32 v13, 16, v50
	v_mul_f32_e32 v33, 0xbfb8aa3b, v13
	v_exp_f32_e32 v33, v33
	s_waitcnt vmcnt(0)
	v_pk_mul_f32 v[22:23], v[22:23], v[30:31]
	v_add_f32_e32 v31, 1.0, v45
	v_rcp_f32_e32 v31, v31
	v_add_f32_e32 v30, 1.0, v33
	v_rcp_f32_e32 v30, v30
	v_pk_mul_f32 v[20:21], v[20:21], v[28:29]
	v_lshlrev_b32_e32 v28, 16, v51
	v_mul_f32_e32 v29, 0xbfb8aa3b, v28
	v_mul_f32_e32 v13, v30, v13
	v_and_b32_e32 v30, 0xffff0000, v51
	v_mul_f32_e32 v13, v13, v20
	v_mul_f32_e32 v20, v31, v44
	v_mul_f32_e32 v31, 0xbfb8aa3b, v30
	v_exp_f32_e32 v29, v29
	v_exp_f32_e32 v31, v31
	v_mul_f32_e32 v20, v20, v21
	v_cvt_pk_bf16_f32 v20, v13, v20
	v_add_f32_e32 v21, 1.0, v29
	v_add_f32_e32 v29, 1.0, v31
	v_rcp_f32_e32 v21, v21
	v_rcp_f32_e32 v29, v29
	v_and_b32_e32 v33, 0xffff0000, v48
	v_mul_f32_e32 v44, 0xbfb8aa3b, v33
	v_mul_f32_e32 v13, v21, v28
	v_mul_f32_e32 v21, v29, v30
	v_mul_f32_e32 v21, v21, v23
	v_mul_f32_e32 v13, v13, v22
	v_cvt_pk_bf16_f32 v21, v13, v21
	global_store_dwordx2 v[14:15], v[20:21], off
	v_mov_b32_e32 v20, v176
	v_mov_b32_e32 v21, v177
	v_mov_b32_e32 v22, v178
	v_mov_b32_e32 v23, v179
	v_pk_mul_f32 v[28:29], v[66:67], v[12:13] op_sel_hi:[1,0]
	v_pk_mul_f32 v[30:31], v[62:63], v[12:13] op_sel_hi:[1,0]
	v_mul_f32_e32 v13, 0xbfb8aa3b, v2
	v_exp_f32_e32 v13, v13
	v_exp_f32_e32 v44, v44
	v_add_f32_e32 v13, 1.0, v13
	v_rcp_f32_e32 v13, v13
	v_pk_mul_f32 v[22:23], v[22:23], v[30:31]
	v_add_f32_e32 v30, 1.0, v44
	v_rcp_f32_e32 v30, v30
	v_pk_mul_f32 v[20:21], v[20:21], v[28:29]
	v_mul_f32_e32 v2, v13, v2
	v_lshlrev_b32_e32 v28, 16, v49
	v_mul_f32_e32 v2, v2, v20
	v_mul_f32_e32 v20, 0xbfb8aa3b, v28
	v_and_b32_e32 v29, 0xffff0000, v49
	v_mul_f32_e32 v13, v30, v33
	v_exp_f32_e32 v20, v20
	v_mul_f32_e32 v30, 0xbfb8aa3b, v29
	v_exp_f32_e32 v30, v30
	v_mul_f32_e32 v13, v13, v21
	v_add_f32_e32 v20, 1.0, v20
	v_rcp_f32_e32 v21, v20
	v_add_f32_e32 v20, 1.0, v30
	v_rcp_f32_e32 v30, v20
	v_cvt_pk_bf16_f32 v20, v2, v13
	v_mul_f32_e32 v2, v21, v28
	v_mul_f32_e32 v2, v2, v22
	v_mul_f32_e32 v13, v30, v29
	v_mul_f32_e32 v13, v13, v23
	v_cvt_pk_bf16_f32 v21, v2, v13
	global_store_dwordx2 v[14:15], v[20:21], off offset:32
	v_mov_b32_e32 v20, v180
	v_mov_b32_e32 v21, v181
	v_mov_b32_e32 v22, v182
	v_mov_b32_e32 v23, v183
	v_lshlrev_b32_e32 v2, 16, v46
	v_pk_mul_f32 v[28:29], v[58:59], v[12:13] op_sel_hi:[1,0]
	v_pk_mul_f32 v[30:31], v[56:57], v[12:13] op_sel_hi:[1,0]
	v_mul_f32_e32 v13, 0xbfb8aa3b, v2
	v_exp_f32_e32 v13, v13
	v_and_b32_e32 v33, 0xffff0000, v46
	v_mul_f32_e32 v44, 0xbfb8aa3b, v33
	v_exp_f32_e32 v44, v44
	v_add_f32_e32 v13, 1.0, v13
	v_rcp_f32_e32 v13, v13
	v_pk_mul_f32 v[22:23], v[22:23], v[30:31]
	v_add_f32_e32 v30, 1.0, v44
	v_rcp_f32_e32 v30, v30
	v_pk_mul_f32 v[20:21], v[20:21], v[28:29]
	v_mul_f32_e32 v2, v13, v2
	v_lshlrev_b32_e32 v28, 16, v47
	v_mul_f32_e32 v2, v2, v20
	v_mul_f32_e32 v20, 0xbfb8aa3b, v28
	v_and_b32_e32 v29, 0xffff0000, v47
	v_mul_f32_e32 v13, v30, v33
	v_exp_f32_e32 v20, v20
	v_mul_f32_e32 v30, 0xbfb8aa3b, v29
	v_exp_f32_e32 v30, v30
	v_mul_f32_e32 v13, v13, v21
	v_add_f32_e32 v20, 1.0, v20
	v_rcp_f32_e32 v21, v20
	v_add_f32_e32 v20, 1.0, v30
	v_rcp_f32_e32 v30, v20
	v_cvt_pk_bf16_f32 v20, v2, v13
	v_mul_f32_e32 v2, v21, v28
	v_mul_f32_e32 v2, v2, v22
	v_mul_f32_e32 v13, v30, v29
	v_mul_f32_e32 v13, v13, v23
	v_cvt_pk_bf16_f32 v21, v2, v13
	global_store_dwordx2 v[14:15], v[20:21], off offset:64
	v_mov_b32_e32 v20, v184
	v_mov_b32_e32 v21, v185
	v_mov_b32_e32 v22, v186
	v_mov_b32_e32 v23, v187
	v_lshlrev_b32_e32 v2, 16, v42
	v_pk_mul_f32 v[28:29], v[54:55], v[12:13] op_sel_hi:[1,0]
	v_pk_mul_f32 v[30:31], v[52:53], v[12:13] op_sel_hi:[1,0]
	v_mul_f32_e32 v13, 0xbfb8aa3b, v2
	v_exp_f32_e32 v13, v13
; __device__ __forceinline__ unsigned pk2(float lo, float hi) { return cvtpk(lo, hi); }
; __device__ __forceinline__ float silu(float x) { return x * __builtin_amdgcn_rcpf(1.0f + __builtin_amdgcn_exp2f(x * -1.44269504089f)); }
; #define SEG_BEGIN(id) unsigned long long segt0_##id = 0; if ((PROBE_SEG >> (id)) & 1) segt0_##id = __builtin_amdgcn_s_memrealtime();
; #define SEG_END(id) if ((PROBE_SEG >> (id)) & 1) { __syncthreads(); const unsigned long long t1_ = __builtin_amdgcn_s_memrealtime(); while (__builtin_amdgcn_s_memrealtime() - t1_ < t1_ - segt0_##id) __builtin_amdgcn_s_sleep(16); __syncthreads(); }
; #define nw (inp(I_NORMW) + (size_t)layer * 6 * D)
; __device__ __forceinline__ void m4_ret_unit(Frame& F, int layer, int cr, int h) {
;     ...
;     for (int mt = 0; mt < 8; ++mt) { const int e = 16 * mt + 4 * g; const f32x4 wv = *(const f32x4*)(nw + e);
;         const unsigned long long gt = gq[mt]; const unsigned g0 = (unsigned)gt, g1 = (unsigned)(gt >> 32);
;         const f32x4 o = y[mt] * rstd * wv;
;         *(unsigned long long*)(pA + m * D + h * 128 + e) = (unsigned long long)pk2(o[0] * silu(bflo(g0)), o[1] * silu(bfhi(g0))) | ((unsigned long long)pk2(o[2] * silu(bflo(g1)), o[3] * silu(bfhi(g1))) << 32); }
;     ...
;     else if (which & 2) { SEG_BEGIN(1) for (int u = bid - ncr; u < ncr * 4; u += F.G - ncr) m4_ret_unit(F, layer, u >> 2, u & 3); SEG_END(1) }
	v_and_b32_e32 v33, 0xffff0000, v42
	v_mul_f32_e32 v42, 0xbfb8aa3b, v33
	v_exp_f32_e32 v42, v42
	v_add_f32_e32 v13, 1.0, v13
	v_rcp_f32_e32 v13, v13
	v_pk_mul_f32 v[22:23], v[22:23], v[30:31]
	v_add_f32_e32 v30, 1.0, v42
	v_rcp_f32_e32 v30, v30
	v_pk_mul_f32 v[20:21], v[20:21], v[28:29]
	v_mul_f32_e32 v2, v13, v2
	v_lshlrev_b32_e32 v28, 16, v43
	v_mul_f32_e32 v2, v2, v20
	v_mul_f32_e32 v20, 0xbfb8aa3b, v28
	v_and_b32_e32 v29, 0xffff0000, v43
	v_mul_f32_e32 v13, v30, v33
	v_exp_f32_e32 v20, v20
	v_mul_f32_e32 v30, 0xbfb8aa3b, v29
	v_exp_f32_e32 v30, v30
	v_mul_f32_e32 v13, v13, v21
	v_add_f32_e32 v20, 1.0, v20
	v_rcp_f32_e32 v21, v20
	v_add_f32_e32 v20, 1.0, v30
	v_rcp_f32_e32 v30, v20
	v_cvt_pk_bf16_f32 v20, v2, v13
	v_mul_f32_e32 v2, v21, v28
	v_mul_f32_e32 v2, v2, v22
	v_mul_f32_e32 v13, v30, v29
	v_mul_f32_e32 v13, v13, v23
	v_cvt_pk_bf16_f32 v21, v2, v13
	global_store_dwordx2 v[14:15], v[20:21], off offset:96
	v_mov_b32_e32 v20, v188
	v_mov_b32_e32 v21, v189
	v_mov_b32_e32 v22, v190
	v_mov_b32_e32 v23, v191
	v_and_b32_e32 v13, 0xffff0000, v40
	v_mul_f32_e32 v31, 0xbfb8aa3b, v13
	v_lshlrev_b32_e32 v28, 16, v41
	v_exp_f32_e32 v31, v31
	v_lshlrev_b32_e32 v2, 16, v40
	v_and_b32_e32 v29, 0xffff0000, v41
	v_mul_f32_e32 v33, 0xbfb8aa3b, v28
	v_mul_f32_e32 v30, 0xbfb8aa3b, v2
	v_mul_f32_e32 v40, 0xbfb8aa3b, v29
	v_exp_f32_e32 v33, v33
	v_exp_f32_e32 v30, v30
	v_exp_f32_e32 v40, v40
	v_add_f32_e32 v31, 1.0, v31
	v_rcp_f32_e32 v31, v31
	v_add_f32_e32 v33, 1.0, v33
	v_add_f32_e32 v30, 1.0, v30
	v_add_f32_e32 v40, 1.0, v40
	v_rcp_f32_e32 v33, v33
	v_rcp_f32_e32 v30, v30
	v_rcp_f32_e32 v40, v40
	v_mul_f32_e32 v13, v31, v13
	v_pk_mul_f32 v[26:27], v[26:27], v[12:13] op_sel_hi:[1,0]
	v_pk_mul_f32 v[24:25], v[24:25], v[12:13] op_sel_hi:[1,0]
	v_mul_f32_e32 v28, v33, v28
	v_mul_f32_e32 v2, v30, v2
	v_mul_f32_e32 v29, v40, v29
	v_pk_mul_f32 v[22:23], v[22:23], v[24:25]
	v_pk_mul_f32 v[20:21], v[20:21], v[26:27]
	v_and_b32_e32 v25, 0xffff0000, v39
	v_mul_f32_e32 v13, v13, v21
	v_mul_f32_e32 v21, v28, v22
	v_mul_f32_e32 v2, v2, v20
	v_mul_f32_e32 v22, v29, v23
	v_cvt_pk_bf16_f32 v20, v2, v13
	v_cvt_pk_bf16_f32 v21, v21, v22
	global_store_dwordx2 v[14:15], v[20:21], off offset:128
	v_mov_b32_e32 v20, v192
	v_mov_b32_e32 v21, v193
	v_mov_b32_e32 v22, v194
	v_mov_b32_e32 v23, v195
	v_and_b32_e32 v13, 0xffff0000, v38
	v_mul_f32_e32 v27, 0xbfb8aa3b, v13
	v_exp_f32_e32 v27, v27
	v_lshlrev_b32_e32 v2, 16, v38
	v_lshlrev_b32_e32 v24, 16, v39
	v_mul_f32_e32 v29, 0xbfb8aa3b, v25
	v_mul_f32_e32 v26, 0xbfb8aa3b, v2
	v_mul_f32_e32 v28, 0xbfb8aa3b, v24
	v_exp_f32_e32 v29, v29
	v_exp_f32_e32 v26, v26
	v_exp_f32_e32 v28, v28
	v_add_f32_e32 v27, 1.0, v27
	v_rcp_f32_e32 v27, v27
	v_add_f32_e32 v29, 1.0, v29
	v_add_f32_e32 v26, 1.0, v26
	v_add_f32_e32 v28, 1.0, v28
	v_rcp_f32_e32 v29, v29
	v_rcp_f32_e32 v26, v26
	v_rcp_f32_e32 v28, v28
	v_mul_f32_e32 v13, v27, v13
	v_pk_mul_f32 v[16:17], v[16:17], v[12:13] op_sel_hi:[1,0]
	v_mul_f32_e32 v25, v29, v25
	v_pk_mul_f32 v[18:19], v[18:19], v[12:13] op_sel_hi:[1,0]
	v_mul_f32_e32 v2, v26, v2
	v_mul_f32_e32 v24, v28, v24
	v_pk_mul_f32 v[16:17], v[22:23], v[16:17]
	v_pk_mul_f32 v[18:19], v[20:21], v[18:19]
	v_mul_f32_e32 v17, v25, v17
	v_mul_f32_e32 v2, v2, v18
	v_mul_f32_e32 v13, v13, v19
	v_mul_f32_e32 v18, v24, v16
	v_cvt_pk_bf16_f32 v16, v2, v13
	v_cvt_pk_bf16_f32 v17, v18, v17
	global_store_dwordx2 v[14:15], v[16:17], off offset:160
	v_mov_b32_e32 v16, v196
	v_mov_b32_e32 v17, v197
	v_mov_b32_e32 v18, v198
	v_mov_b32_e32 v19, v199
	v_and_b32_e32 v13, 0xffff0000, v36
	v_mul_f32_e32 v23, 0xbfb8aa3b, v13
	v_and_b32_e32 v21, 0xffff0000, v37
	v_exp_f32_e32 v23, v23
	v_lshlrev_b32_e32 v2, 16, v36
	v_lshlrev_b32_e32 v20, 16, v37
	v_mul_f32_e32 v25, 0xbfb8aa3b, v21
	v_mul_f32_e32 v22, 0xbfb8aa3b, v2
	v_mul_f32_e32 v24, 0xbfb8aa3b, v20
	v_exp_f32_e32 v25, v25
	v_exp_f32_e32 v22, v22
	v_exp_f32_e32 v24, v24
	v_add_f32_e32 v23, 1.0, v23
	v_rcp_f32_e32 v23, v23
	v_add_f32_e32 v25, 1.0, v25
	v_add_f32_e32 v22, 1.0, v22
	v_add_f32_e32 v24, 1.0, v24
	v_rcp_f32_e32 v25, v25
	v_rcp_f32_e32 v22, v22
	v_rcp_f32_e32 v24, v24
	v_mul_f32_e32 v13, v23, v13
	v_pk_mul_f32 v[8:9], v[8:9], v[12:13] op_sel_hi:[1,0]
	v_mul_f32_e32 v21, v25, v21
	v_pk_mul_f32 v[10:11], v[10:11], v[12:13] op_sel_hi:[1,0]
	v_mul_f32_e32 v2, v22, v2
	v_mul_f32_e32 v20, v24, v20
	v_pk_mul_f32 v[8:9], v[8:9], v[18:19]
	v_pk_mul_f32 v[10:11], v[10:11], v[16:17]
	v_mul_f32_e32 v9, v21, v9
	v_mul_f32_e32 v2, v2, v10
	v_mul_f32_e32 v10, v13, v11
	v_mul_f32_e32 v11, v20, v8
	v_cvt_pk_bf16_f32 v8, v2, v10
	v_cvt_pk_bf16_f32 v9, v11, v9
	global_store_dwordx2 v[14:15], v[8:9], off offset:192
	v_mov_b32_e32 v8, v200
	v_mov_b32_e32 v9, v201
	v_mov_b32_e32 v10, v202
	v_mov_b32_e32 v11, v203
	v_and_b32_e32 v13, 0xffff0000, v34
	v_mul_f32_e32 v19, 0xbfb8aa3b, v13
	v_and_b32_e32 v17, 0xffff0000, v35
	v_exp_f32_e32 v19, v19
	v_lshlrev_b32_e32 v2, 16, v34
	v_lshlrev_b32_e32 v16, 16, v35
	v_mul_f32_e32 v21, 0xbfb8aa3b, v17
	v_mul_f32_e32 v18, 0xbfb8aa3b, v2
	v_mul_f32_e32 v20, 0xbfb8aa3b, v16
	v_exp_f32_e32 v21, v21
	v_exp_f32_e32 v18, v18
	v_exp_f32_e32 v20, v20
	v_add_f32_e32 v19, 1.0, v19
	v_rcp_f32_e32 v19, v19
	v_add_f32_e32 v21, 1.0, v21
	v_add_f32_e32 v18, 1.0, v18
	v_add_f32_e32 v20, 1.0, v20
	v_rcp_f32_e32 v21, v21
	v_rcp_f32_e32 v18, v18
	v_rcp_f32_e32 v20, v20
	v_mul_f32_e32 v13, v19, v13
	v_pk_mul_f32 v[4:5], v[4:5], v[12:13] op_sel_hi:[1,0]
	v_mul_f32_e32 v17, v21, v17
	v_pk_mul_f32 v[6:7], v[6:7], v[12:13] op_sel_hi:[1,0]
	v_mul_f32_e32 v2, v18, v2
	v_mul_f32_e32 v16, v20, v16
	v_pk_mul_f32 v[4:5], v[4:5], v[10:11]
	v_pk_mul_f32 v[6:7], v[6:7], v[8:9]
	v_mul_f32_e32 v5, v17, v5
	v_mul_f32_e32 v2, v2, v6
	v_mul_f32_e32 v6, v13, v7
	v_mul_f32_e32 v7, v16, v4
	v_cvt_pk_bf16_f32 v4, v2, v6
	v_cvt_pk_bf16_f32 v5, v7, v5
	global_store_dwordx2 v[14:15], v[4:5], off offset:224
	s_cbranch_scc1 .LBB0_1175

; #define M4_STAGE_LD(step) _Pragma("unroll") for (int k = 0; k < 8; ++k) sr[k] = *(const v4u*)(sbase + (size_t)(step) * 32768 + (size_t)k * 4096)
;     ...
;     for (int s = 0; s < 8; ++s) { const int sp = (s + s0) & 7, spn = (s + 1 + s0) & 7;
;         if (s == 0 || (sp & 3) == 0) {
; #pragma unroll
;             for (int ks = 0; ks < 4; ++ks) cf[ks] = *(const bf16x8*)(pSC + m * 256 + (sp >> 2) * 128 + 32 * ks + 8 * g); }
;         if (s < 7) { M4_STAGE_LD(spn); }
.LBB0_1180:
	s_add_i32 s10, s0, s1
	s_add_i32 s11, s10, -1
	s_and_b32 s14, s11, 7
	s_and_b32 s11, s11, 3
	s_mov_b32 s101, s11
	s_cmp_eq_u32 s1, 1
	s_cselect_b32 s101, 0, s101
	s_cmp_lg_u32 s11, 0
	s_cbranch_scc1 .LBB0_1182
	s_lshl_b32 s92, s14, 6
	v_lshl_add_u64 v[16:17], v[162:163], 0, s[92:93]
	global_load_dwordx4 v[4:7], v[16:17], off
	global_load_dwordx4 v[8:11], v[16:17], off offset:64
	global_load_dwordx4 v[12:15], v[16:17], off offset:128
	s_nop 0
	global_load_dwordx4 v[16:19], v[16:17], off offset:192

; #define M4_STAGE_LD(step) _Pragma("unroll") for (int k = 0; k < 8; ++k) sr[k] = *(const v4u*)(sbase + (size_t)(step) * 32768 + (size_t)k * 4096)
;     ...
;             for (int ks = 0; ks < 4; ++ks) cf[ks] = *(const bf16x8*)(pSC + m * 256 + (sp >> 2) * 128 + 32 * ks + 8 * g); }
;         if (s < 7) { M4_STAGE_LD(spn); }
;         ldsp T = F.lds + (s & 1) * HB;
;         f32x4 acc[2][2][4];
; #pragma unroll
;         for (int j = 0; j < 2; ++j)
; #pragma unroll
;             for (int dir = 0; dir < 2; ++dir) { zero_acc(acc[j][dir]); if (flags & 1) mma_xt<4>(acc[j][dir], T + (2 * j + dir) * (64 * TSR), TSR, cf, lane); }
.LBB0_1184:
	s_and_b32 s13, 1, s1
	s_cselect_b32 s15, 0, 0x11000
	s_add_i32 s15, s15, 0
	v_add3_u32 v2, s15, v191, v192
	ds_read_b128 v[100:103], v2
	ds_read_b128 v[104:107], v2 offset:4352
	ds_read_b128 v[108:111], v2 offset:8704
	ds_read_b128 v[112:115], v2 offset:13056
	v_add3_u32 v174, s15, v192, v191
	ds_read_b128 v[116:119], v174 offset:64
	ds_read_b128 v[120:123], v174 offset:4416
	ds_read_b128 v[124:127], v174 offset:8768
	ds_read_b128 v[128:131], v174 offset:13120
	s_cmp_lg_u32 s101, 0
	s_cbranch_scc1 .Lm4w_nocf
	s_cmp_eq_u32 s1, 8
	s_cbranch_scc1 .Lm4w_cf_nostage
	s_waitcnt vmcnt(8)
	s_branch .Lm4w_nocf

; #define MFMA16(a, b, c) __builtin_amdgcn_mfma_f32_16x16x32_bf16(a, b, c, 0, 0, 0)
; #define SCHED_FENCE() __builtin_amdgcn_sched_barrier(0)
; template <int MT> __device__ __forceinline__ void mma_xt(f32x4 (&acc)[MT], ldsp t, int ts, const bf16x8 (&own)[4], int lane) {
;     bf16x8 a[MT];
; #pragma unroll
;     for (int mt = 0; mt < MT; ++mt) a[mt] = row_frag(t, ts, 16 * mt, 0, lane);
; #pragma unroll
;     for (int ks = 0; ks < 4; ++ks) { bf16x8 an[MT];
;         if (ks < 3) {
; #pragma unroll
;             for (int mt = 0; mt < MT; ++mt) an[mt] = row_frag(t, ts, 16 * mt, ks + 1, lane); }
; #pragma unroll
;         for (int mt = 0; mt < MT; ++mt) acc[mt] = MFMA16(a[mt], own[ks], acc[mt]);
;         SCHED_FENCE();
;         if (ks < 3) {
; #pragma unroll
;             for (int mt = 0; mt < MT; ++mt) a[mt] = an[mt]; }
;     }
; }
;     ...
;         ldsp T = F.lds + (s & 1) * HB;
;         f32x4 acc[2][2][4];
; #pragma unroll
;         for (int j = 0; j < 2; ++j)
; #pragma unroll
;             for (int dir = 0; dir < 2; ++dir) { zero_acc(acc[j][dir]); if (flags & 1) mma_xt<4>(acc[j][dir], T + (2 * j + dir) * (64 * TSR), TSR, cf, lane); }
.Lm4w_nocf:
	s_waitcnt lgkmcnt(7)
	v_mfma_f32_16x16x32_bf16 v[100:103], v[100:103], v[4:7], 0
	s_waitcnt lgkmcnt(5)
	v_mfma_f32_16x16x32_bf16 v[108:111], v[108:111], v[4:7], 0
	v_mfma_f32_16x16x32_bf16 v[104:107], v[104:107], v[4:7], 0
	s_waitcnt lgkmcnt(4)
	v_mfma_f32_16x16x32_bf16 v[112:115], v[112:115], v[4:7], 0
	s_waitcnt lgkmcnt(3)
	v_mfma_f32_16x16x32_bf16 v[100:103], v[116:119], v[8:11], v[100:103]
	s_waitcnt lgkmcnt(2)
	v_mfma_f32_16x16x32_bf16 v[104:107], v[120:123], v[8:11], v[104:107]
	s_waitcnt lgkmcnt(1)
	v_mfma_f32_16x16x32_bf16 v[108:111], v[124:127], v[8:11], v[108:111]
	ds_read_b128 v[116:119], v174 offset:128
	ds_read_b128 v[120:123], v174 offset:4480
	ds_read_b128 v[124:127], v174 offset:8832
	ds_read_b128 v[132:135], v174 offset:13184
	s_waitcnt lgkmcnt(4)
	v_mfma_f32_16x16x32_bf16 v[112:115], v[128:131], v[8:11], v[112:115]
	s_waitcnt lgkmcnt(3)
	v_mfma_f32_16x16x32_bf16 v[100:103], v[116:119], v[12:15], v[100:103]
	s_waitcnt lgkmcnt(2)
	v_mfma_f32_16x16x32_bf16 v[104:107], v[120:123], v[12:15], v[104:107]
	s_waitcnt lgkmcnt(1)
	v_mfma_f32_16x16x32_bf16 v[108:111], v[124:127], v[12:15], v[108:111]
	ds_read_b128 v[116:119], v174 offset:192
	ds_read_b128 v[120:123], v174 offset:4544
	ds_read_b128 v[124:127], v174 offset:8896
	ds_read_b128 v[128:131], v174 offset:13248
	s_waitcnt lgkmcnt(4)
	v_mfma_f32_16x16x32_bf16 v[112:115], v[132:135], v[12:15], v[112:115]
	s_waitcnt lgkmcnt(3)
	v_mfma_f32_16x16x32_bf16 v[194:197], v[116:119], v[16:19], v[100:103]
	s_waitcnt lgkmcnt(2)
	v_mfma_f32_16x16x32_bf16 v[198:201], v[120:123], v[16:19], v[104:107]
	s_waitcnt lgkmcnt(1)
	v_mfma_f32_16x16x32_bf16 v[140:143], v[124:127], v[16:19], v[108:111]
	s_waitcnt lgkmcnt(0)
	v_mfma_f32_16x16x32_bf16 v[124:127], v[128:131], v[16:19], v[112:115]
	ds_read_b128 v[100:103], v2 offset:17408
	ds_read_b128 v[104:107], v2 offset:21760
	ds_read_b128 v[108:111], v2 offset:26112
	ds_read_b128 v[112:115], v2 offset:30464
	ds_read_b128 v[116:119], v174 offset:17472
	ds_read_b128 v[120:123], v174 offset:21824
	ds_read_b128 v[128:131], v174 offset:26176
	ds_read_b128 v[132:135], v174 offset:30528
	s_waitcnt lgkmcnt(7)
	v_mfma_f32_16x16x32_bf16 v[100:103], v[100:103], v[4:7], 0
	s_waitcnt lgkmcnt(6)
	v_mfma_f32_16x16x32_bf16 v[104:107], v[104:107], v[4:7], 0
	s_waitcnt lgkmcnt(5)
	v_mfma_f32_16x16x32_bf16 v[108:111], v[108:111], v[4:7], 0
	s_waitcnt lgkmcnt(4)
	v_mfma_f32_16x16x32_bf16 v[112:115], v[112:115], v[4:7], 0
	s_waitcnt lgkmcnt(3)
	v_mfma_f32_16x16x32_bf16 v[100:103], v[116:119], v[8:11], v[100:103]
	s_waitcnt lgkmcnt(2)
	v_mfma_f32_16x16x32_bf16 v[104:107], v[120:123], v[8:11], v[104:107]
	s_waitcnt lgkmcnt(1)
	v_mfma_f32_16x16x32_bf16 v[108:111], v[128:131], v[8:11], v[108:111]
	ds_read_b128 v[116:119], v174 offset:17536
	ds_read_b128 v[120:123], v174 offset:21888
	ds_read_b128 v[128:131], v174 offset:26240
	ds_read_b128 v[136:139], v174 offset:30592
	s_waitcnt lgkmcnt(4)
	v_mfma_f32_16x16x32_bf16 v[112:115], v[132:135], v[8:11], v[112:115]
	s_waitcnt lgkmcnt(3)
	v_mfma_f32_16x16x32_bf16 v[100:103], v[116:119], v[12:15], v[100:103]
	s_waitcnt lgkmcnt(2)
	v_mfma_f32_16x16x32_bf16 v[104:107], v[120:123], v[12:15], v[104:107]
	s_waitcnt lgkmcnt(1)
	v_mfma_f32_16x16x32_bf16 v[108:111], v[128:131], v[12:15], v[108:111]
	ds_read_b128 v[116:119], v174 offset:17600
	ds_read_b128 v[120:123], v174 offset:21952
	ds_read_b128 v[128:131], v174 offset:26304
	ds_read_b128 v[132:135], v174 offset:30656
	s_waitcnt lgkmcnt(4)
	v_mfma_f32_16x16x32_bf16 v[112:115], v[136:139], v[12:15], v[112:115]
	s_waitcnt lgkmcnt(0)
	v_mfma_f32_16x16x32_bf16 v[132:135], v[132:135], v[16:19], v[112:115]
	v_mfma_f32_16x16x32_bf16 v[202:205], v[116:119], v[16:19], v[100:103]
	v_mfma_f32_16x16x32_bf16 v[206:209], v[120:123], v[16:19], v[104:107]
	v_mfma_f32_16x16x32_bf16 v[144:147], v[128:131], v[16:19], v[108:111]
	s_nop 0
	ds_read_b128 v[100:103], v2 offset:34816
	ds_read_b128 v[104:107], v2 offset:39168
	ds_read_b128 v[108:111], v2 offset:43520
	ds_read_b128 v[112:115], v2 offset:47872
	ds_read_b128 v[116:119], v174 offset:34880
	ds_read_b128 v[120:123], v174 offset:39232
	ds_read_b128 v[128:131], v174 offset:43584
	ds_read_b128 v[136:139], v174 offset:47936
	s_waitcnt lgkmcnt(7)
; #define MFMA16(a, b, c) __builtin_amdgcn_mfma_f32_16x16x32_bf16(a, b, c, 0, 0, 0)
; #define SCHED_FENCE() __builtin_amdgcn_sched_barrier(0)
; template <int MT> __device__ __forceinline__ void mma_xt(f32x4 (&acc)[MT], ldsp t, int ts, const bf16x8 (&own)[4], int lane) {
;     bf16x8 a[MT];
; #pragma unroll
;     for (int mt = 0; mt < MT; ++mt) a[mt] = row_frag(t, ts, 16 * mt, 0, lane);
; #pragma unroll
;     for (int ks = 0; ks < 4; ++ks) { bf16x8 an[MT];
;         if (ks < 3) {
; #pragma unroll
;             for (int mt = 0; mt < MT; ++mt) an[mt] = row_frag(t, ts, 16 * mt, ks + 1, lane); }
; #pragma unroll
;         for (int mt = 0; mt < MT; ++mt) acc[mt] = MFMA16(a[mt], own[ks], acc[mt]);
;         SCHED_FENCE();
;         if (ks < 3) {
; #pragma unroll
;             for (int mt = 0; mt < MT; ++mt) a[mt] = an[mt]; }
;     }
; }
;     ...
;         ldsp T = F.lds + (s & 1) * HB;
;         f32x4 acc[2][2][4];
; #pragma unroll
;         for (int j = 0; j < 2; ++j)
; #pragma unroll
;             for (int dir = 0; dir < 2; ++dir) { zero_acc(acc[j][dir]); if (flags & 1) mma_xt<4>(acc[j][dir], T + (2 * j + dir) * (64 * TSR), TSR, cf, lane); }
	v_mfma_f32_16x16x32_bf16 v[100:103], v[100:103], v[4:7], 0
	s_waitcnt lgkmcnt(6)
	v_mfma_f32_16x16x32_bf16 v[104:107], v[104:107], v[4:7], 0
	s_waitcnt lgkmcnt(5)
	v_mfma_f32_16x16x32_bf16 v[108:111], v[108:111], v[4:7], 0
	s_waitcnt lgkmcnt(4)
	v_mfma_f32_16x16x32_bf16 v[112:115], v[112:115], v[4:7], 0
	s_waitcnt lgkmcnt(3)
	v_mfma_f32_16x16x32_bf16 v[100:103], v[116:119], v[8:11], v[100:103]
	s_waitcnt lgkmcnt(2)
	v_mfma_f32_16x16x32_bf16 v[104:107], v[120:123], v[8:11], v[104:107]
	s_waitcnt lgkmcnt(1)
	v_mfma_f32_16x16x32_bf16 v[108:111], v[128:131], v[8:11], v[108:111]
	ds_read_b128 v[116:119], v174 offset:34944
	ds_read_b128 v[120:123], v174 offset:39296
	ds_read_b128 v[128:131], v174 offset:43648
	ds_read_b128 v[210:213], v174 offset:48000
	s_waitcnt lgkmcnt(4)
	v_mfma_f32_16x16x32_bf16 v[112:115], v[136:139], v[8:11], v[112:115]
	s_waitcnt lgkmcnt(3)
	v_mfma_f32_16x16x32_bf16 v[100:103], v[116:119], v[12:15], v[100:103]
	s_waitcnt lgkmcnt(2)
	v_mfma_f32_16x16x32_bf16 v[104:107], v[120:123], v[12:15], v[104:107]
	ds_read_b128 v[116:119], v174 offset:35008
	ds_read_b128 v[120:123], v174 offset:39360
	ds_read_b128 v[136:139], v174 offset:43712
	ds_read_b128 v[226:229], v174 offset:48064
	s_waitcnt lgkmcnt(5)
	v_mfma_f32_16x16x32_bf16 v[108:111], v[128:131], v[12:15], v[108:111]
	s_waitcnt lgkmcnt(4)
	v_mfma_f32_16x16x32_bf16 v[112:115], v[210:213], v[12:15], v[112:115]
	s_waitcnt lgkmcnt(3)
	v_mfma_f32_16x16x32_bf16 v[128:131], v[116:119], v[16:19], v[100:103]
	s_waitcnt lgkmcnt(2)
	v_mfma_f32_16x16x32_bf16 v[116:119], v[120:123], v[16:19], v[104:107]
	s_waitcnt lgkmcnt(1)
	v_mfma_f32_16x16x32_bf16 v[108:111], v[136:139], v[16:19], v[108:111]
	s_waitcnt lgkmcnt(0)
	v_mfma_f32_16x16x32_bf16 v[100:103], v[226:229], v[16:19], v[112:115]
	ds_read_b128 v[104:107], v2 offset:52224
	s_nop 1
	ds_read_b128 v[112:115], v2 offset:56576
	ds_read_b128 v[120:123], v2 offset:60928
	ds_read_b128 v[136:139], v2 offset:65280
	ds_read_b128 v[210:213], v174 offset:52288
	ds_read_b128 v[226:229], v174 offset:56640
	ds_read_b128 v[230:233], v174 offset:60992
	ds_read_b128 v[234:237], v174 offset:65344
	s_waitcnt lgkmcnt(7)
	v_mfma_f32_16x16x32_bf16 v[104:107], v[104:107], v[4:7], 0
	s_waitcnt lgkmcnt(6)
	v_mfma_f32_16x16x32_bf16 v[112:115], v[112:115], v[4:7], 0
	s_waitcnt lgkmcnt(5)
	v_mfma_f32_16x16x32_bf16 v[120:123], v[120:123], v[4:7], 0
	s_waitcnt lgkmcnt(4)
	v_mfma_f32_16x16x32_bf16 v[136:139], v[136:139], v[4:7], 0
	s_waitcnt lgkmcnt(3)
	v_mfma_f32_16x16x32_bf16 v[104:107], v[210:213], v[8:11], v[104:107]
	s_waitcnt lgkmcnt(2)
	v_mfma_f32_16x16x32_bf16 v[112:115], v[226:229], v[8:11], v[112:115]
	s_waitcnt lgkmcnt(1)
	v_mfma_f32_16x16x32_bf16 v[120:123], v[230:233], v[8:11], v[120:123]
	ds_read_b128 v[210:213], v174 offset:52352
	ds_read_b128 v[226:229], v174 offset:56704
	ds_read_b128 v[230:233], v174 offset:61056
	ds_read_b128 v[238:241], v174 offset:65408
	s_waitcnt lgkmcnt(4)
	v_mfma_f32_16x16x32_bf16 v[136:139], v[234:237], v[8:11], v[136:139]
	s_waitcnt lgkmcnt(3)
	v_mfma_f32_16x16x32_bf16 v[104:107], v[210:213], v[12:15], v[104:107]
	s_waitcnt lgkmcnt(2)
	v_mfma_f32_16x16x32_bf16 v[112:115], v[226:229], v[12:15], v[112:115]
	s_waitcnt lgkmcnt(1)
	v_mfma_f32_16x16x32_bf16 v[210:213], v[230:233], v[12:15], v[120:123]
	s_nop 2
	ds_read_b128 v[120:123], v174 offset:52416
	ds_read_b128 v[226:229], v174 offset:56768
	ds_read_b128 v[230:233], v174 offset:61120
	ds_read_b128 v[234:237], v174 offset:65472
	s_waitcnt lgkmcnt(4)
	v_mfma_f32_16x16x32_bf16 v[238:241], v[238:241], v[12:15], v[136:139]
	s_waitcnt lgkmcnt(3)
	v_mfma_f32_16x16x32_bf16 v[136:139], v[120:123], v[16:19], v[104:107]
	s_waitcnt lgkmcnt(2)
	v_mfma_f32_16x16x32_bf16 v[120:123], v[226:229], v[16:19], v[112:115]
	s_waitcnt lgkmcnt(1)
	v_mfma_f32_16x16x32_bf16 v[112:115], v[230:233], v[16:19], v[210:213]
	s_waitcnt lgkmcnt(0)
	v_mfma_f32_16x16x32_bf16 v[104:107], v[234:237], v[16:19], v[238:241]
	s_nop 0
	s_cmp_eq_u32 s1, 8
	s_cbranch_scc1 .Lm4w_epi_nostage
	s_waitcnt vmcnt(8)
	s_branch .Lm4w_epi_go

; __device__ __forceinline__ unsigned pk2(float lo, float hi) { return cvtpk(lo, hi); }
; __device__ __forceinline__ float silu(float x) { return x * __builtin_amdgcn_rcpf(1.0f + __builtin_amdgcn_exp2f(x * -1.44269504089f)); }
;     ...
;         for (int j = 0; j < 2; ++j) { const float ef = __builtin_amdgcn_exp2f(cfq[j]), eb = __builtin_amdgcn_exp2f(cbq[j]), dsk = dq[j];
; #pragma unroll
;             for (int mt = 0; mt < 4; ++mt) { const int c = (2 * sp + j) * 64 + M4_COL(mt);
;                 const unsigned x0 = (unsigned)xq[j][mt], x1 = (unsigned)(xq[j][mt] >> 32), z0 = (unsigned)zq[j][mt], z1 = (unsigned)(zq[j][mt] >> 32), y0 = (unsigned)yq[j][mt], y1 = (unsigned)(yq[j][mt] >> 32);
;                 f32x4 y = (f32x4){bflo(y0), bfhi(y0), bflo(y1), bfhi(y1)} + acc[j][0][mt] * ef + acc[j][1][mt] * eb;
;                 y[0] = (y[0] + dsk * bflo(x0)) * silu(bflo(z0)); y[1] = (y[1] + dsk * bfhi(x0)) * silu(bfhi(z0)); y[2] = (y[2] + dsk * bflo(x1)) * silu(bflo(z1)); y[3] = (y[3] + dsk * bfhi(x1)) * silu(bfhi(z1));
;                 ssq += (y[0] * y[0] + y[1] * y[1]) + (y[2] * y[2] + y[3] * y[3]);
;                 *(u64*)(pA + m * D + 1024 + c) = (u64)pk2(y[0], y[1]) | ((u64)pk2(y[2], y[3]) << 32); } }
.Lm4w_epi_go:
	v_exp_f32_e32 v210, v164
	v_lshlrev_b32_e32 v174, 16, v52
	v_and_b32_e32 v175, 0xffff0000, v52
	v_exp_f32_e32 v212, v166
	v_pk_fma_f32 v[174:175], v[210:211], v[194:195], v[174:175] op_sel_hi:[0,1,1]
	v_lshlrev_b32_e32 v194, 16, v68
	v_mul_f32_e32 v195, 0xbfb8aa3b, v194
	v_exp_f32_e32 v195, v195
	v_pk_fma_f32 v[174:175], v[212:213], v[202:203], v[174:175] op_sel_hi:[0,1,1]
	v_lshlrev_b32_e32 v202, 16, v60
	v_fma_f32 v174, v172, v202, v174
	v_and_b32_e32 v202, 0xffff0000, v68
	v_add_f32_e32 v195, 1.0, v195
	v_mul_f32_e32 v203, 0xbfb8aa3b, v202
	v_rcp_f32_e32 v195, v195
	v_exp_f32_e32 v203, v203
	v_lshlrev_b32_e32 v220, 16, v53
	v_and_b32_e32 v221, 0xffff0000, v53
	v_mul_f32_e32 v194, v195, v194
	v_add_f32_e32 v195, 1.0, v203
	v_rcp_f32_e32 v195, v195
	v_pk_fma_f32 v[196:197], v[210:211], v[196:197], v[220:221] op_sel_hi:[0,1,1]
	v_mul_f32_e32 v194, v194, v174
	v_and_b32_e32 v174, 0xffff0000, v60
	v_lshlrev_b32_e32 v203, 16, v69
	v_pk_fma_f32 v[196:197], v[212:213], v[204:205], v[196:197] op_sel_hi:[0,1,1]
	v_mul_f32_e32 v204, 0xbfb8aa3b, v203
	v_fmac_f32_e32 v175, v172, v174
	v_mul_f32_e32 v174, v195, v202
	v_exp_f32_e32 v204, v204
	v_mul_f32_e32 v195, v174, v175
	v_and_b32_e32 v175, 0xffff0000, v69
	v_mul_f32_e32 v202, 0xbfb8aa3b, v175
	v_exp_f32_e32 v202, v202
	v_add_f32_e32 v174, 1.0, v204
	v_rcp_f32_e32 v174, v174
	v_lshlrev_b32_e32 v204, 16, v61
	v_add_f32_e32 v202, 1.0, v202
	v_rcp_f32_e32 v202, v202
	s_lshl_b32 s14, s14, 7
	v_fma_f32 v196, v172, v204, v196
	v_mul_f32_e32 v174, v174, v203
	v_or_b32_e32 v2, s14, v148
	v_mul_f32_e32 v196, v174, v196
	v_and_b32_e32 v174, 0xffff0000, v61
	v_fmac_f32_e32 v197, v172, v174
	v_mul_f32_e32 v174, v202, v175
	v_lshlrev_b32_e32 v2, 1, v2
	v_mul_f32_e32 v197, v174, v197
	v_lshl_add_u64 v[174:175], v[160:161], 0, v[2:3]
	v_lshlrev_b32_e32 v204, 16, v54
	v_and_b32_e32 v205, 0xffff0000, v54
	v_lshlrev_b32_e32 v2, 16, v70
	v_pk_fma_f32 v[198:199], v[210:211], v[198:199], v[204:205] op_sel_hi:[0,1,1]
	v_mul_f32_e32 v204, 0xbfb8aa3b, v2
	v_exp_f32_e32 v204, v204
	v_pk_fma_f32 v[198:199], v[212:213], v[206:207], v[198:199] op_sel_hi:[0,1,1]
	v_lshlrev_b32_e32 v205, 16, v62
	v_fma_f32 v198, v172, v205, v198
	v_and_b32_e32 v205, 0xffff0000, v70
	v_add_f32_e32 v204, 1.0, v204
	v_mul_f32_e32 v206, 0xbfb8aa3b, v205
	v_rcp_f32_e32 v204, v204
	v_exp_f32_e32 v206, v206
	v_lshlrev_b32_e32 v220, 16, v55
	v_and_b32_e32 v221, 0xffff0000, v55
	v_mul_f32_e32 v2, v204, v2
	v_add_f32_e32 v204, 1.0, v206
	v_rcp_f32_e32 v204, v204
	v_lshlrev_b32_e32 v206, 16, v71
	v_mul_f32_e32 v198, v2, v198
	v_and_b32_e32 v2, 0xffff0000, v62
	v_mul_f32_e32 v207, 0xbfb8aa3b, v206
	v_exp_f32_e32 v207, v207
	v_fmac_f32_e32 v199, v172, v2
	v_mul_f32_e32 v2, v204, v205
	v_and_b32_e32 v204, 0xffff0000, v71
	v_mul_f32_e32 v205, 0xbfb8aa3b, v204
	v_exp_f32_e32 v205, v205
	v_mul_f32_e32 v199, v2, v199
	v_add_f32_e32 v2, 1.0, v207
	v_rcp_f32_e32 v2, v2
	v_add_f32_e32 v205, 1.0, v205
	v_pk_fma_f32 v[200:201], v[210:211], v[200:201], v[220:221] op_sel_hi:[0,1,1]
	v_rcp_f32_e32 v205, v205
	v_pk_fma_f32 v[200:201], v[212:213], v[208:209], v[200:201] op_sel_hi:[0,1,1]
	v_lshlrev_b32_e32 v207, 16, v63
	v_fma_f32 v200, v172, v207, v200
	v_mul_f32_e32 v2, v2, v206
	v_mul_f32_e32 v200, v2, v200
	v_and_b32_e32 v2, 0xffff0000, v63
	v_fmac_f32_e32 v201, v172, v2
	v_mul_f32_e32 v2, v205, v204
	v_mul_f32_e32 v201, v2, v201
	v_cvt_pk_bf16_f32 v204, v198, v199
	v_cvt_pk_bf16_f32 v205, v200, v201
	v_cvt_pk_bf16_f32 v202, v194, v195
	v_cvt_pk_bf16_f32 v203, v196, v197
	global_store_dwordx4 v[174:175], v[202:205], off offset:2048
	v_lshlrev_b32_e32 v2, 16, v72
	s_andn2_b64 vcc, exec, s[10:11]
	v_lshlrev_b32_e32 v204, 16, v57
	v_and_b32_e32 v205, 0xffff0000, v57
	v_pk_fma_f32 v[142:143], v[210:211], v[142:143], v[204:205] op_sel_hi:[0,1,1]
	v_pk_fma_f32 v[142:143], v[212:213], v[146:147], v[142:143] op_sel_hi:[0,1,1]
	v_mul_f32_e32 v146, 0xbfb8aa3b, v2
	v_exp_f32_e32 v146, v146
	v_lshlrev_b32_e32 v202, 16, v56
	v_and_b32_e32 v203, 0xffff0000, v56
	v_pk_fma_f32 v[140:141], v[210:211], v[140:141], v[202:203] op_sel_hi:[0,1,1]
	v_pk_fma_f32 v[140:141], v[212:213], v[144:145], v[140:141] op_sel_hi:[0,1,1]
	v_lshlrev_b32_e32 v144, 16, v64
	v_and_b32_e32 v145, 0xffff0000, v72
	v_fma_f32 v140, v172, v144, v140
	v_add_f32_e32 v144, 1.0, v146
	v_mul_f32_e32 v146, 0xbfb8aa3b, v145
	v_rcp_f32_e32 v144, v144
	v_exp_f32_e32 v146, v146
	v_lshlrev_b32_e32 v202, 16, v59
	v_and_b32_e32 v203, 0xffff0000, v59
	v_mul_f32_e32 v2, v144, v2
	v_add_f32_e32 v144, 1.0, v146
	v_rcp_f32_e32 v144, v144
	v_lshlrev_b32_e32 v146, 16, v73
	v_mul_f32_e32 v140, v2, v140
	v_and_b32_e32 v2, 0xffff0000, v64
	v_mul_f32_e32 v147, 0xbfb8aa3b, v146
	v_exp_f32_e32 v147, v147
	v_fmac_f32_e32 v141, v172, v2
	v_mul_f32_e32 v2, v144, v145
	v_and_b32_e32 v144, 0xffff0000, v73
	v_mul_f32_e32 v145, 0xbfb8aa3b, v144
	v_exp_f32_e32 v145, v145
	v_mul_f32_e32 v141, v2, v141
	v_add_f32_e32 v2, 1.0, v147
	v_rcp_f32_e32 v2, v2
	v_add_f32_e32 v145, 1.0, v145
	v_rcp_f32_e32 v145, v145
	v_lshlrev_b32_e32 v147, 16, v65
	v_fma_f32 v142, v172, v147, v142
	v_mul_f32_e32 v2, v2, v146
	v_mul_f32_e32 v142, v2, v142
	v_and_b32_e32 v2, 0xffff0000, v65
	v_fmac_f32_e32 v143, v172, v2
	v_mul_f32_e32 v2, v145, v144
	v_mul_f32_e32 v143, v2, v143
	v_pk_fma_f32 v[126:127], v[210:211], v[126:127], v[202:203] op_sel_hi:[0,1,1]
	v_lshlrev_b32_e32 v2, 16, v74
	v_lshlrev_b32_e32 v146, 16, v58
	v_and_b32_e32 v147, 0xffff0000, v58
	v_pk_fma_f32 v[134:135], v[212:213], v[134:135], v[126:127] op_sel_hi:[0,1,1]
	v_mul_f32_e32 v126, 0xbfb8aa3b, v2
	v_pk_fma_f32 v[124:125], v[210:211], v[124:125], v[146:147] op_sel_hi:[0,1,1]
; __device__ __forceinline__ unsigned pk2(float lo, float hi) { return cvtpk(lo, hi); }
; __device__ __forceinline__ float silu(float x) { return x * __builtin_amdgcn_rcpf(1.0f + __builtin_amdgcn_exp2f(x * -1.44269504089f)); }
;     ...
;         for (int j = 0; j < 2; ++j) { const float ef = __builtin_amdgcn_exp2f(cfq[j]), eb = __builtin_amdgcn_exp2f(cbq[j]), dsk = dq[j];
; #pragma unroll
;             for (int mt = 0; mt < 4; ++mt) { const int c = (2 * sp + j) * 64 + M4_COL(mt);
;                 const unsigned x0 = (unsigned)xq[j][mt], x1 = (unsigned)(xq[j][mt] >> 32), z0 = (unsigned)zq[j][mt], z1 = (unsigned)(zq[j][mt] >> 32), y0 = (unsigned)yq[j][mt], y1 = (unsigned)(yq[j][mt] >> 32);
;                 f32x4 y = (f32x4){bflo(y0), bfhi(y0), bflo(y1), bfhi(y1)} + acc[j][0][mt] * ef + acc[j][1][mt] * eb;
;                 y[0] = (y[0] + dsk * bflo(x0)) * silu(bflo(z0)); y[1] = (y[1] + dsk * bfhi(x0)) * silu(bfhi(z0)); y[2] = (y[2] + dsk * bflo(x1)) * silu(bflo(z1)); y[3] = (y[3] + dsk * bfhi(x1)) * silu(bfhi(z1));
;                 ssq += (y[0] * y[0] + y[1] * y[1]) + (y[2] * y[2] + y[3] * y[3]);
;                 *(u64*)(pA + m * D + 1024 + c) = (u64)pk2(y[0], y[1]) | ((u64)pk2(y[2], y[3]) << 32); } }
	v_exp_f32_e32 v146, v126
	v_pk_fma_f32 v[126:127], v[212:213], v[132:133], v[124:125] op_sel_hi:[0,1,1]
	v_lshlrev_b32_e32 v124, 16, v66
	v_fma_f32 v124, v172, v124, v126
	v_add_f32_e32 v125, 1.0, v146
	v_and_b32_e32 v126, 0xffff0000, v74
	v_rcp_f32_e32 v125, v125
	v_mul_f32_e32 v132, 0xbfb8aa3b, v126
	v_exp_f32_e32 v132, v132
	v_cvt_pk_bf16_f32 v144, v140, v141
	v_mul_f32_e32 v2, v125, v2
	v_mul_f32_e32 v125, v2, v124
	v_add_f32_e32 v124, 1.0, v132
	v_rcp_f32_e32 v124, v124
	v_lshlrev_b32_e32 v132, 16, v75
	v_mul_f32_e32 v133, 0xbfb8aa3b, v132
	v_exp_f32_e32 v133, v133
	v_and_b32_e32 v2, 0xffff0000, v66
	v_fmac_f32_e32 v127, v172, v2
	v_mul_f32_e32 v2, v124, v126
	v_and_b32_e32 v124, 0xffff0000, v75
	v_mul_f32_e32 v126, v2, v127
	v_mul_f32_e32 v127, 0xbfb8aa3b, v124
	v_add_f32_e32 v2, 1.0, v133
	v_exp_f32_e32 v127, v127
	v_rcp_f32_e32 v2, v2
	v_lshlrev_b32_e32 v133, 16, v67
	v_fma_f32 v133, v172, v133, v134
	v_add_f32_e32 v127, 1.0, v127
	v_mul_f32_e32 v2, v2, v132
	v_rcp_f32_e32 v132, v127
	v_mul_f32_e32 v127, v2, v133
	v_and_b32_e32 v2, 0xffff0000, v67
	v_fmac_f32_e32 v135, v172, v2
	v_mul_f32_e32 v2, v132, v124
	v_exp_f32_e32 v134, v165
	v_mul_f32_e32 v132, v2, v135
	v_exp_f32_e32 v124, v167
	v_lshlrev_b32_e32 v2, 16, v92
	v_cvt_pk_bf16_f32 v145, v142, v143
	v_mul_f32_e32 v133, 0xbfb8aa3b, v2
	v_cvt_pk_bf16_f32 v146, v125, v126
	v_cvt_pk_bf16_f32 v147, v127, v132
	global_store_dwordx4 v[174:175], v[144:147], off offset:2112
	v_exp_f32_e32 v133, v133
	s_nop 0
	v_lshlrev_b32_e32 v144, 16, v76
	v_and_b32_e32 v145, 0xffff0000, v76
	v_lshlrev_b32_e32 v146, 16, v77
	v_and_b32_e32 v147, 0xffff0000, v77
	v_pk_fma_f32 v[128:129], v[134:135], v[128:129], v[144:145] op_sel_hi:[0,1,1]
	v_pk_fma_f32 v[130:131], v[134:135], v[130:131], v[146:147] op_sel_hi:[0,1,1]
	v_pk_fma_f32 v[128:129], v[124:125], v[136:137], v[128:129] op_sel_hi:[0,1,1]
	v_lshlrev_b32_e32 v135, 16, v84
	v_fma_f32 v128, v173, v135, v128
	v_and_b32_e32 v135, 0xffff0000, v92
	v_add_f32_e32 v133, 1.0, v133
	v_mul_f32_e32 v136, 0xbfb8aa3b, v135
	v_rcp_f32_e32 v133, v133
	v_exp_f32_e32 v136, v136
	v_pk_fma_f32 v[130:131], v[124:125], v[138:139], v[130:131] op_sel_hi:[0,1,1]
	v_lshlrev_b32_e32 v138, 16, v79
	v_mul_f32_e32 v2, v133, v2
	v_add_f32_e32 v133, 1.0, v136
	v_rcp_f32_e32 v133, v133
	v_lshlrev_b32_e32 v136, 16, v93
	v_mul_f32_e32 v128, v2, v128
	v_and_b32_e32 v2, 0xffff0000, v84
	v_mul_f32_e32 v137, 0xbfb8aa3b, v136
	v_exp_f32_e32 v137, v137
	v_fmac_f32_e32 v129, v173, v2
	v_mul_f32_e32 v2, v133, v135
	v_and_b32_e32 v133, 0xffff0000, v93
	v_mul_f32_e32 v135, 0xbfb8aa3b, v133
	v_exp_f32_e32 v135, v135
	v_mul_f32_e32 v129, v2, v129
	v_add_f32_e32 v2, 1.0, v137
	v_rcp_f32_e32 v2, v2
	v_add_f32_e32 v135, 1.0, v135
	v_rcp_f32_e32 v135, v135
	v_lshlrev_b32_e32 v137, 16, v85
	v_fma_f32 v130, v173, v137, v130
	v_mul_f32_e32 v2, v2, v136
	v_mul_f32_e32 v130, v2, v130
	v_and_b32_e32 v2, 0xffff0000, v85
	v_fmac_f32_e32 v131, v173, v2
	v_mul_f32_e32 v2, v135, v133
	v_and_b32_e32 v139, 0xffff0000, v79
	v_mul_f32_e32 v131, v2, v131
	v_pk_fma_f32 v[118:119], v[134:135], v[118:119], v[138:139] op_sel_hi:[0,1,1]
	v_lshlrev_b32_e32 v2, 16, v94
	v_pk_fma_f32 v[118:119], v[124:125], v[122:123], v[118:119] op_sel_hi:[0,1,1]
	v_mul_f32_e32 v122, 0xbfb8aa3b, v2
	v_cvt_pk_bf16_f32 v136, v128, v129
	v_cvt_pk_bf16_f32 v137, v130, v131
	v_exp_f32_e32 v122, v122
	global_store_dwordx2 v[174:175], v[136:137], off offset:2176
	v_lshlrev_b32_e32 v136, 16, v78
	v_and_b32_e32 v137, 0xffff0000, v78
	v_pk_fma_f32 v[116:117], v[134:135], v[116:117], v[136:137] op_sel_hi:[0,1,1]
	v_pk_fma_f32 v[116:117], v[124:125], v[120:121], v[116:117] op_sel_hi:[0,1,1]
	v_lshlrev_b32_e32 v120, 16, v86
	v_and_b32_e32 v121, 0xffff0000, v94
	v_fma_f32 v116, v173, v120, v116
	v_add_f32_e32 v120, 1.0, v122
	v_mul_f32_e32 v122, 0xbfb8aa3b, v121
	v_rcp_f32_e32 v120, v120
	v_exp_f32_e32 v122, v122
	v_mul_f32_e32 v2, v120, v2
	v_add_f32_e32 v120, 1.0, v122
	v_rcp_f32_e32 v120, v120
	v_lshlrev_b32_e32 v122, 16, v95
	v_mul_f32_e32 v116, v2, v116
	v_and_b32_e32 v2, 0xffff0000, v86
	v_mul_f32_e32 v123, 0xbfb8aa3b, v122
	v_exp_f32_e32 v123, v123
	v_fmac_f32_e32 v117, v173, v2
	v_mul_f32_e32 v2, v120, v121
	v_and_b32_e32 v120, 0xffff0000, v95
	v_mul_f32_e32 v121, 0xbfb8aa3b, v120
	v_exp_f32_e32 v121, v121
	v_mul_f32_e32 v117, v2, v117
	v_add_f32_e32 v2, 1.0, v123
	v_rcp_f32_e32 v2, v2
	v_add_f32_e32 v121, 1.0, v121
	v_rcp_f32_e32 v121, v121
	v_lshlrev_b32_e32 v123, 16, v87
	v_fma_f32 v118, v173, v123, v118
	v_mul_f32_e32 v2, v2, v122
	v_mul_f32_e32 v118, v2, v118
	v_and_b32_e32 v2, 0xffff0000, v87
	v_fmac_f32_e32 v119, v173, v2
	v_mul_f32_e32 v2, v121, v120
	v_mul_f32_e32 v119, v2, v119
	v_or_b32_e32 v2, s14, v181
	v_lshlrev_b32_e32 v2, 1, v2
	v_lshl_add_u64 v[122:123], v[160:161], 0, v[2:3]
	v_cvt_pk_bf16_f32 v120, v116, v117
	v_cvt_pk_bf16_f32 v121, v118, v119
	global_store_dwordx2 v[122:123], v[120:121], off offset:2176
	v_lshlrev_b32_e32 v122, 16, v81
	v_and_b32_e32 v123, 0xffff0000, v81
	v_pk_fma_f32 v[110:111], v[134:135], v[110:111], v[122:123] op_sel_hi:[0,1,1]
	v_lshlrev_b32_e32 v2, 16, v96
	v_pk_fma_f32 v[110:111], v[124:125], v[114:115], v[110:111] op_sel_hi:[0,1,1]
	v_mul_f32_e32 v114, 0xbfb8aa3b, v2
	v_exp_f32_e32 v114, v114
	v_lshlrev_b32_e32 v120, 16, v80
	v_and_b32_e32 v121, 0xffff0000, v80
	v_pk_fma_f32 v[108:109], v[134:135], v[108:109], v[120:121] op_sel_hi:[0,1,1]
	v_pk_fma_f32 v[108:109], v[124:125], v[112:113], v[108:109] op_sel_hi:[0,1,1]
	v_lshlrev_b32_e32 v112, 16, v88
	v_and_b32_e32 v113, 0xffff0000, v96
; __device__ __forceinline__ unsigned pk2(float lo, float hi) { return cvtpk(lo, hi); }
; __device__ __forceinline__ float silu(float x) { return x * __builtin_amdgcn_rcpf(1.0f + __builtin_amdgcn_exp2f(x * -1.44269504089f)); }
; #define M4_STAGE_ST(buf) _Pragma("unroll") for (int k = 0; k < 8; ++k) { const int c = tid + 512 * k; *(LAS v4u*)(F.lds + (buf) * HB + (c >> 10) * (64 * TSR) + M4_RHO((c >> 4) & 63) * TSR + ((c & 15) << 4)) = sr[k]; }
;     ...
;     u64 yq[2][4], xq[2][4], zq[2][4]; float cfq[2], cbq[2], dq[2];
;     ...
;         for (int j = 0; j < 2; ++j) { const float ef = __builtin_amdgcn_exp2f(cfq[j]), eb = __builtin_amdgcn_exp2f(cbq[j]), dsk = dq[j];
; #pragma unroll
;             for (int mt = 0; mt < 4; ++mt) { const int c = (2 * sp + j) * 64 + M4_COL(mt);
;                 const unsigned x0 = (unsigned)xq[j][mt], x1 = (unsigned)(xq[j][mt] >> 32), z0 = (unsigned)zq[j][mt], z1 = (unsigned)(zq[j][mt] >> 32), y0 = (unsigned)yq[j][mt], y1 = (unsigned)(yq[j][mt] >> 32);
;                 f32x4 y = (f32x4){bflo(y0), bfhi(y0), bflo(y1), bfhi(y1)} + acc[j][0][mt] * ef + acc[j][1][mt] * eb;
;                 y[0] = (y[0] + dsk * bflo(x0)) * silu(bflo(z0)); y[1] = (y[1] + dsk * bfhi(x0)) * silu(bfhi(z0)); y[2] = (y[2] + dsk * bflo(x1)) * silu(bflo(z1)); y[3] = (y[3] + dsk * bfhi(x1)) * silu(bfhi(z1));
;                 ssq += (y[0] * y[0] + y[1] * y[1]) + (y[2] * y[2] + y[3] * y[3]);
;                 *(u64*)(pA + m * D + 1024 + c) = (u64)pk2(y[0], y[1]) | ((u64)pk2(y[2], y[3]) << 32); } }
;         if (s < 7) { M4_EPI_LD(spn); M4_STAGE_ST((s + 1) & 1); }
	v_fma_f32 v108, v173, v112, v108
	v_add_f32_e32 v112, 1.0, v114
	v_mul_f32_e32 v114, 0xbfb8aa3b, v113
	v_rcp_f32_e32 v112, v112
	v_exp_f32_e32 v114, v114
	v_mul_f32_e32 v2, v112, v2
	v_add_f32_e32 v112, 1.0, v114
	v_rcp_f32_e32 v112, v112
	v_lshlrev_b32_e32 v114, 16, v97
	v_mul_f32_e32 v108, v2, v108
	v_and_b32_e32 v2, 0xffff0000, v88
	v_mul_f32_e32 v115, 0xbfb8aa3b, v114
	v_exp_f32_e32 v115, v115
	v_fmac_f32_e32 v109, v173, v2
	v_mul_f32_e32 v2, v112, v113
	v_and_b32_e32 v112, 0xffff0000, v97
	v_mul_f32_e32 v113, 0xbfb8aa3b, v112
	v_exp_f32_e32 v113, v113
	v_mul_f32_e32 v109, v2, v109
	v_add_f32_e32 v2, 1.0, v115
	v_rcp_f32_e32 v2, v2
	v_add_f32_e32 v113, 1.0, v113
	v_rcp_f32_e32 v113, v113
	v_lshlrev_b32_e32 v115, 16, v89
	v_fma_f32 v110, v173, v115, v110
	v_mul_f32_e32 v2, v2, v114
	v_mul_f32_e32 v110, v2, v110
	v_and_b32_e32 v2, 0xffff0000, v89
	v_fmac_f32_e32 v111, v173, v2
	v_mul_f32_e32 v2, v113, v112
	v_mul_f32_e32 v111, v2, v111
	v_or_b32_e32 v2, s14, v149
	v_lshlrev_b32_e32 v2, 1, v2
	v_lshl_add_u64 v[114:115], v[160:161], 0, v[2:3]
	v_cvt_pk_bf16_f32 v112, v108, v109
	v_cvt_pk_bf16_f32 v113, v110, v111
	global_store_dwordx2 v[114:115], v[112:113], off offset:2176
	v_lshlrev_b32_e32 v114, 16, v83
	v_and_b32_e32 v115, 0xffff0000, v83
	v_pk_fma_f32 v[102:103], v[134:135], v[102:103], v[114:115] op_sel_hi:[0,1,1]
	v_lshlrev_b32_e32 v2, 16, v98
	v_pk_fma_f32 v[102:103], v[124:125], v[106:107], v[102:103] op_sel_hi:[0,1,1]
	v_mul_f32_e32 v106, 0xbfb8aa3b, v2
	v_exp_f32_e32 v106, v106
	v_lshlrev_b32_e32 v112, 16, v82
	v_and_b32_e32 v113, 0xffff0000, v82
	v_pk_fma_f32 v[100:101], v[134:135], v[100:101], v[112:113] op_sel_hi:[0,1,1]
	v_pk_fma_f32 v[100:101], v[124:125], v[104:105], v[100:101] op_sel_hi:[0,1,1]
	v_lshlrev_b32_e32 v104, 16, v90
	v_and_b32_e32 v105, 0xffff0000, v98
	v_fma_f32 v100, v173, v104, v100
	v_add_f32_e32 v104, 1.0, v106
	v_mul_f32_e32 v106, 0xbfb8aa3b, v105
	v_rcp_f32_e32 v104, v104
	v_exp_f32_e32 v106, v106
	v_mul_f32_e32 v2, v104, v2
	v_add_f32_e32 v104, 1.0, v106
	v_rcp_f32_e32 v104, v104
	v_lshlrev_b32_e32 v106, 16, v99
	v_mul_f32_e32 v100, v2, v100
	v_and_b32_e32 v2, 0xffff0000, v90
	v_mul_f32_e32 v107, 0xbfb8aa3b, v106
	v_exp_f32_e32 v107, v107
	v_fmac_f32_e32 v101, v173, v2
	v_mul_f32_e32 v2, v104, v105
	v_and_b32_e32 v104, 0xffff0000, v99
	v_mul_f32_e32 v105, 0xbfb8aa3b, v104
	v_exp_f32_e32 v105, v105
	v_mul_f32_e32 v101, v2, v101
	v_add_f32_e32 v2, 1.0, v107
	v_rcp_f32_e32 v2, v2
	v_add_f32_e32 v105, 1.0, v105
	v_rcp_f32_e32 v105, v105
	v_lshlrev_b32_e32 v107, 16, v91
	v_fma_f32 v102, v173, v107, v102
	v_mul_f32_e32 v2, v2, v106
	v_mul_f32_e32 v102, v2, v102
	v_and_b32_e32 v2, 0xffff0000, v91
	v_fmac_f32_e32 v103, v173, v2
	v_mul_f32_e32 v2, v105, v104
	v_mul_f32_e32 v103, v2, v103
	v_or_b32_e32 v2, s14, v182
	v_lshlrev_b32_e32 v2, 1, v2
	v_lshl_add_u64 v[106:107], v[160:161], 0, v[2:3]
	v_cvt_pk_bf16_f32 v104, v100, v101
	v_cvt_pk_bf16_f32 v105, v102, v103
	global_store_dwordx2 v[106:107], v[104:105], off offset:2176
	s_cbranch_vccnz .LBB0_1179
	s_lshl_b32 s10, s12, 7
	v_or_b32_e32 v2, s10, v148
	v_lshlrev_b32_e32 v2, 1, v2
	v_lshl_add_u64 v[56:57], v[152:153], 0, v[2:3]
	v_lshl_add_u64 v[64:65], v[154:155], 0, v[2:3]
	v_lshl_add_u64 v[68:69], v[156:157], 0, v[2:3]
	v_or_b32_e32 v2, s10, v149
	v_lshlrev_b32_e32 v2, 1, v2
	s_or_b32 s10, s10, 64
	v_lshl_add_u64 v[72:73], v[156:157], 0, v[2:3]
	v_lshl_or_b32 v76, s12, 1, v158
	v_mov_b32_e32 v77, v159
	v_or_b32_e32 v2, s10, v148
	v_lshlrev_b64 v[76:77], 2, v[76:77]
	v_lshlrev_b32_e32 v2, 1, v2
	v_lshl_add_u64 v[78:79], s[4:5], 0, v[76:77]
	v_lshl_add_u64 v[76:77], s[6:7], 0, v[76:77]
	v_lshl_add_u64 v[80:81], v[152:153], 0, v[2:3]
	v_lshl_add_u64 v[88:89], v[154:155], 0, v[2:3]
	v_lshl_add_u64 v[92:93], v[156:157], 0, v[2:3]
	v_or_b32_e32 v2, s10, v149
	global_load_dwordx4 v[52:55], v[56:57], off
	s_nop 0
	global_load_dwordx4 v[56:59], v[56:57], off offset:64
	s_nop 0
	global_load_dwordx4 v[60:63], v[64:65], off
	s_nop 0
	global_load_dwordx4 v[64:67], v[64:65], off offset:64
	s_nop 0
	global_load_dwordx4 v[68:71], v[68:69], off
	s_nop 0
	global_load_dwordx4 v[72:75], v[72:73], off
	s_nop 0
	global_load_dwordx2 v[164:165], v[78:79], off
	global_load_dwordx2 v[166:167], v[76:77], off
	s_lshl_b32 s11, s12, 3
	global_load_dwordx4 v[76:79], v[80:81], off
	s_nop 0
	global_load_dwordx4 v[80:83], v[80:81], off offset:64
	s_nop 0
	global_load_dwordx4 v[84:87], v[88:89], off
	s_nop 0
	global_load_dwordx4 v[88:91], v[88:89], off offset:64
	v_lshlrev_b32_e32 v2, 1, v2
	v_lshl_add_u64 v[96:97], v[156:157], 0, v[2:3]
	v_mov_b32_e32 v2, s11
	global_load_dwordx4 v[92:95], v[92:93], off
	s_nop 0
	global_load_dwordx4 v[96:99], v[96:97], off
	s_cmp_eq_u32 s13, 1
	global_load_dwordx2 v[172:173], v2, s[8:9]
	s_cselect_b32 s10, 0x11000, 0
	s_add_i32 s10, s10, 0
	v_add_u32_e32 v2, s10, v183
	v_add3_u32 v2, v2, v176, v168
	s_waitcnt vmcnt(21)
	ds_write_b128 v2, v[20:23]
	v_add_u32_e32 v2, s10, v184
	v_add3_u32 v2, v2, v177, v168
	ds_write_b128 v2, v[24:27]
	v_add_u32_e32 v2, s10, v185
	v_add3_u32 v2, v2, v176, v168
	ds_write_b128 v2, v[28:31]
	v_add_u32_e32 v2, s10, v186
	v_add3_u32 v2, v2, v178, v168
	ds_write_b128 v2, v[32:35]
	v_add_u32_e32 v2, s10, v187
	v_add3_u32 v2, v2, v176, v168
	ds_write_b128 v2, v[36:39]
	v_add_u32_e32 v2, s10, v188
	v_add3_u32 v2, v2, v179, v168
	ds_write_b128 v2, v[40:43]
	v_add_u32_e32 v2, s10, v189
	v_add3_u32 v2, v2, v176, v168
	ds_write_b128 v2, v[44:47]
	v_add_u32_e32 v2, s10, v190
	v_add3_u32 v2, v2, v180, v168
	ds_write_b128 v2, v[48:51]
	s_branch .LBB0_1179

; #define PG8_STAGE(bufoff, gbase, voff) do { _Pragma("unroll") for (int _i = 0; _i < 2; ++_i) \
;         __builtin_amdgcn_global_load_lds((const unsigned*)((const char*)(gbase) + (voff)[_i]), (PG8_LAS unsigned*)(lds + (bufoff) + ldsw + _i * 8192), 16, 0, 0); } while (0)
; #define PG8_LDA(dst, b, h) do { _Pragma("unroll") for (int m = 0; m < 4; ++m) _Pragma("unroll") for (int k = 0; k < 2; ++k) dst[m][k] = *(const PG8_LAS bf16x8*)(lds + PG8_SA(b, h) + aoffk[k] + m * 2048); } while (0)
; #define PG8_LDB(dst, b, h) do { _Pragma("unroll") for (int n = 0; n < 2; ++n) _Pragma("unroll") for (int k = 0; k < 2; ++k) dst[n][k] = *(const PG8_LAS bf16x8*)(lds + PG8_SB(b, h) + boffk[k] + n * 2048); } while (0)
; #define PG8_MMA(ai, bj, At, Bt) do { __builtin_amdgcn_s_setprio(1); _Pragma("unroll") for (int m = 0; m < 4; ++m) _Pragma("unroll") for (int n = 0; n < 2; ++n) _Pragma("unroll") for (int k = 0; k < 2; ++k) \
;         acc[ai][bj][m][n] = __builtin_amdgcn_mfma_f32_16x16x32_bf16(Bt[n][k], At[m][k], acc[ai][bj][m][n], 0, 0, 0); __builtin_amdgcn_s_setprio(0); } while (0)
; #define PG8_WAIT_V(n) asm volatile("s_waitcnt vmcnt(" #n ")" ::: "memory")
; #define PG8_WAIT_L(n) asm volatile("s_waitcnt lgkmcnt(" #n ")" ::: "memory")
; template <class Epi, class Sched, bool ALIGN_EPI = false, bool SP2 = false>
; __device__ __forceinline__ void gemm_phase(PG8_LAS unsigned char* lds, const Gemm g, const Sched& S, const Epi& E) {
;     ...
;         for (int t = 0; t < nt; t += 2) {
;             const bool last = (t == nt - 2);
;             const char* a1 = cA + (size_t)(t + 1) * kstep;
;             const char* a2 = last ? nA : cA + (size_t)(t + 2) * kstep; const char* b2 = last ? nB : cB + (size_t)(t + 2) * kstep;
;             const char* a3 = a2 + kstep; const char* b3 = b2 + kstep;
;             if (last && has_next) S.a_ready(nxt);
;             if constexpr (SP2) {
;             PG8_LDB(B0, 0, 0); PG8_LDB(B1, 0, 1); PG8_SCHED; PG8_LDA(At, 0, 0); PG8_STAGE(PG8_SA(1, 1), a1 + hstepA, voffA);
;             PG8_WAIT_V(8); PG8_WAIT_L(0); PG8_BAR; PG8_MMA(0, 0, At, B0); PG8_MMA(0, 1, At, B1); PG8_BAR; PG8_SCHED;
;             PG8_LDA(At, 0, 1); PG8_STAGE(PG8_SB(0, 0), b2, voffB); PG8_STAGE(PG8_SB(0, 1), b2 + hstepB, voffB); PG8_STAGE(PG8_SA(0, 0), a2, voffA);
;             PG8_WAIT_V(8); PG8_WAIT_L(0); PG8_BAR; PG8_MMA(1, 0, At, B0); PG8_MMA(1, 1, At, B1); PG8_BAR; PG8_SCHED;
.LBB0_1293:
	s_add_i32 s48, s22, 2
	s_add_u32 s23, s20, 0xfff80080
	s_addc_u32 s24, s21, -1
	s_add_i32 s49, 0, 0x10000
	s_cmp_eq_u32 s11, s22
	v_add_u32_e32 v142, s49, v145
	s_cselect_b32 s25, s17, s24
	s_cselect_b32 s24, s16, s23
	v_add_u32_e32 v143, s49, v146
	ds_read_b128 v[150:153], v142
	ds_read_b128 v[154:157], v143
	v_add_u32_e32 v142, s53, v145
	s_cselect_b32 s23, s19, s15
	s_cselect_b32 s22, s18, s13
	s_add_i32 s52, 0, 0x14000
	v_add_u32_e32 v143, s53, v146
	ds_read_b128 v[158:161], v142
	ds_read_b128 v[162:165], v143
	v_add_u32_e32 v142, s52, v145
	v_add_u32_e32 v143, s52, v146
	ds_read_b128 v[172:175], v142
	ds_read_b128 v[176:179], v143
	v_add_u32_e32 v142, s54, v145
	v_add_u32_e32 v143, s54, v146
	ds_read_b128 v[180:183], v142
	ds_read_b128 v[184:187], v143
	v_lshl_add_u64 v[142:143], s[20:21], 0, v[138:139]
	s_add_i32 m0, s5, 0xc000
	ds_read_b128 v[188:191], v148
	ds_read_b128 v[192:195], v148 offset:1024
	ds_read_b128 v[196:199], v148 offset:2048
	ds_read_b128 v[200:203], v148 offset:3072
	ds_read_b128 v[204:207], v148 offset:4096
	ds_read_b128 v[208:211], v148 offset:5120
	ds_read_b128 v[226:229], v148 offset:6144
	ds_read_b128 v[230:233], v148 offset:7168
	global_load_lds_dwordx4 v[142:143], off
	v_lshl_add_u64 v[142:143], s[20:21], 0, v[140:141]
	s_add_i32 m0, s5, 0xe000
	s_nop 0
	global_load_lds_dwordx4 v[142:143], off
	s_nop 0
	s_nop 0
	s_nop 0
	s_nop 0
	s_nop 0
	s_nop 0
	s_nop 0
	s_nop 0
	s_nop 0
	s_waitcnt vmcnt(8)
	s_waitcnt lgkmcnt(0)
	s_barrier
	v_mfma_f32_16x16x32_bf16 v[128:131], v[150:153], v[188:191], v[128:131]
	v_mfma_f32_16x16x32_bf16 v[124:127], v[158:161], v[188:191], v[124:127]
	v_mfma_f32_16x16x32_bf16 v[120:123], v[150:153], v[196:199], v[120:123]
	v_mfma_f32_16x16x32_bf16 v[112:115], v[158:161], v[196:199], v[112:115]
	v_mfma_f32_16x16x32_bf16 v[104:107], v[150:153], v[204:207], v[104:107]
	v_mfma_f32_16x16x32_bf16 v[96:99], v[158:161], v[204:207], v[96:99]
	v_mfma_f32_16x16x32_bf16 v[88:91], v[150:153], v[226:229], v[88:91]
	v_mfma_f32_16x16x32_bf16 v[80:83], v[158:161], v[226:229], v[80:83]
	v_mfma_f32_16x16x32_bf16 v[128:131], v[154:157], v[192:195], v[128:131]
	v_mfma_f32_16x16x32_bf16 v[124:127], v[162:165], v[192:195], v[124:127]
	v_mfma_f32_16x16x32_bf16 v[120:123], v[154:157], v[200:203], v[120:123]
	v_mfma_f32_16x16x32_bf16 v[112:115], v[162:165], v[200:203], v[112:115]
	v_mfma_f32_16x16x32_bf16 v[104:107], v[154:157], v[208:211], v[104:107]
	v_mfma_f32_16x16x32_bf16 v[96:99], v[162:165], v[208:211], v[96:99]
	v_mfma_f32_16x16x32_bf16 v[88:91], v[154:157], v[230:233], v[88:91]
	v_mfma_f32_16x16x32_bf16 v[80:83], v[162:165], v[230:233], v[80:83]
	v_mfma_f32_16x16x32_bf16 v[116:119], v[172:175], v[188:191], v[116:119]
	v_mfma_f32_16x16x32_bf16 v[108:111], v[180:183], v[188:191], v[108:111]
	v_mfma_f32_16x16x32_bf16 v[100:103], v[172:175], v[196:199], v[100:103]
	v_mfma_f32_16x16x32_bf16 v[92:95], v[180:183], v[196:199], v[92:95]
	v_mfma_f32_16x16x32_bf16 v[84:87], v[172:175], v[204:207], v[84:87]
	v_mfma_f32_16x16x32_bf16 v[76:79], v[180:183], v[204:207], v[76:79]
	v_mfma_f32_16x16x32_bf16 v[72:75], v[172:175], v[226:229], v[72:75]
	v_mfma_f32_16x16x32_bf16 v[68:71], v[180:183], v[226:229], v[68:71]
	v_mfma_f32_16x16x32_bf16 v[116:119], v[176:179], v[192:195], v[116:119]
	v_mfma_f32_16x16x32_bf16 v[108:111], v[184:187], v[192:195], v[108:111]
	v_mfma_f32_16x16x32_bf16 v[100:103], v[176:179], v[200:203], v[100:103]
	v_mfma_f32_16x16x32_bf16 v[92:95], v[184:187], v[200:203], v[92:95]
	v_mfma_f32_16x16x32_bf16 v[84:87], v[176:179], v[208:211], v[84:87]
	v_mfma_f32_16x16x32_bf16 v[76:79], v[184:187], v[208:211], v[76:79]
	v_mfma_f32_16x16x32_bf16 v[72:75], v[176:179], v[230:233], v[72:75]
	v_mfma_f32_16x16x32_bf16 v[68:71], v[184:187], v[230:233], v[68:71]
	s_barrier
	s_add_i32 s49, s49, s33
	v_lshl_add_u64 v[142:143], s[22:23], 0, v[2:3]
	s_mov_b32 m0, s49
	ds_read_b128 v[188:191], v148 offset:16384
	ds_read_b128 v[192:195], v148 offset:17408
	ds_read_b128 v[196:199], v148 offset:18432
	ds_read_b128 v[200:203], v148 offset:19456
	ds_read_b128 v[204:207], v148 offset:20480
	ds_read_b128 v[208:211], v148 offset:21504
	ds_read_b128 v[226:229], v148 offset:22528
	ds_read_b128 v[230:233], v148 offset:23552
	global_load_lds_dwordx4 v[142:143], off
	s_add_i32 m0, s49, 0x2000
	s_add_u32 s50, s22, 0x80000
	v_lshl_add_u64 v[166:167], s[22:23], 0, v[136:137]
	s_addc_u32 s51, s23, 0
	s_add_i32 s49, s52, s33
	global_load_lds_dwordx4 v[166:167], off
	v_lshl_add_u64 v[212:213], s[50:51], 0, v[2:3]
	s_mov_b32 m0, s49
	v_lshl_add_u64 v[220:221], s[24:25], 0, v[134:135]
	global_load_lds_dwordx4 v[212:213], off
	v_lshl_add_u64 v[212:213], s[50:51], 0, v[136:137]
	s_add_i32 m0, s49, 0x2000
	s_nop 0
	global_load_lds_dwordx4 v[212:213], off
	v_lshl_add_u64 v[212:213], s[24:25], 0, v[132:133]
	s_mov_b32 m0, s5
	s_nop 0
	global_load_lds_dwordx4 v[212:213], off
	s_mov_b32 m0, s7
	s_nop 0
	global_load_lds_dwordx4 v[220:221], off
	s_nop 0
	s_nop 0
	s_nop 0
	s_nop 0
	s_waitcnt vmcnt(8)
	s_waitcnt lgkmcnt(0)
	s_barrier
; #define PG8_STAGE(bufoff, gbase, voff) do { _Pragma("unroll") for (int _i = 0; _i < 2; ++_i) \
;         __builtin_amdgcn_global_load_lds((const unsigned*)((const char*)(gbase) + (voff)[_i]), (PG8_LAS unsigned*)(lds + (bufoff) + ldsw + _i * 8192), 16, 0, 0); } while (0)
; #define PG8_LDA(dst, b, h) do { _Pragma("unroll") for (int m = 0; m < 4; ++m) _Pragma("unroll") for (int k = 0; k < 2; ++k) dst[m][k] = *(const PG8_LAS bf16x8*)(lds + PG8_SA(b, h) + aoffk[k] + m * 2048); } while (0)
; #define PG8_LDB(dst, b, h) do { _Pragma("unroll") for (int n = 0; n < 2; ++n) _Pragma("unroll") for (int k = 0; k < 2; ++k) dst[n][k] = *(const PG8_LAS bf16x8*)(lds + PG8_SB(b, h) + boffk[k] + n * 2048); } while (0)
; #define PG8_MMA(ai, bj, At, Bt) do { __builtin_amdgcn_s_setprio(1); _Pragma("unroll") for (int m = 0; m < 4; ++m) _Pragma("unroll") for (int n = 0; n < 2; ++n) _Pragma("unroll") for (int k = 0; k < 2; ++k) \
;         acc[ai][bj][m][n] = __builtin_amdgcn_mfma_f32_16x16x32_bf16(Bt[n][k], At[m][k], acc[ai][bj][m][n], 0, 0, 0); __builtin_amdgcn_s_setprio(0); } while (0)
; #define PG8_WAIT_V(n) asm volatile("s_waitcnt vmcnt(" #n ")" ::: "memory")
; #define PG8_WAIT_L(n) asm volatile("s_waitcnt lgkmcnt(" #n ")" ::: "memory")
; #define PG8_BAR __builtin_amdgcn_s_barrier()
; #define PG8_SCHED __builtin_amdgcn_sched_barrier(0)
; template <class Epi, class Sched, bool ALIGN_EPI = false, bool SP2 = false>
; __device__ __forceinline__ void gemm_phase(PG8_LAS unsigned char* lds, const Gemm g, const Sched& S, const Epi& E) {
;     ...
;             PG8_WAIT_V(8); PG8_WAIT_L(0); PG8_BAR; PG8_MMA(1, 0, At, B0); PG8_MMA(1, 1, At, B1); PG8_BAR; PG8_SCHED;
;             PG8_LDB(B0, 1, 0); PG8_LDB(B1, 1, 1); PG8_SCHED; PG8_LDA(At, 1, 0); PG8_STAGE(PG8_SA(0, 1), a2 + hstepA, voffA);
;             PG8_WAIT_V(8); PG8_WAIT_L(0); PG8_BAR; PG8_MMA(0, 0, At, B0); PG8_MMA(0, 1, At, B1); PG8_BAR; PG8_SCHED;
	v_mfma_f32_16x16x32_bf16 v[64:67], v[150:153], v[188:191], v[64:67]
	v_mfma_f32_16x16x32_bf16 v[60:63], v[158:161], v[188:191], v[60:63]
	v_mfma_f32_16x16x32_bf16 v[56:59], v[150:153], v[196:199], v[56:59]
	v_mfma_f32_16x16x32_bf16 v[48:51], v[158:161], v[196:199], v[48:51]
	v_mfma_f32_16x16x32_bf16 v[40:43], v[150:153], v[204:207], v[40:43]
	v_mfma_f32_16x16x32_bf16 v[32:35], v[158:161], v[204:207], v[32:35]
	v_mfma_f32_16x16x32_bf16 v[24:27], v[150:153], v[226:229], v[24:27]
	v_mfma_f32_16x16x32_bf16 v[16:19], v[158:161], v[226:229], v[16:19]
	v_mfma_f32_16x16x32_bf16 v[64:67], v[154:157], v[192:195], v[64:67]
	v_mfma_f32_16x16x32_bf16 v[60:63], v[162:165], v[192:195], v[60:63]
	v_mfma_f32_16x16x32_bf16 v[56:59], v[154:157], v[200:203], v[56:59]
	v_mfma_f32_16x16x32_bf16 v[48:51], v[162:165], v[200:203], v[48:51]
	v_mfma_f32_16x16x32_bf16 v[40:43], v[154:157], v[208:211], v[40:43]
	v_mfma_f32_16x16x32_bf16 v[32:35], v[162:165], v[208:211], v[32:35]
	v_mfma_f32_16x16x32_bf16 v[24:27], v[154:157], v[230:233], v[24:27]
	v_mfma_f32_16x16x32_bf16 v[16:19], v[162:165], v[230:233], v[16:19]
	v_mfma_f32_16x16x32_bf16 v[52:55], v[172:175], v[188:191], v[52:55]
	v_mfma_f32_16x16x32_bf16 v[44:47], v[180:183], v[188:191], v[44:47]
	v_mfma_f32_16x16x32_bf16 v[36:39], v[172:175], v[196:199], v[36:39]
	v_mfma_f32_16x16x32_bf16 v[28:31], v[180:183], v[196:199], v[28:31]
	v_mfma_f32_16x16x32_bf16 v[20:23], v[172:175], v[204:207], v[20:23]
	v_mfma_f32_16x16x32_bf16 v[12:15], v[180:183], v[204:207], v[12:15]
	v_mfma_f32_16x16x32_bf16 v[8:11], v[172:175], v[226:229], v[8:11]
	v_mfma_f32_16x16x32_bf16 v[4:7], v[180:183], v[226:229], v[4:7]
	v_mfma_f32_16x16x32_bf16 v[52:55], v[176:179], v[192:195], v[52:55]
	v_mfma_f32_16x16x32_bf16 v[44:47], v[184:187], v[192:195], v[44:47]
	v_mfma_f32_16x16x32_bf16 v[36:39], v[176:179], v[200:203], v[36:39]
	v_mfma_f32_16x16x32_bf16 v[28:31], v[184:187], v[200:203], v[28:31]
	v_mfma_f32_16x16x32_bf16 v[20:23], v[176:179], v[208:211], v[20:23]
	v_mfma_f32_16x16x32_bf16 v[12:15], v[184:187], v[208:211], v[12:15]
	v_mfma_f32_16x16x32_bf16 v[8:11], v[176:179], v[230:233], v[8:11]
	v_mfma_f32_16x16x32_bf16 v[4:7], v[184:187], v[230:233], v[4:7]
	s_barrier
	s_add_i32 s49, 0, 0x18000
	v_add_u32_e32 v149, s49, v145
	v_add_u32_e32 v154, s49, v146
	ds_read_b128 v[150:153], v149
	ds_read_b128 v[154:157], v154
	v_add_u32_e32 v149, s55, v145
	v_add_u32_e32 v162, s55, v146
	s_add_i32 s50, 0, 0x1c000
	ds_read_b128 v[158:161], v149
	ds_read_b128 v[162:165], v162
	v_add_u32_e32 v149, s50, v145
	v_add_u32_e32 v168, s50, v146
	ds_read_b128 v[172:175], v149
	ds_read_b128 v[176:179], v168
	v_add_u32_e32 v149, s56, v145
	v_add_u32_e32 v168, s56, v146
	ds_read_b128 v[180:183], v149
	ds_read_b128 v[184:187], v168
	s_add_u32 s24, s24, 0x80000
	s_addc_u32 s25, s25, 0
	s_mov_b32 m0, s34
	v_lshl_add_u64 v[234:235], s[24:25], 0, v[132:133]
	ds_read_b128 v[188:191], v148 offset:32768
	ds_read_b128 v[192:195], v148 offset:33792
	ds_read_b128 v[196:199], v148 offset:34816
	ds_read_b128 v[200:203], v148 offset:35840
	ds_read_b128 v[204:207], v148 offset:36864
	ds_read_b128 v[208:211], v148 offset:37888
	ds_read_b128 v[226:229], v148 offset:38912
	ds_read_b128 v[230:233], v148 offset:39936
	global_load_lds_dwordx4 v[234:235], off
	v_lshl_add_u64 v[234:235], s[24:25], 0, v[134:135]
	s_mov_b32 m0, s35
	s_nop 0
	global_load_lds_dwordx4 v[234:235], off
	s_nop 0
	s_nop 0
	s_waitcnt vmcnt(8)
	s_waitcnt lgkmcnt(0)
	s_barrier
	v_mfma_f32_16x16x32_bf16 v[128:131], v[150:153], v[188:191], v[128:131]
	v_mfma_f32_16x16x32_bf16 v[124:127], v[158:161], v[188:191], v[124:127]
	v_mfma_f32_16x16x32_bf16 v[120:123], v[150:153], v[196:199], v[120:123]
	v_mfma_f32_16x16x32_bf16 v[112:115], v[158:161], v[196:199], v[112:115]
	v_mfma_f32_16x16x32_bf16 v[104:107], v[150:153], v[204:207], v[104:107]
	v_mfma_f32_16x16x32_bf16 v[96:99], v[158:161], v[204:207], v[96:99]
	v_mfma_f32_16x16x32_bf16 v[88:91], v[150:153], v[226:229], v[88:91]
	v_mfma_f32_16x16x32_bf16 v[80:83], v[158:161], v[226:229], v[80:83]
	v_mfma_f32_16x16x32_bf16 v[128:131], v[154:157], v[192:195], v[128:131]
	v_mfma_f32_16x16x32_bf16 v[124:127], v[162:165], v[192:195], v[124:127]
	v_mfma_f32_16x16x32_bf16 v[120:123], v[154:157], v[200:203], v[120:123]
	v_mfma_f32_16x16x32_bf16 v[112:115], v[162:165], v[200:203], v[112:115]
	v_mfma_f32_16x16x32_bf16 v[104:107], v[154:157], v[208:211], v[104:107]
	v_mfma_f32_16x16x32_bf16 v[96:99], v[162:165], v[208:211], v[96:99]
	v_mfma_f32_16x16x32_bf16 v[88:91], v[154:157], v[230:233], v[88:91]
	v_mfma_f32_16x16x32_bf16 v[80:83], v[162:165], v[230:233], v[80:83]
	v_mfma_f32_16x16x32_bf16 v[116:119], v[172:175], v[188:191], v[116:119]
	v_mfma_f32_16x16x32_bf16 v[108:111], v[180:183], v[188:191], v[108:111]
	v_mfma_f32_16x16x32_bf16 v[100:103], v[172:175], v[196:199], v[100:103]
	v_mfma_f32_16x16x32_bf16 v[92:95], v[180:183], v[196:199], v[92:95]
	v_mfma_f32_16x16x32_bf16 v[84:87], v[172:175], v[204:207], v[84:87]
	v_mfma_f32_16x16x32_bf16 v[76:79], v[180:183], v[204:207], v[76:79]
	v_mfma_f32_16x16x32_bf16 v[72:75], v[172:175], v[226:229], v[72:75]
	v_mfma_f32_16x16x32_bf16 v[68:71], v[180:183], v[226:229], v[68:71]
	v_mfma_f32_16x16x32_bf16 v[116:119], v[176:179], v[192:195], v[116:119]
	v_mfma_f32_16x16x32_bf16 v[108:111], v[184:187], v[192:195], v[108:111]
	v_mfma_f32_16x16x32_bf16 v[100:103], v[176:179], v[200:203], v[100:103]
	v_mfma_f32_16x16x32_bf16 v[92:95], v[184:187], v[200:203], v[92:95]
	v_mfma_f32_16x16x32_bf16 v[84:87], v[176:179], v[208:211], v[84:87]
	v_mfma_f32_16x16x32_bf16 v[76:79], v[184:187], v[208:211], v[76:79]
	v_mfma_f32_16x16x32_bf16 v[72:75], v[176:179], v[230:233], v[72:75]
	v_mfma_f32_16x16x32_bf16 v[68:71], v[184:187], v[230:233], v[68:71]
	s_barrier
; #define PG8_STAGE(bufoff, gbase, voff) do { _Pragma("unroll") for (int _i = 0; _i < 2; ++_i) \
;         __builtin_amdgcn_global_load_lds((const unsigned*)((const char*)(gbase) + (voff)[_i]), (PG8_LAS unsigned*)(lds + (bufoff) + ldsw + _i * 8192), 16, 0, 0); } while (0)
; #define PG8_LDA(dst, b, h) do { _Pragma("unroll") for (int m = 0; m < 4; ++m) _Pragma("unroll") for (int k = 0; k < 2; ++k) dst[m][k] = *(const PG8_LAS bf16x8*)(lds + PG8_SA(b, h) + aoffk[k] + m * 2048); } while (0)
; #define PG8_MMA(ai, bj, At, Bt) do { __builtin_amdgcn_s_setprio(1); _Pragma("unroll") for (int m = 0; m < 4; ++m) _Pragma("unroll") for (int n = 0; n < 2; ++n) _Pragma("unroll") for (int k = 0; k < 2; ++k) \
;         acc[ai][bj][m][n] = __builtin_amdgcn_mfma_f32_16x16x32_bf16(Bt[n][k], At[m][k], acc[ai][bj][m][n], 0, 0, 0); __builtin_amdgcn_s_setprio(0); } while (0)
; #define PG8_WAIT_V(n) asm volatile("s_waitcnt vmcnt(" #n ")" ::: "memory")
; #define PG8_WAIT_L(n) asm volatile("s_waitcnt lgkmcnt(" #n ")" ::: "memory")
; #define PG8_BAR __builtin_amdgcn_s_barrier()
; #define PG8_SCHED __builtin_amdgcn_sched_barrier(0)
; template <class Epi, class Sched, bool ALIGN_EPI = false, bool SP2 = false>
; __device__ __forceinline__ void gemm_phase(PG8_LAS unsigned char* lds, const Gemm g, const Sched& S, const Epi& E) {
;     ...
;             PG8_LDA(At, 1, 1); PG8_STAGE(PG8_SB(1, 0), b3, voffB); PG8_STAGE(PG8_SB(1, 1), b3 + hstepB, voffB); PG8_STAGE(PG8_SA(1, 0), a3, voffA);
;             PG8_WAIT_V(8); PG8_WAIT_L(0); PG8_BAR; PG8_MMA(1, 0, At, B0); PG8_MMA(1, 1, At, B1); PG8_BAR; PG8_SCHED;
;     ...
;         if constexpr (ALIGN_EPI) { if (wr == 0) PG8_BAR; }
	s_add_i32 s24, s49, s33
	v_lshl_add_u64 v[142:143], v[142:143], 0, s[58:59]
	s_mov_b32 m0, s24
	ds_read_b128 v[188:191], v148 offset:49152
	ds_read_b128 v[192:195], v148 offset:50176
	ds_read_b128 v[196:199], v148 offset:51200
	ds_read_b128 v[200:203], v148 offset:52224
	ds_read_b128 v[204:207], v148 offset:53248
	ds_read_b128 v[208:211], v148 offset:54272
	ds_read_b128 v[226:229], v148 offset:55296
	ds_read_b128 v[230:233], v148 offset:56320
	global_load_lds_dwordx4 v[142:143], off
	s_add_i32 m0, s24, 0x2000
	s_add_u32 s22, s22, 0x80080
	v_lshl_add_u64 v[142:143], v[166:167], 0, s[58:59]
	s_addc_u32 s23, s23, 0
	s_add_i32 s24, s50, s33
	global_load_lds_dwordx4 v[142:143], off
	v_lshl_add_u64 v[142:143], s[22:23], 0, v[2:3]
	s_mov_b32 m0, s24
	s_nop 0
	global_load_lds_dwordx4 v[142:143], off
	v_lshl_add_u64 v[142:143], s[22:23], 0, v[136:137]
	s_add_i32 m0, s24, 0x2000
	s_nop 0
	global_load_lds_dwordx4 v[142:143], off
	v_lshl_add_u64 v[142:143], v[212:213], 0, s[58:59]
	s_mov_b32 m0, s40
	s_nop 0
	global_load_lds_dwordx4 v[142:143], off
	v_lshl_add_u64 v[142:143], v[220:221], 0, s[58:59]
	s_mov_b32 m0, s41
	s_nop 0
	global_load_lds_dwordx4 v[142:143], off
	s_nop 0
	s_nop 0
	s_nop 0
	s_waitcnt vmcnt(8)
	s_waitcnt lgkmcnt(0)
	s_barrier
	v_mfma_f32_16x16x32_bf16 v[64:67], v[150:153], v[188:191], v[64:67]
	v_mfma_f32_16x16x32_bf16 v[60:63], v[158:161], v[188:191], v[60:63]
	v_mfma_f32_16x16x32_bf16 v[56:59], v[150:153], v[196:199], v[56:59]
	v_mfma_f32_16x16x32_bf16 v[48:51], v[158:161], v[196:199], v[48:51]
	v_mfma_f32_16x16x32_bf16 v[40:43], v[150:153], v[204:207], v[40:43]
	v_mfma_f32_16x16x32_bf16 v[32:35], v[158:161], v[204:207], v[32:35]
	v_mfma_f32_16x16x32_bf16 v[24:27], v[150:153], v[226:229], v[24:27]
	v_mfma_f32_16x16x32_bf16 v[16:19], v[158:161], v[226:229], v[16:19]
	v_mfma_f32_16x16x32_bf16 v[64:67], v[154:157], v[192:195], v[64:67]
	v_mfma_f32_16x16x32_bf16 v[60:63], v[162:165], v[192:195], v[60:63]
	v_mfma_f32_16x16x32_bf16 v[56:59], v[154:157], v[200:203], v[56:59]
	v_mfma_f32_16x16x32_bf16 v[48:51], v[162:165], v[200:203], v[48:51]
	v_mfma_f32_16x16x32_bf16 v[40:43], v[154:157], v[208:211], v[40:43]
	v_mfma_f32_16x16x32_bf16 v[32:35], v[162:165], v[208:211], v[32:35]
	v_mfma_f32_16x16x32_bf16 v[24:27], v[154:157], v[230:233], v[24:27]
	v_mfma_f32_16x16x32_bf16 v[16:19], v[162:165], v[230:233], v[16:19]
	v_mfma_f32_16x16x32_bf16 v[52:55], v[172:175], v[188:191], v[52:55]
	v_mfma_f32_16x16x32_bf16 v[44:47], v[180:183], v[188:191], v[44:47]
	v_mfma_f32_16x16x32_bf16 v[36:39], v[172:175], v[196:199], v[36:39]
	v_mfma_f32_16x16x32_bf16 v[28:31], v[180:183], v[196:199], v[28:31]
	v_mfma_f32_16x16x32_bf16 v[20:23], v[172:175], v[204:207], v[20:23]
	v_mfma_f32_16x16x32_bf16 v[12:15], v[180:183], v[204:207], v[12:15]
	v_mfma_f32_16x16x32_bf16 v[8:11], v[172:175], v[226:229], v[8:11]
	v_mfma_f32_16x16x32_bf16 v[4:7], v[180:183], v[226:229], v[4:7]
	v_mfma_f32_16x16x32_bf16 v[52:55], v[176:179], v[192:195], v[52:55]
	v_mfma_f32_16x16x32_bf16 v[44:47], v[184:187], v[192:195], v[44:47]
	v_mfma_f32_16x16x32_bf16 v[36:39], v[176:179], v[200:203], v[36:39]
	v_mfma_f32_16x16x32_bf16 v[28:31], v[184:187], v[200:203], v[28:31]
	v_mfma_f32_16x16x32_bf16 v[20:23], v[176:179], v[208:211], v[20:23]
	v_mfma_f32_16x16x32_bf16 v[12:15], v[184:187], v[208:211], v[12:15]
	v_mfma_f32_16x16x32_bf16 v[8:11], v[176:179], v[230:233], v[8:11]
	v_mfma_f32_16x16x32_bf16 v[4:7], v[184:187], v[230:233], v[4:7]
	s_barrier
	s_add_u32 s20, s20, 0x100
	s_addc_u32 s21, s21, 0
	s_add_u32 s13, s13, 0x100
	s_addc_u32 s15, s15, 0
	s_cmp_ge_i32 s48, s45
	s_mov_b32 s22, s48
	s_cbranch_scc0 .LBB0_1293
	s_and_b64 vcc, exec, s[8:9]
	s_cbranch_vccz .LBB0_1296
	s_barrier

; #define PG8_STAGE(bufoff, gbase, voff) do { _Pragma("unroll") for (int _i = 0; _i < 2; ++_i) \
;         __builtin_amdgcn_global_load_lds((const unsigned*)((const char*)(gbase) + (voff)[_i]), (PG8_LAS unsigned*)(lds + (bufoff) + ldsw + _i * 8192), 16, 0, 0); } while (0)
; #define PG8_LDA(dst, b, h) do { _Pragma("unroll") for (int m = 0; m < 4; ++m) _Pragma("unroll") for (int k = 0; k < 2; ++k) dst[m][k] = *(const PG8_LAS bf16x8*)(lds + PG8_SA(b, h) + aoffk[k] + m * 2048); } while (0)
; #define PG8_LDB(dst, b, h) do { _Pragma("unroll") for (int n = 0; n < 2; ++n) _Pragma("unroll") for (int k = 0; k < 2; ++k) dst[n][k] = *(const PG8_LAS bf16x8*)(lds + PG8_SB(b, h) + boffk[k] + n * 2048); } while (0)
; #define PG8_MMA(ai, bj, At, Bt) do { __builtin_amdgcn_s_setprio(1); _Pragma("unroll") for (int m = 0; m < 4; ++m) _Pragma("unroll") for (int n = 0; n < 2; ++n) _Pragma("unroll") for (int k = 0; k < 2; ++k) \
;         acc[ai][bj][m][n] = __builtin_amdgcn_mfma_f32_16x16x32_bf16(Bt[n][k], At[m][k], acc[ai][bj][m][n], 0, 0, 0); __builtin_amdgcn_s_setprio(0); } while (0)
; #define PG8_WAIT_V(n) asm volatile("s_waitcnt vmcnt(" #n ")" ::: "memory")
; #define PG8_WAIT_L(n) asm volatile("s_waitcnt lgkmcnt(" #n ")" ::: "memory")
; template <class Epi, class Sched, bool ALIGN_EPI = false, bool SP2 = false>
; __device__ __forceinline__ void gemm_phase(PG8_LAS unsigned char* lds, const Gemm g, const Sched& S, const Epi& E) {
;     ...
;         for (int t = 0; t < nt; t += 2) {
;             const bool last = (t == nt - 2);
;             const char* a1 = cA + (size_t)(t + 1) * kstep;
;             const char* a2 = last ? nA : cA + (size_t)(t + 2) * kstep; const char* b2 = last ? nB : cB + (size_t)(t + 2) * kstep;
;             const char* a3 = a2 + kstep; const char* b3 = b2 + kstep;
;             if (last && has_next) S.a_ready(nxt);
;             if constexpr (SP2) {
;             PG8_LDB(B0, 0, 0); PG8_LDB(B1, 0, 1); PG8_SCHED; PG8_LDA(At, 0, 0); PG8_STAGE(PG8_SA(1, 1), a1 + hstepA, voffA);
;             PG8_WAIT_V(8); PG8_WAIT_L(0); PG8_BAR; PG8_MMA(0, 0, At, B0); PG8_MMA(0, 1, At, B1); PG8_BAR; PG8_SCHED;
;             PG8_LDA(At, 0, 1); PG8_STAGE(PG8_SB(0, 0), b2, voffB); PG8_STAGE(PG8_SB(0, 1), b2 + hstepB, voffB); PG8_STAGE(PG8_SA(0, 0), a2, voffA);
;             PG8_WAIT_V(8); PG8_WAIT_L(0); PG8_BAR; PG8_MMA(1, 0, At, B0); PG8_MMA(1, 1, At, B1); PG8_BAR; PG8_SCHED;
.LBB0_1432:
	s_add_u32 s20, s18, 0xfff80080
	s_addc_u32 s21, s19, -1
	s_add_i32 s47, 0, 0x10000
	s_cmp_eq_u32 s46, 28
	v_add_u32_e32 v142, s47, v147
	v_add_u32_e32 v151, s47, v148
	s_cselect_b32 s23, s9, s21
	s_cselect_b32 s22, s33, s20
	ds_read_b128 v[142:145], v142
	ds_read_b128 v[152:155], v151
	v_add_u32_e32 v151, s51, v147
	v_add_u32_e32 v160, s51, v148
	s_cselect_b32 s21, s7, s45
	s_cselect_b32 s20, s43, s44
	s_add_i32 s50, 0, 0x14000
	ds_read_b128 v[156:159], v151
	ds_read_b128 v[160:163], v160
	v_add_u32_e32 v151, s50, v147
	v_add_u32_e32 v168, s50, v148
	ds_read_b128 v[164:167], v151
	ds_read_b128 v[172:175], v168
	v_add_u32_e32 v151, s52, v147
	v_add_u32_e32 v168, s52, v148
	ds_read_b128 v[176:179], v151
	ds_read_b128 v[180:183], v168
	v_lshl_add_u64 v[212:213], s[18:19], 0, v[138:139]
	s_add_i32 m0, s36, 0xc000
	ds_read_b128 v[184:187], v150
	ds_read_b128 v[188:191], v150 offset:1024
	ds_read_b128 v[192:195], v150 offset:2048
	ds_read_b128 v[196:199], v150 offset:3072
	ds_read_b128 v[200:203], v150 offset:4096
	ds_read_b128 v[204:207], v150 offset:5120
	ds_read_b128 v[208:211], v150 offset:6144
	ds_read_b128 v[226:229], v150 offset:7168
	global_load_lds_dwordx4 v[212:213], off
	v_lshl_add_u64 v[212:213], s[18:19], 0, v[140:141]
	s_add_i32 m0, s36, 0xe000
	s_nop 0
	global_load_lds_dwordx4 v[212:213], off
	s_nop 0
	s_nop 0
	s_waitcnt vmcnt(8)
	s_waitcnt lgkmcnt(0)
	s_barrier
	v_mfma_f32_16x16x32_bf16 v[128:131], v[142:145], v[184:187], v[128:131]
	v_mfma_f32_16x16x32_bf16 v[120:123], v[156:159], v[184:187], v[120:123]
	v_mfma_f32_16x16x32_bf16 v[112:115], v[142:145], v[192:195], v[112:115]
	v_mfma_f32_16x16x32_bf16 v[104:107], v[156:159], v[192:195], v[104:107]
	v_mfma_f32_16x16x32_bf16 v[96:99], v[142:145], v[200:203], v[96:99]
	v_mfma_f32_16x16x32_bf16 v[88:91], v[156:159], v[200:203], v[88:91]
	v_mfma_f32_16x16x32_bf16 v[80:83], v[142:145], v[208:211], v[80:83]
	v_mfma_f32_16x16x32_bf16 v[72:75], v[156:159], v[208:211], v[72:75]
	v_mfma_f32_16x16x32_bf16 v[128:131], v[152:155], v[188:191], v[128:131]
	v_mfma_f32_16x16x32_bf16 v[120:123], v[160:163], v[188:191], v[120:123]
	v_mfma_f32_16x16x32_bf16 v[112:115], v[152:155], v[196:199], v[112:115]
	v_mfma_f32_16x16x32_bf16 v[104:107], v[160:163], v[196:199], v[104:107]
	v_mfma_f32_16x16x32_bf16 v[96:99], v[152:155], v[204:207], v[96:99]
	v_mfma_f32_16x16x32_bf16 v[88:91], v[160:163], v[204:207], v[88:91]
	v_mfma_f32_16x16x32_bf16 v[80:83], v[152:155], v[226:229], v[80:83]
	v_mfma_f32_16x16x32_bf16 v[72:75], v[160:163], v[226:229], v[72:75]
	v_mfma_f32_16x16x32_bf16 v[124:127], v[164:167], v[184:187], v[124:127]
	v_mfma_f32_16x16x32_bf16 v[116:119], v[176:179], v[184:187], v[116:119]
	v_mfma_f32_16x16x32_bf16 v[108:111], v[164:167], v[192:195], v[108:111]
	v_mfma_f32_16x16x32_bf16 v[100:103], v[176:179], v[192:195], v[100:103]
	v_mfma_f32_16x16x32_bf16 v[92:95], v[164:167], v[200:203], v[92:95]
	v_mfma_f32_16x16x32_bf16 v[84:87], v[176:179], v[200:203], v[84:87]
	v_mfma_f32_16x16x32_bf16 v[76:79], v[164:167], v[208:211], v[76:79]
	v_mfma_f32_16x16x32_bf16 v[68:71], v[176:179], v[208:211], v[68:71]
	v_mfma_f32_16x16x32_bf16 v[124:127], v[172:175], v[188:191], v[124:127]
	v_mfma_f32_16x16x32_bf16 v[116:119], v[180:183], v[188:191], v[116:119]
	v_mfma_f32_16x16x32_bf16 v[108:111], v[172:175], v[196:199], v[108:111]
	v_mfma_f32_16x16x32_bf16 v[100:103], v[180:183], v[196:199], v[100:103]
	v_mfma_f32_16x16x32_bf16 v[92:95], v[172:175], v[204:207], v[92:95]
	v_mfma_f32_16x16x32_bf16 v[84:87], v[180:183], v[204:207], v[84:87]
	v_mfma_f32_16x16x32_bf16 v[76:79], v[172:175], v[226:229], v[76:79]
	v_mfma_f32_16x16x32_bf16 v[68:71], v[180:183], v[226:229], v[68:71]
	s_barrier
	s_add_i32 s47, s47, s31
	v_lshl_add_u64 v[212:213], s[20:21], 0, v[2:3]
	s_mov_b32 m0, s47
	ds_read_b128 v[184:187], v150 offset:16384
	ds_read_b128 v[188:191], v150 offset:17408
	ds_read_b128 v[192:195], v150 offset:18432
	ds_read_b128 v[196:199], v150 offset:19456
	ds_read_b128 v[200:203], v150 offset:20480
	ds_read_b128 v[204:207], v150 offset:21504
	ds_read_b128 v[208:211], v150 offset:22528
	ds_read_b128 v[226:229], v150 offset:23552
	global_load_lds_dwordx4 v[212:213], off
	s_add_i32 m0, s47, 0x2000
	s_add_u32 s48, s20, 0x80000
	v_lshl_add_u64 v[220:221], s[20:21], 0, v[132:133]
	s_addc_u32 s49, s21, 0
	s_add_i32 s47, s50, s31
	global_load_lds_dwordx4 v[220:221], off
	v_lshl_add_u64 v[230:231], s[48:49], 0, v[2:3]
	s_mov_b32 m0, s47
	v_lshl_add_u64 v[232:233], s[22:23], 0, v[134:135]
	global_load_lds_dwordx4 v[230:231], off
	v_lshl_add_u64 v[230:231], s[48:49], 0, v[132:133]
	s_add_i32 m0, s47, 0x2000
	s_nop 0
	global_load_lds_dwordx4 v[230:231], off
	v_lshl_add_u64 v[230:231], s[22:23], 0, v[136:137]
	s_mov_b32 m0, s36
	s_nop 0
	global_load_lds_dwordx4 v[230:231], off
	s_mov_b32 m0, s37
	s_nop 0
	global_load_lds_dwordx4 v[232:233], off
	s_nop 0
	s_nop 0
	s_nop 0
	s_nop 0
	s_waitcnt vmcnt(8)
	s_waitcnt lgkmcnt(0)
	s_barrier
; #define PG8_STAGE(bufoff, gbase, voff) do { _Pragma("unroll") for (int _i = 0; _i < 2; ++_i) \
;         __builtin_amdgcn_global_load_lds((const unsigned*)((const char*)(gbase) + (voff)[_i]), (PG8_LAS unsigned*)(lds + (bufoff) + ldsw + _i * 8192), 16, 0, 0); } while (0)
; #define PG8_LDA(dst, b, h) do { _Pragma("unroll") for (int m = 0; m < 4; ++m) _Pragma("unroll") for (int k = 0; k < 2; ++k) dst[m][k] = *(const PG8_LAS bf16x8*)(lds + PG8_SA(b, h) + aoffk[k] + m * 2048); } while (0)
; #define PG8_LDB(dst, b, h) do { _Pragma("unroll") for (int n = 0; n < 2; ++n) _Pragma("unroll") for (int k = 0; k < 2; ++k) dst[n][k] = *(const PG8_LAS bf16x8*)(lds + PG8_SB(b, h) + boffk[k] + n * 2048); } while (0)
; #define PG8_MMA(ai, bj, At, Bt) do { __builtin_amdgcn_s_setprio(1); _Pragma("unroll") for (int m = 0; m < 4; ++m) _Pragma("unroll") for (int n = 0; n < 2; ++n) _Pragma("unroll") for (int k = 0; k < 2; ++k) \
;         acc[ai][bj][m][n] = __builtin_amdgcn_mfma_f32_16x16x32_bf16(Bt[n][k], At[m][k], acc[ai][bj][m][n], 0, 0, 0); __builtin_amdgcn_s_setprio(0); } while (0)
; #define PG8_WAIT_V(n) asm volatile("s_waitcnt vmcnt(" #n ")" ::: "memory")
; #define PG8_WAIT_L(n) asm volatile("s_waitcnt lgkmcnt(" #n ")" ::: "memory")
; #define PG8_BAR __builtin_amdgcn_s_barrier()
; #define PG8_SCHED __builtin_amdgcn_sched_barrier(0)
; template <class Epi, class Sched, bool ALIGN_EPI = false, bool SP2 = false>
; __device__ __forceinline__ void gemm_phase(PG8_LAS unsigned char* lds, const Gemm g, const Sched& S, const Epi& E) {
;     ...
;             PG8_WAIT_V(8); PG8_WAIT_L(0); PG8_BAR; PG8_MMA(1, 0, At, B0); PG8_MMA(1, 1, At, B1); PG8_BAR; PG8_SCHED;
;             PG8_LDB(B0, 1, 0); PG8_LDB(B1, 1, 1); PG8_SCHED; PG8_LDA(At, 1, 0); PG8_STAGE(PG8_SA(0, 1), a2 + hstepA, voffA);
;             PG8_WAIT_V(8); PG8_WAIT_L(0); PG8_BAR; PG8_MMA(0, 0, At, B0); PG8_MMA(0, 1, At, B1); PG8_BAR; PG8_SCHED;
	v_mfma_f32_16x16x32_bf16 v[64:67], v[142:145], v[184:187], v[64:67]
	v_mfma_f32_16x16x32_bf16 v[56:59], v[156:159], v[184:187], v[56:59]
	v_mfma_f32_16x16x32_bf16 v[48:51], v[142:145], v[192:195], v[48:51]
	v_mfma_f32_16x16x32_bf16 v[40:43], v[156:159], v[192:195], v[40:43]
	v_mfma_f32_16x16x32_bf16 v[32:35], v[142:145], v[200:203], v[32:35]
	v_mfma_f32_16x16x32_bf16 v[24:27], v[156:159], v[200:203], v[24:27]
	v_mfma_f32_16x16x32_bf16 v[16:19], v[142:145], v[208:211], v[16:19]
	v_mfma_f32_16x16x32_bf16 v[8:11], v[156:159], v[208:211], v[8:11]
	v_mfma_f32_16x16x32_bf16 v[64:67], v[152:155], v[188:191], v[64:67]
	v_mfma_f32_16x16x32_bf16 v[56:59], v[160:163], v[188:191], v[56:59]
	v_mfma_f32_16x16x32_bf16 v[48:51], v[152:155], v[196:199], v[48:51]
	v_mfma_f32_16x16x32_bf16 v[40:43], v[160:163], v[196:199], v[40:43]
	v_mfma_f32_16x16x32_bf16 v[32:35], v[152:155], v[204:207], v[32:35]
	v_mfma_f32_16x16x32_bf16 v[24:27], v[160:163], v[204:207], v[24:27]
	v_mfma_f32_16x16x32_bf16 v[16:19], v[152:155], v[226:229], v[16:19]
	v_mfma_f32_16x16x32_bf16 v[8:11], v[160:163], v[226:229], v[8:11]
	v_mfma_f32_16x16x32_bf16 v[60:63], v[164:167], v[184:187], v[60:63]
	v_mfma_f32_16x16x32_bf16 v[52:55], v[176:179], v[184:187], v[52:55]
	v_mfma_f32_16x16x32_bf16 v[44:47], v[164:167], v[192:195], v[44:47]
	v_mfma_f32_16x16x32_bf16 v[36:39], v[176:179], v[192:195], v[36:39]
	v_mfma_f32_16x16x32_bf16 v[28:31], v[164:167], v[200:203], v[28:31]
	v_mfma_f32_16x16x32_bf16 v[20:23], v[176:179], v[200:203], v[20:23]
	v_mfma_f32_16x16x32_bf16 v[12:15], v[164:167], v[208:211], v[12:15]
	v_mfma_f32_16x16x32_bf16 v[4:7], v[176:179], v[208:211], v[4:7]
	v_mfma_f32_16x16x32_bf16 v[60:63], v[172:175], v[188:191], v[60:63]
	v_mfma_f32_16x16x32_bf16 v[52:55], v[180:183], v[188:191], v[52:55]
	v_mfma_f32_16x16x32_bf16 v[44:47], v[172:175], v[196:199], v[44:47]
	v_mfma_f32_16x16x32_bf16 v[36:39], v[180:183], v[196:199], v[36:39]
	v_mfma_f32_16x16x32_bf16 v[28:31], v[172:175], v[204:207], v[28:31]
	v_mfma_f32_16x16x32_bf16 v[20:23], v[180:183], v[204:207], v[20:23]
	v_mfma_f32_16x16x32_bf16 v[12:15], v[172:175], v[226:229], v[12:15]
	v_mfma_f32_16x16x32_bf16 v[4:7], v[180:183], v[226:229], v[4:7]
	s_barrier
	s_add_i32 s47, 0, 0x18000
	v_add_u32_e32 v142, s47, v147
	v_add_u32_e32 v151, s47, v148
	ds_read_b128 v[142:145], v142
	ds_read_b128 v[152:155], v151
	v_add_u32_e32 v151, s53, v147
	v_add_u32_e32 v160, s53, v148
	s_add_i32 s48, 0, 0x1c000
	ds_read_b128 v[156:159], v151
	ds_read_b128 v[160:163], v160
	v_add_u32_e32 v151, s48, v147
	v_add_u32_e32 v168, s48, v148
	ds_read_b128 v[164:167], v151
	ds_read_b128 v[172:175], v168
	v_add_u32_e32 v151, s54, v147
	v_add_u32_e32 v168, s54, v148
	ds_read_b128 v[176:179], v151
	ds_read_b128 v[180:183], v168
	s_add_u32 s22, s22, 0x80000
	s_addc_u32 s23, s23, 0
	s_mov_b32 m0, s38
	v_lshl_add_u64 v[234:235], s[22:23], 0, v[136:137]
	ds_read_b128 v[184:187], v150 offset:32768
	ds_read_b128 v[188:191], v150 offset:33792
	ds_read_b128 v[192:195], v150 offset:34816
	ds_read_b128 v[196:199], v150 offset:35840
	ds_read_b128 v[200:203], v150 offset:36864
	ds_read_b128 v[204:207], v150 offset:37888
	ds_read_b128 v[208:211], v150 offset:38912
	ds_read_b128 v[226:229], v150 offset:39936
	global_load_lds_dwordx4 v[234:235], off
	v_lshl_add_u64 v[234:235], s[22:23], 0, v[134:135]
	s_mov_b32 m0, s39
	s_nop 0
	global_load_lds_dwordx4 v[234:235], off
	s_nop 0
	s_nop 0
	s_waitcnt vmcnt(8)
	s_waitcnt lgkmcnt(0)
	s_barrier
	v_mfma_f32_16x16x32_bf16 v[128:131], v[142:145], v[184:187], v[128:131]
	v_mfma_f32_16x16x32_bf16 v[120:123], v[156:159], v[184:187], v[120:123]
	v_mfma_f32_16x16x32_bf16 v[112:115], v[142:145], v[192:195], v[112:115]
	v_mfma_f32_16x16x32_bf16 v[104:107], v[156:159], v[192:195], v[104:107]
	v_mfma_f32_16x16x32_bf16 v[96:99], v[142:145], v[200:203], v[96:99]
	v_mfma_f32_16x16x32_bf16 v[88:91], v[156:159], v[200:203], v[88:91]
	v_mfma_f32_16x16x32_bf16 v[80:83], v[142:145], v[208:211], v[80:83]
	v_mfma_f32_16x16x32_bf16 v[72:75], v[156:159], v[208:211], v[72:75]
	v_mfma_f32_16x16x32_bf16 v[128:131], v[152:155], v[188:191], v[128:131]
	v_mfma_f32_16x16x32_bf16 v[120:123], v[160:163], v[188:191], v[120:123]
	v_mfma_f32_16x16x32_bf16 v[112:115], v[152:155], v[196:199], v[112:115]
	v_mfma_f32_16x16x32_bf16 v[104:107], v[160:163], v[196:199], v[104:107]
	v_mfma_f32_16x16x32_bf16 v[96:99], v[152:155], v[204:207], v[96:99]
	v_mfma_f32_16x16x32_bf16 v[88:91], v[160:163], v[204:207], v[88:91]
	v_mfma_f32_16x16x32_bf16 v[80:83], v[152:155], v[226:229], v[80:83]
	v_mfma_f32_16x16x32_bf16 v[72:75], v[160:163], v[226:229], v[72:75]
	v_mfma_f32_16x16x32_bf16 v[124:127], v[164:167], v[184:187], v[124:127]
	v_mfma_f32_16x16x32_bf16 v[116:119], v[176:179], v[184:187], v[116:119]
	v_mfma_f32_16x16x32_bf16 v[108:111], v[164:167], v[192:195], v[108:111]
	v_mfma_f32_16x16x32_bf16 v[100:103], v[176:179], v[192:195], v[100:103]
	v_mfma_f32_16x16x32_bf16 v[92:95], v[164:167], v[200:203], v[92:95]
	v_mfma_f32_16x16x32_bf16 v[84:87], v[176:179], v[200:203], v[84:87]
	v_mfma_f32_16x16x32_bf16 v[76:79], v[164:167], v[208:211], v[76:79]
	v_mfma_f32_16x16x32_bf16 v[68:71], v[176:179], v[208:211], v[68:71]
	v_mfma_f32_16x16x32_bf16 v[124:127], v[172:175], v[188:191], v[124:127]
	v_mfma_f32_16x16x32_bf16 v[116:119], v[180:183], v[188:191], v[116:119]
	v_mfma_f32_16x16x32_bf16 v[108:111], v[172:175], v[196:199], v[108:111]
	v_mfma_f32_16x16x32_bf16 v[100:103], v[180:183], v[196:199], v[100:103]
	v_mfma_f32_16x16x32_bf16 v[92:95], v[172:175], v[204:207], v[92:95]
	v_mfma_f32_16x16x32_bf16 v[84:87], v[180:183], v[204:207], v[84:87]
	v_mfma_f32_16x16x32_bf16 v[76:79], v[172:175], v[226:229], v[76:79]
	v_mfma_f32_16x16x32_bf16 v[68:71], v[180:183], v[226:229], v[68:71]
	s_barrier
; #define PG8_STAGE(bufoff, gbase, voff) do { _Pragma("unroll") for (int _i = 0; _i < 2; ++_i) \
;         __builtin_amdgcn_global_load_lds((const unsigned*)((const char*)(gbase) + (voff)[_i]), (PG8_LAS unsigned*)(lds + (bufoff) + ldsw + _i * 8192), 16, 0, 0); } while (0)
; #define PG8_LDA(dst, b, h) do { _Pragma("unroll") for (int m = 0; m < 4; ++m) _Pragma("unroll") for (int k = 0; k < 2; ++k) dst[m][k] = *(const PG8_LAS bf16x8*)(lds + PG8_SA(b, h) + aoffk[k] + m * 2048); } while (0)
; #define PG8_MMA(ai, bj, At, Bt) do { __builtin_amdgcn_s_setprio(1); _Pragma("unroll") for (int m = 0; m < 4; ++m) _Pragma("unroll") for (int n = 0; n < 2; ++n) _Pragma("unroll") for (int k = 0; k < 2; ++k) \
;         acc[ai][bj][m][n] = __builtin_amdgcn_mfma_f32_16x16x32_bf16(Bt[n][k], At[m][k], acc[ai][bj][m][n], 0, 0, 0); __builtin_amdgcn_s_setprio(0); } while (0)
; #define PG8_WAIT_V(n) asm volatile("s_waitcnt vmcnt(" #n ")" ::: "memory")
; #define PG8_WAIT_L(n) asm volatile("s_waitcnt lgkmcnt(" #n ")" ::: "memory")
; #define PG8_BAR __builtin_amdgcn_s_barrier()
; #define PG8_SCHED __builtin_amdgcn_sched_barrier(0)
; template <class Epi, class Sched, bool ALIGN_EPI = false, bool SP2 = false>
; __device__ __forceinline__ void gemm_phase(PG8_LAS unsigned char* lds, const Gemm g, const Sched& S, const Epi& E) {
;     ...
;             PG8_LDA(At, 1, 1); PG8_STAGE(PG8_SB(1, 0), b3, voffB); PG8_STAGE(PG8_SB(1, 1), b3 + hstepB, voffB); PG8_STAGE(PG8_SA(1, 0), a3, voffA);
;             PG8_WAIT_V(8); PG8_WAIT_L(0); PG8_BAR; PG8_MMA(1, 0, At, B0); PG8_MMA(1, 1, At, B1); PG8_BAR; PG8_SCHED;
;     ...
;         if constexpr (ALIGN_EPI) { if (wr == 0) PG8_BAR; }
	s_add_i32 s22, s47, s31
	v_lshl_add_u64 v[212:213], v[212:213], 0, s[56:57]
	s_mov_b32 m0, s22
	ds_read_b128 v[184:187], v150 offset:49152
	ds_read_b128 v[188:191], v150 offset:50176
	ds_read_b128 v[192:195], v150 offset:51200
	ds_read_b128 v[196:199], v150 offset:52224
	ds_read_b128 v[200:203], v150 offset:53248
	ds_read_b128 v[204:207], v150 offset:54272
	ds_read_b128 v[208:211], v150 offset:55296
	ds_read_b128 v[226:229], v150 offset:56320
	global_load_lds_dwordx4 v[212:213], off
	s_add_i32 m0, s22, 0x2000
	s_add_u32 s20, s20, 0x80080
	v_lshl_add_u64 v[212:213], v[220:221], 0, s[56:57]
	s_addc_u32 s21, s21, 0
	s_add_i32 s22, s48, s31
	global_load_lds_dwordx4 v[212:213], off
	v_lshl_add_u64 v[212:213], s[20:21], 0, v[2:3]
	s_mov_b32 m0, s22
	s_nop 0
	global_load_lds_dwordx4 v[212:213], off
	v_lshl_add_u64 v[212:213], s[20:21], 0, v[132:133]
	s_add_i32 m0, s22, 0x2000
	s_nop 0
	global_load_lds_dwordx4 v[212:213], off
	v_lshl_add_u64 v[212:213], v[230:231], 0, s[56:57]
	s_mov_b32 m0, s40
	s_nop 0
	global_load_lds_dwordx4 v[212:213], off
	v_lshl_add_u64 v[212:213], v[232:233], 0, s[56:57]
	s_mov_b32 m0, s41
	s_nop 0
	global_load_lds_dwordx4 v[212:213], off
	s_nop 0
	s_nop 0
	s_nop 0
	s_waitcnt vmcnt(8)
	s_waitcnt lgkmcnt(0)
	s_barrier
	v_mfma_f32_16x16x32_bf16 v[64:67], v[142:145], v[184:187], v[64:67]
	v_mfma_f32_16x16x32_bf16 v[56:59], v[156:159], v[184:187], v[56:59]
	v_mfma_f32_16x16x32_bf16 v[48:51], v[142:145], v[192:195], v[48:51]
	v_mfma_f32_16x16x32_bf16 v[40:43], v[156:159], v[192:195], v[40:43]
	v_mfma_f32_16x16x32_bf16 v[32:35], v[142:145], v[200:203], v[32:35]
	v_mfma_f32_16x16x32_bf16 v[24:27], v[156:159], v[200:203], v[24:27]
	v_mfma_f32_16x16x32_bf16 v[16:19], v[142:145], v[208:211], v[16:19]
	v_mfma_f32_16x16x32_bf16 v[8:11], v[156:159], v[208:211], v[8:11]
	v_mfma_f32_16x16x32_bf16 v[64:67], v[152:155], v[188:191], v[64:67]
	v_mfma_f32_16x16x32_bf16 v[56:59], v[160:163], v[188:191], v[56:59]
	v_mfma_f32_16x16x32_bf16 v[48:51], v[152:155], v[196:199], v[48:51]
	v_mfma_f32_16x16x32_bf16 v[40:43], v[160:163], v[196:199], v[40:43]
	v_mfma_f32_16x16x32_bf16 v[32:35], v[152:155], v[204:207], v[32:35]
	v_mfma_f32_16x16x32_bf16 v[24:27], v[160:163], v[204:207], v[24:27]
	v_mfma_f32_16x16x32_bf16 v[16:19], v[152:155], v[226:229], v[16:19]
	v_mfma_f32_16x16x32_bf16 v[8:11], v[160:163], v[226:229], v[8:11]
	v_mfma_f32_16x16x32_bf16 v[60:63], v[164:167], v[184:187], v[60:63]
	v_mfma_f32_16x16x32_bf16 v[52:55], v[176:179], v[184:187], v[52:55]
	v_mfma_f32_16x16x32_bf16 v[44:47], v[164:167], v[192:195], v[44:47]
	v_mfma_f32_16x16x32_bf16 v[36:39], v[176:179], v[192:195], v[36:39]
	v_mfma_f32_16x16x32_bf16 v[28:31], v[164:167], v[200:203], v[28:31]
	v_mfma_f32_16x16x32_bf16 v[20:23], v[176:179], v[200:203], v[20:23]
	v_mfma_f32_16x16x32_bf16 v[12:15], v[164:167], v[208:211], v[12:15]
	v_mfma_f32_16x16x32_bf16 v[4:7], v[176:179], v[208:211], v[4:7]
	v_mfma_f32_16x16x32_bf16 v[60:63], v[172:175], v[188:191], v[60:63]
	v_mfma_f32_16x16x32_bf16 v[52:55], v[180:183], v[188:191], v[52:55]
	v_mfma_f32_16x16x32_bf16 v[44:47], v[172:175], v[196:199], v[44:47]
	v_mfma_f32_16x16x32_bf16 v[36:39], v[180:183], v[196:199], v[36:39]
	v_mfma_f32_16x16x32_bf16 v[28:31], v[172:175], v[204:207], v[28:31]
	v_mfma_f32_16x16x32_bf16 v[20:23], v[180:183], v[204:207], v[20:23]
	v_mfma_f32_16x16x32_bf16 v[12:15], v[172:175], v[226:229], v[12:15]
	v_mfma_f32_16x16x32_bf16 v[4:7], v[180:183], v[226:229], v[4:7]
	s_barrier
	s_add_i32 s46, s46, 2
	s_add_u32 s18, s18, 0x100
	s_addc_u32 s19, s19, 0
	s_add_u32 s44, s44, 0x100
	s_addc_u32 s45, s45, 0
	s_cmp_gt_u32 s46, 29
	s_cbranch_scc0 .LBB0_1432
	s_and_b64 vcc, exec, s[4:5]
	s_cbranch_vccz .LBB0_1435
	s_barrier

; #define PG8_STAGE(bufoff, gbase, voff) do { _Pragma("unroll") for (int _i = 0; _i < 2; ++_i) \
;         __builtin_amdgcn_global_load_lds((const unsigned*)((const char*)(gbase) + (voff)[_i]), (PG8_LAS unsigned*)(lds + (bufoff) + ldsw + _i * 8192), 16, 0, 0); } while (0)
; #define PG8_LDA(dst, b, h) do { _Pragma("unroll") for (int m = 0; m < 4; ++m) _Pragma("unroll") for (int k = 0; k < 2; ++k) dst[m][k] = *(const PG8_LAS bf16x8*)(lds + PG8_SA(b, h) + aoffk[k] + m * 2048); } while (0)
; #define PG8_LDB(dst, b, h) do { _Pragma("unroll") for (int n = 0; n < 2; ++n) _Pragma("unroll") for (int k = 0; k < 2; ++k) dst[n][k] = *(const PG8_LAS bf16x8*)(lds + PG8_SB(b, h) + boffk[k] + n * 2048); } while (0)
; #define PG8_MMA(ai, bj, At, Bt) do { __builtin_amdgcn_s_setprio(1); _Pragma("unroll") for (int m = 0; m < 4; ++m) _Pragma("unroll") for (int n = 0; n < 2; ++n) _Pragma("unroll") for (int k = 0; k < 2; ++k) \
;         acc[ai][bj][m][n] = __builtin_amdgcn_mfma_f32_16x16x32_bf16(Bt[n][k], At[m][k], acc[ai][bj][m][n], 0, 0, 0); __builtin_amdgcn_s_setprio(0); } while (0)
; #define PG8_WAIT_V(n) asm volatile("s_waitcnt vmcnt(" #n ")" ::: "memory")
; #define PG8_WAIT_L(n) asm volatile("s_waitcnt lgkmcnt(" #n ")" ::: "memory")
; template <class Epi, class Sched, bool ALIGN_EPI = false, bool SP2 = false>
; __device__ __forceinline__ void gemm_phase(PG8_LAS unsigned char* lds, const Gemm g, const Sched& S, const Epi& E) {
;     ...
;         for (int t = 0; t < nt; t += 2) {
;             const bool last = (t == nt - 2);
;             const char* a1 = cA + (size_t)(t + 1) * kstep;
;             const char* a2 = last ? nA : cA + (size_t)(t + 2) * kstep; const char* b2 = last ? nB : cB + (size_t)(t + 2) * kstep;
;             const char* a3 = a2 + kstep; const char* b3 = b2 + kstep;
;             if (last && has_next) S.a_ready(nxt);
;             if constexpr (SP2) {
;             PG8_LDB(B0, 0, 0); PG8_LDB(B1, 0, 1); PG8_SCHED; PG8_LDA(At, 0, 0); PG8_STAGE(PG8_SA(1, 1), a1 + hstepA, voffA);
;             PG8_WAIT_V(8); PG8_WAIT_L(0); PG8_BAR; PG8_MMA(0, 0, At, B0); PG8_MMA(0, 1, At, B1); PG8_BAR; PG8_SCHED;
;             PG8_LDA(At, 0, 1); PG8_STAGE(PG8_SB(0, 0), b2, voffB); PG8_STAGE(PG8_SB(0, 1), b2 + hstepB, voffB); PG8_STAGE(PG8_SA(0, 0), a2, voffA);
;             PG8_WAIT_V(8); PG8_WAIT_L(0); PG8_BAR; PG8_MMA(1, 0, At, B0); PG8_MMA(1, 1, At, B1); PG8_BAR; PG8_SCHED;
.LBB0_1592:
	s_add_i32 s50, s16, 2
	s_add_u32 s14, s12, 0x100
	s_addc_u32 s15, s13, 0
	s_add_i32 s51, 0, 0x10000
	s_cmp_eq_u32 s7, s16
	v_add_u32_e32 v142, s51, v145
	s_cselect_b32 s19, s9, s15
	s_cselect_b32 s18, s8, s14
	v_add_u32_e32 v143, s51, v146
	ds_read_b128 v[150:153], v142
	ds_read_b128 v[154:157], v143
	v_add_u32_e32 v142, s53, v145
	s_cselect_b32 s17, s11, s49
	s_cselect_b32 s16, s10, s48
	s_add_i32 s52, 0, 0x14000
	v_add_u32_e32 v143, s53, v146
	ds_read_b128 v[158:161], v142
	ds_read_b128 v[162:165], v143
	v_add_u32_e32 v142, s52, v145
	v_add_u32_e32 v143, s52, v146
	ds_read_b128 v[172:175], v142
	ds_read_b128 v[176:179], v143
	v_add_u32_e32 v142, s54, v145
	v_add_u32_e32 v143, s54, v146
	ds_read_b128 v[180:183], v142
	ds_read_b128 v[184:187], v143
	v_lshl_add_u64 v[142:143], s[12:13], 0, v[138:139]
	s_add_i32 m0, s26, 0xc000
	ds_read_b128 v[188:191], v148
	ds_read_b128 v[192:195], v148 offset:1024
	ds_read_b128 v[196:199], v148 offset:2048
	ds_read_b128 v[200:203], v148 offset:3072
	ds_read_b128 v[204:207], v148 offset:4096
	ds_read_b128 v[208:211], v148 offset:5120
	ds_read_b128 v[226:229], v148 offset:6144
	ds_read_b128 v[230:233], v148 offset:7168
	global_load_lds_dwordx4 v[142:143], off
	v_lshl_add_u64 v[142:143], s[12:13], 0, v[140:141]
	s_add_i32 m0, s26, 0xe000
	s_nop 0
	global_load_lds_dwordx4 v[142:143], off
	s_nop 0
	s_nop 0
	s_nop 0
	s_nop 0
	s_nop 0
	s_nop 0
	s_nop 0
	s_nop 0
	s_nop 0
	s_waitcnt vmcnt(8)
	s_waitcnt lgkmcnt(0)
	s_barrier
	v_mfma_f32_16x16x32_bf16 v[128:131], v[150:153], v[188:191], v[128:131]
	v_mfma_f32_16x16x32_bf16 v[124:127], v[158:161], v[188:191], v[124:127]
	v_mfma_f32_16x16x32_bf16 v[120:123], v[150:153], v[196:199], v[120:123]
	v_mfma_f32_16x16x32_bf16 v[112:115], v[158:161], v[196:199], v[112:115]
	v_mfma_f32_16x16x32_bf16 v[104:107], v[150:153], v[204:207], v[104:107]
	v_mfma_f32_16x16x32_bf16 v[96:99], v[158:161], v[204:207], v[96:99]
	v_mfma_f32_16x16x32_bf16 v[88:91], v[150:153], v[226:229], v[88:91]
	v_mfma_f32_16x16x32_bf16 v[80:83], v[158:161], v[226:229], v[80:83]
	v_mfma_f32_16x16x32_bf16 v[128:131], v[154:157], v[192:195], v[128:131]
	v_mfma_f32_16x16x32_bf16 v[124:127], v[162:165], v[192:195], v[124:127]
	v_mfma_f32_16x16x32_bf16 v[120:123], v[154:157], v[200:203], v[120:123]
	v_mfma_f32_16x16x32_bf16 v[112:115], v[162:165], v[200:203], v[112:115]
	v_mfma_f32_16x16x32_bf16 v[104:107], v[154:157], v[208:211], v[104:107]
	v_mfma_f32_16x16x32_bf16 v[96:99], v[162:165], v[208:211], v[96:99]
	v_mfma_f32_16x16x32_bf16 v[88:91], v[154:157], v[230:233], v[88:91]
	v_mfma_f32_16x16x32_bf16 v[80:83], v[162:165], v[230:233], v[80:83]
	v_mfma_f32_16x16x32_bf16 v[116:119], v[172:175], v[188:191], v[116:119]
	v_mfma_f32_16x16x32_bf16 v[108:111], v[180:183], v[188:191], v[108:111]
	v_mfma_f32_16x16x32_bf16 v[100:103], v[172:175], v[196:199], v[100:103]
	v_mfma_f32_16x16x32_bf16 v[92:95], v[180:183], v[196:199], v[92:95]
	v_mfma_f32_16x16x32_bf16 v[84:87], v[172:175], v[204:207], v[84:87]
	v_mfma_f32_16x16x32_bf16 v[76:79], v[180:183], v[204:207], v[76:79]
	v_mfma_f32_16x16x32_bf16 v[72:75], v[172:175], v[226:229], v[72:75]
	v_mfma_f32_16x16x32_bf16 v[68:71], v[180:183], v[226:229], v[68:71]
	v_mfma_f32_16x16x32_bf16 v[116:119], v[176:179], v[192:195], v[116:119]
	v_mfma_f32_16x16x32_bf16 v[108:111], v[184:187], v[192:195], v[108:111]
	v_mfma_f32_16x16x32_bf16 v[100:103], v[176:179], v[200:203], v[100:103]
	v_mfma_f32_16x16x32_bf16 v[92:95], v[184:187], v[200:203], v[92:95]
	v_mfma_f32_16x16x32_bf16 v[84:87], v[176:179], v[208:211], v[84:87]
	v_mfma_f32_16x16x32_bf16 v[76:79], v[184:187], v[208:211], v[76:79]
	v_mfma_f32_16x16x32_bf16 v[72:75], v[176:179], v[230:233], v[72:75]
	v_mfma_f32_16x16x32_bf16 v[68:71], v[184:187], v[230:233], v[68:71]
	s_barrier
	s_add_i32 s12, s51, s25
	v_lshl_add_u64 v[142:143], s[16:17], 0, v[2:3]
	s_mov_b32 m0, s12
	ds_read_b128 v[188:191], v148 offset:16384
	ds_read_b128 v[192:195], v148 offset:17408
	ds_read_b128 v[196:199], v148 offset:18432
	ds_read_b128 v[200:203], v148 offset:19456
	ds_read_b128 v[204:207], v148 offset:20480
	ds_read_b128 v[208:211], v148 offset:21504
	ds_read_b128 v[226:229], v148 offset:22528
	ds_read_b128 v[230:233], v148 offset:23552
	global_load_lds_dwordx4 v[142:143], off
	s_add_i32 m0, s12, 0x2000
	s_add_u32 s12, s16, 0x160000
	v_lshl_add_u64 v[166:167], s[16:17], 0, v[136:137]
	s_addc_u32 s13, s17, 0
	s_add_i32 s51, s52, s25
	global_load_lds_dwordx4 v[166:167], off
	v_lshl_add_u64 v[212:213], s[12:13], 0, v[2:3]
	s_mov_b32 m0, s51
	v_lshl_add_u64 v[220:221], s[18:19], 0, v[134:135]
	global_load_lds_dwordx4 v[212:213], off
	v_lshl_add_u64 v[212:213], s[12:13], 0, v[136:137]
	s_add_i32 m0, s51, 0x2000
	s_nop 0
	global_load_lds_dwordx4 v[212:213], off
	v_lshl_add_u64 v[212:213], s[18:19], 0, v[132:133]
	s_mov_b32 m0, s26
	s_nop 0
	global_load_lds_dwordx4 v[212:213], off
	s_mov_b32 m0, s27
	s_nop 0
	global_load_lds_dwordx4 v[220:221], off
	s_nop 0
	s_nop 0
	s_nop 0
	s_nop 0
	s_waitcnt vmcnt(8)
	s_waitcnt lgkmcnt(0)
	s_barrier
; #define PG8_STAGE(bufoff, gbase, voff) do { _Pragma("unroll") for (int _i = 0; _i < 2; ++_i) \
;         __builtin_amdgcn_global_load_lds((const unsigned*)((const char*)(gbase) + (voff)[_i]), (PG8_LAS unsigned*)(lds + (bufoff) + ldsw + _i * 8192), 16, 0, 0); } while (0)
; #define PG8_LDA(dst, b, h) do { _Pragma("unroll") for (int m = 0; m < 4; ++m) _Pragma("unroll") for (int k = 0; k < 2; ++k) dst[m][k] = *(const PG8_LAS bf16x8*)(lds + PG8_SA(b, h) + aoffk[k] + m * 2048); } while (0)
; #define PG8_LDB(dst, b, h) do { _Pragma("unroll") for (int n = 0; n < 2; ++n) _Pragma("unroll") for (int k = 0; k < 2; ++k) dst[n][k] = *(const PG8_LAS bf16x8*)(lds + PG8_SB(b, h) + boffk[k] + n * 2048); } while (0)
; #define PG8_MMA(ai, bj, At, Bt) do { __builtin_amdgcn_s_setprio(1); _Pragma("unroll") for (int m = 0; m < 4; ++m) _Pragma("unroll") for (int n = 0; n < 2; ++n) _Pragma("unroll") for (int k = 0; k < 2; ++k) \
;         acc[ai][bj][m][n] = __builtin_amdgcn_mfma_f32_16x16x32_bf16(Bt[n][k], At[m][k], acc[ai][bj][m][n], 0, 0, 0); __builtin_amdgcn_s_setprio(0); } while (0)
; #define PG8_WAIT_V(n) asm volatile("s_waitcnt vmcnt(" #n ")" ::: "memory")
; #define PG8_WAIT_L(n) asm volatile("s_waitcnt lgkmcnt(" #n ")" ::: "memory")
; #define PG8_BAR __builtin_amdgcn_s_barrier()
; #define PG8_SCHED __builtin_amdgcn_sched_barrier(0)
; template <class Epi, class Sched, bool ALIGN_EPI = false, bool SP2 = false>
; __device__ __forceinline__ void gemm_phase(PG8_LAS unsigned char* lds, const Gemm g, const Sched& S, const Epi& E) {
;     ...
;             PG8_WAIT_V(8); PG8_WAIT_L(0); PG8_BAR; PG8_MMA(1, 0, At, B0); PG8_MMA(1, 1, At, B1); PG8_BAR; PG8_SCHED;
;             PG8_LDB(B0, 1, 0); PG8_LDB(B1, 1, 1); PG8_SCHED; PG8_LDA(At, 1, 0); PG8_STAGE(PG8_SA(0, 1), a2 + hstepA, voffA);
;             PG8_WAIT_V(8); PG8_WAIT_L(0); PG8_BAR; PG8_MMA(0, 0, At, B0); PG8_MMA(0, 1, At, B1); PG8_BAR; PG8_SCHED;
	v_mfma_f32_16x16x32_bf16 v[64:67], v[150:153], v[188:191], v[64:67]
	v_mfma_f32_16x16x32_bf16 v[60:63], v[158:161], v[188:191], v[60:63]
	v_mfma_f32_16x16x32_bf16 v[56:59], v[150:153], v[196:199], v[56:59]
	v_mfma_f32_16x16x32_bf16 v[48:51], v[158:161], v[196:199], v[48:51]
	v_mfma_f32_16x16x32_bf16 v[40:43], v[150:153], v[204:207], v[40:43]
	v_mfma_f32_16x16x32_bf16 v[32:35], v[158:161], v[204:207], v[32:35]
	v_mfma_f32_16x16x32_bf16 v[24:27], v[150:153], v[226:229], v[24:27]
	v_mfma_f32_16x16x32_bf16 v[16:19], v[158:161], v[226:229], v[16:19]
	v_mfma_f32_16x16x32_bf16 v[64:67], v[154:157], v[192:195], v[64:67]
	v_mfma_f32_16x16x32_bf16 v[60:63], v[162:165], v[192:195], v[60:63]
	v_mfma_f32_16x16x32_bf16 v[56:59], v[154:157], v[200:203], v[56:59]
	v_mfma_f32_16x16x32_bf16 v[48:51], v[162:165], v[200:203], v[48:51]
	v_mfma_f32_16x16x32_bf16 v[40:43], v[154:157], v[208:211], v[40:43]
	v_mfma_f32_16x16x32_bf16 v[32:35], v[162:165], v[208:211], v[32:35]
	v_mfma_f32_16x16x32_bf16 v[24:27], v[154:157], v[230:233], v[24:27]
	v_mfma_f32_16x16x32_bf16 v[16:19], v[162:165], v[230:233], v[16:19]
	v_mfma_f32_16x16x32_bf16 v[52:55], v[172:175], v[188:191], v[52:55]
	v_mfma_f32_16x16x32_bf16 v[44:47], v[180:183], v[188:191], v[44:47]
	v_mfma_f32_16x16x32_bf16 v[36:39], v[172:175], v[196:199], v[36:39]
	v_mfma_f32_16x16x32_bf16 v[28:31], v[180:183], v[196:199], v[28:31]
	v_mfma_f32_16x16x32_bf16 v[20:23], v[172:175], v[204:207], v[20:23]
	v_mfma_f32_16x16x32_bf16 v[12:15], v[180:183], v[204:207], v[12:15]
	v_mfma_f32_16x16x32_bf16 v[8:11], v[172:175], v[226:229], v[8:11]
	v_mfma_f32_16x16x32_bf16 v[4:7], v[180:183], v[226:229], v[4:7]
	v_mfma_f32_16x16x32_bf16 v[52:55], v[176:179], v[192:195], v[52:55]
	v_mfma_f32_16x16x32_bf16 v[44:47], v[184:187], v[192:195], v[44:47]
	v_mfma_f32_16x16x32_bf16 v[36:39], v[176:179], v[200:203], v[36:39]
	v_mfma_f32_16x16x32_bf16 v[28:31], v[184:187], v[200:203], v[28:31]
	v_mfma_f32_16x16x32_bf16 v[20:23], v[176:179], v[208:211], v[20:23]
	v_mfma_f32_16x16x32_bf16 v[12:15], v[184:187], v[208:211], v[12:15]
	v_mfma_f32_16x16x32_bf16 v[8:11], v[176:179], v[230:233], v[8:11]
	v_mfma_f32_16x16x32_bf16 v[4:7], v[184:187], v[230:233], v[4:7]
	s_barrier
	s_add_i32 s51, 0, 0x18000
	v_add_u32_e32 v149, s51, v145
	v_add_u32_e32 v154, s51, v146
	ds_read_b128 v[150:153], v149
	ds_read_b128 v[154:157], v154
	v_add_u32_e32 v149, s55, v145
	v_add_u32_e32 v162, s55, v146
	s_add_i32 s52, 0, 0x1c000
	ds_read_b128 v[158:161], v149
	ds_read_b128 v[162:165], v162
	v_add_u32_e32 v149, s52, v145
	v_add_u32_e32 v168, s52, v146
	ds_read_b128 v[172:175], v149
	ds_read_b128 v[176:179], v168
	v_add_u32_e32 v149, s56, v145
	v_add_u32_e32 v168, s56, v146
	ds_read_b128 v[180:183], v149
	ds_read_b128 v[184:187], v168
	s_add_u32 s12, s18, 0x160000
	s_addc_u32 s13, s19, 0
	s_mov_b32 m0, s28
	v_lshl_add_u64 v[234:235], s[12:13], 0, v[132:133]
	ds_read_b128 v[188:191], v148 offset:32768
	ds_read_b128 v[192:195], v148 offset:33792
	ds_read_b128 v[196:199], v148 offset:34816
	ds_read_b128 v[200:203], v148 offset:35840
	ds_read_b128 v[204:207], v148 offset:36864
	ds_read_b128 v[208:211], v148 offset:37888
	ds_read_b128 v[226:229], v148 offset:38912
	ds_read_b128 v[230:233], v148 offset:39936
	global_load_lds_dwordx4 v[234:235], off
	v_lshl_add_u64 v[234:235], s[12:13], 0, v[134:135]
	s_mov_b32 m0, s29
	s_nop 0
	global_load_lds_dwordx4 v[234:235], off
	s_nop 0
	s_nop 0
	s_waitcnt vmcnt(8)
	s_waitcnt lgkmcnt(0)
	s_barrier
	v_mfma_f32_16x16x32_bf16 v[128:131], v[150:153], v[188:191], v[128:131]
	v_mfma_f32_16x16x32_bf16 v[124:127], v[158:161], v[188:191], v[124:127]
	v_mfma_f32_16x16x32_bf16 v[120:123], v[150:153], v[196:199], v[120:123]
	v_mfma_f32_16x16x32_bf16 v[112:115], v[158:161], v[196:199], v[112:115]
	v_mfma_f32_16x16x32_bf16 v[104:107], v[150:153], v[204:207], v[104:107]
	v_mfma_f32_16x16x32_bf16 v[96:99], v[158:161], v[204:207], v[96:99]
	v_mfma_f32_16x16x32_bf16 v[88:91], v[150:153], v[226:229], v[88:91]
	v_mfma_f32_16x16x32_bf16 v[80:83], v[158:161], v[226:229], v[80:83]
	v_mfma_f32_16x16x32_bf16 v[128:131], v[154:157], v[192:195], v[128:131]
	v_mfma_f32_16x16x32_bf16 v[124:127], v[162:165], v[192:195], v[124:127]
	v_mfma_f32_16x16x32_bf16 v[120:123], v[154:157], v[200:203], v[120:123]
	v_mfma_f32_16x16x32_bf16 v[112:115], v[162:165], v[200:203], v[112:115]
	v_mfma_f32_16x16x32_bf16 v[104:107], v[154:157], v[208:211], v[104:107]
	v_mfma_f32_16x16x32_bf16 v[96:99], v[162:165], v[208:211], v[96:99]
	v_mfma_f32_16x16x32_bf16 v[88:91], v[154:157], v[230:233], v[88:91]
	v_mfma_f32_16x16x32_bf16 v[80:83], v[162:165], v[230:233], v[80:83]
	v_mfma_f32_16x16x32_bf16 v[116:119], v[172:175], v[188:191], v[116:119]
	v_mfma_f32_16x16x32_bf16 v[108:111], v[180:183], v[188:191], v[108:111]
	v_mfma_f32_16x16x32_bf16 v[100:103], v[172:175], v[196:199], v[100:103]
	v_mfma_f32_16x16x32_bf16 v[92:95], v[180:183], v[196:199], v[92:95]
	v_mfma_f32_16x16x32_bf16 v[84:87], v[172:175], v[204:207], v[84:87]
	v_mfma_f32_16x16x32_bf16 v[76:79], v[180:183], v[204:207], v[76:79]
	v_mfma_f32_16x16x32_bf16 v[72:75], v[172:175], v[226:229], v[72:75]
	v_mfma_f32_16x16x32_bf16 v[68:71], v[180:183], v[226:229], v[68:71]
	v_mfma_f32_16x16x32_bf16 v[116:119], v[176:179], v[192:195], v[116:119]
	v_mfma_f32_16x16x32_bf16 v[108:111], v[184:187], v[192:195], v[108:111]
	v_mfma_f32_16x16x32_bf16 v[100:103], v[176:179], v[200:203], v[100:103]
	v_mfma_f32_16x16x32_bf16 v[92:95], v[184:187], v[200:203], v[92:95]
	v_mfma_f32_16x16x32_bf16 v[84:87], v[176:179], v[208:211], v[84:87]
	v_mfma_f32_16x16x32_bf16 v[76:79], v[184:187], v[208:211], v[76:79]
	v_mfma_f32_16x16x32_bf16 v[72:75], v[176:179], v[230:233], v[72:75]
	v_mfma_f32_16x16x32_bf16 v[68:71], v[184:187], v[230:233], v[68:71]
	s_barrier
; #define PG8_STAGE(bufoff, gbase, voff) do { _Pragma("unroll") for (int _i = 0; _i < 2; ++_i) \
;         __builtin_amdgcn_global_load_lds((const unsigned*)((const char*)(gbase) + (voff)[_i]), (PG8_LAS unsigned*)(lds + (bufoff) + ldsw + _i * 8192), 16, 0, 0); } while (0)
; #define PG8_LDA(dst, b, h) do { _Pragma("unroll") for (int m = 0; m < 4; ++m) _Pragma("unroll") for (int k = 0; k < 2; ++k) dst[m][k] = *(const PG8_LAS bf16x8*)(lds + PG8_SA(b, h) + aoffk[k] + m * 2048); } while (0)
; #define PG8_MMA(ai, bj, At, Bt) do { __builtin_amdgcn_s_setprio(1); _Pragma("unroll") for (int m = 0; m < 4; ++m) _Pragma("unroll") for (int n = 0; n < 2; ++n) _Pragma("unroll") for (int k = 0; k < 2; ++k) \
;         acc[ai][bj][m][n] = __builtin_amdgcn_mfma_f32_16x16x32_bf16(Bt[n][k], At[m][k], acc[ai][bj][m][n], 0, 0, 0); __builtin_amdgcn_s_setprio(0); } while (0)
; #define PG8_WAIT_V(n) asm volatile("s_waitcnt vmcnt(" #n ")" ::: "memory")
; #define PG8_WAIT_L(n) asm volatile("s_waitcnt lgkmcnt(" #n ")" ::: "memory")
; #define PG8_BAR __builtin_amdgcn_s_barrier()
; #define PG8_SCHED __builtin_amdgcn_sched_barrier(0)
; template <class Epi, class Sched, bool ALIGN_EPI = false, bool SP2 = false>
; __device__ __forceinline__ void gemm_phase(PG8_LAS unsigned char* lds, const Gemm g, const Sched& S, const Epi& E) {
;     ...
;             PG8_LDA(At, 1, 1); PG8_STAGE(PG8_SB(1, 0), b3, voffB); PG8_STAGE(PG8_SB(1, 1), b3 + hstepB, voffB); PG8_STAGE(PG8_SA(1, 0), a3, voffA);
;             PG8_WAIT_V(8); PG8_WAIT_L(0); PG8_BAR; PG8_MMA(1, 0, At, B0); PG8_MMA(1, 1, At, B1); PG8_BAR; PG8_SCHED;
;     ...
;         if constexpr (ALIGN_EPI) { if (wr == 0) PG8_BAR; }
	s_add_i32 s12, s51, s25
	v_lshl_add_u64 v[142:143], v[142:143], 0, s[58:59]
	s_mov_b32 m0, s12
	ds_read_b128 v[188:191], v148 offset:49152
	ds_read_b128 v[192:195], v148 offset:50176
	ds_read_b128 v[196:199], v148 offset:51200
	ds_read_b128 v[200:203], v148 offset:52224
	ds_read_b128 v[204:207], v148 offset:53248
	ds_read_b128 v[208:211], v148 offset:54272
	ds_read_b128 v[226:229], v148 offset:55296
	ds_read_b128 v[230:233], v148 offset:56320
	global_load_lds_dwordx4 v[142:143], off
	s_add_i32 m0, s12, 0x2000
	s_add_u32 s12, s16, 0x160080
	v_lshl_add_u64 v[142:143], v[166:167], 0, s[58:59]
	s_addc_u32 s13, s17, 0
	s_add_i32 s16, s52, s25
	global_load_lds_dwordx4 v[142:143], off
	v_lshl_add_u64 v[142:143], s[12:13], 0, v[2:3]
	s_mov_b32 m0, s16
	s_nop 0
	global_load_lds_dwordx4 v[142:143], off
	v_lshl_add_u64 v[142:143], s[12:13], 0, v[136:137]
	s_add_i32 m0, s16, 0x2000
	s_nop 0
	global_load_lds_dwordx4 v[142:143], off
	v_lshl_add_u64 v[142:143], v[212:213], 0, s[58:59]
	s_mov_b32 m0, s36
	s_nop 0
	global_load_lds_dwordx4 v[142:143], off
	v_lshl_add_u64 v[142:143], v[220:221], 0, s[58:59]
	s_mov_b32 m0, s37
	s_nop 0
	global_load_lds_dwordx4 v[142:143], off
	s_nop 0
	s_nop 0
	s_nop 0
	s_waitcnt vmcnt(8)
	s_waitcnt lgkmcnt(0)
	s_barrier
	v_mfma_f32_16x16x32_bf16 v[64:67], v[150:153], v[188:191], v[64:67]
	v_mfma_f32_16x16x32_bf16 v[60:63], v[158:161], v[188:191], v[60:63]
	v_mfma_f32_16x16x32_bf16 v[56:59], v[150:153], v[196:199], v[56:59]
	v_mfma_f32_16x16x32_bf16 v[48:51], v[158:161], v[196:199], v[48:51]
	v_mfma_f32_16x16x32_bf16 v[40:43], v[150:153], v[204:207], v[40:43]
	v_mfma_f32_16x16x32_bf16 v[32:35], v[158:161], v[204:207], v[32:35]
	v_mfma_f32_16x16x32_bf16 v[24:27], v[150:153], v[226:229], v[24:27]
	v_mfma_f32_16x16x32_bf16 v[16:19], v[158:161], v[226:229], v[16:19]
	v_mfma_f32_16x16x32_bf16 v[64:67], v[154:157], v[192:195], v[64:67]
	v_mfma_f32_16x16x32_bf16 v[60:63], v[162:165], v[192:195], v[60:63]
	v_mfma_f32_16x16x32_bf16 v[56:59], v[154:157], v[200:203], v[56:59]
	v_mfma_f32_16x16x32_bf16 v[48:51], v[162:165], v[200:203], v[48:51]
	v_mfma_f32_16x16x32_bf16 v[40:43], v[154:157], v[208:211], v[40:43]
	v_mfma_f32_16x16x32_bf16 v[32:35], v[162:165], v[208:211], v[32:35]
	v_mfma_f32_16x16x32_bf16 v[24:27], v[154:157], v[230:233], v[24:27]
	v_mfma_f32_16x16x32_bf16 v[16:19], v[162:165], v[230:233], v[16:19]
	v_mfma_f32_16x16x32_bf16 v[52:55], v[172:175], v[188:191], v[52:55]
	v_mfma_f32_16x16x32_bf16 v[44:47], v[180:183], v[188:191], v[44:47]
	v_mfma_f32_16x16x32_bf16 v[36:39], v[172:175], v[196:199], v[36:39]
	v_mfma_f32_16x16x32_bf16 v[28:31], v[180:183], v[196:199], v[28:31]
	v_mfma_f32_16x16x32_bf16 v[20:23], v[172:175], v[204:207], v[20:23]
	v_mfma_f32_16x16x32_bf16 v[12:15], v[180:183], v[204:207], v[12:15]
	v_mfma_f32_16x16x32_bf16 v[8:11], v[172:175], v[226:229], v[8:11]
	v_mfma_f32_16x16x32_bf16 v[4:7], v[180:183], v[226:229], v[4:7]
	v_mfma_f32_16x16x32_bf16 v[52:55], v[176:179], v[192:195], v[52:55]
	v_mfma_f32_16x16x32_bf16 v[44:47], v[184:187], v[192:195], v[44:47]
	v_mfma_f32_16x16x32_bf16 v[36:39], v[176:179], v[200:203], v[36:39]
	v_mfma_f32_16x16x32_bf16 v[28:31], v[184:187], v[200:203], v[28:31]
	v_mfma_f32_16x16x32_bf16 v[20:23], v[176:179], v[208:211], v[20:23]
	v_mfma_f32_16x16x32_bf16 v[12:15], v[184:187], v[208:211], v[12:15]
	v_mfma_f32_16x16x32_bf16 v[8:11], v[176:179], v[230:233], v[8:11]
	v_mfma_f32_16x16x32_bf16 v[4:7], v[184:187], v[230:233], v[4:7]
	s_barrier
	s_add_u32 s48, s48, 0x100
	s_addc_u32 s49, s49, 0
	s_cmp_ge_i32 s50, s43
	s_mov_b64 s[12:13], s[14:15]
	s_mov_b32 s16, s50
	s_cbranch_scc0 .LBB0_1592
	s_and_b64 vcc, exec, s[4:5]
	s_cbranch_vccz .LBB0_1595
	s_barrier

; __global__ void __launch_bounds__(NTHR, 2) fwd_kernel(Args args) {
	.amdhsa_kernel _Z10fwd_kernel4Args
		.amdhsa_group_segment_fixed_size 0
		.amdhsa_private_segment_fixed_size 0
		.amdhsa_kernarg_size 456
		.amdhsa_user_sgpr_count 2
		.amdhsa_user_sgpr_dispatch_ptr 0
		.amdhsa_user_sgpr_queue_ptr 0
		.amdhsa_user_sgpr_kernarg_segment_ptr 1
		.amdhsa_user_sgpr_dispatch_id 0
		.amdhsa_user_sgpr_kernarg_preload_length 0
		.amdhsa_user_sgpr_kernarg_preload_offset 0
		.amdhsa_user_sgpr_private_segment_size 0
		.amdhsa_uses_dynamic_stack 0
		.amdhsa_enable_private_segment 0
		.amdhsa_system_sgpr_workgroup_id_x 1
		.amdhsa_system_sgpr_workgroup_id_y 0
		.amdhsa_system_sgpr_workgroup_id_z 0
		.amdhsa_system_sgpr_workgroup_info 0
		.amdhsa_system_vgpr_workitem_id 0
		.amdhsa_next_free_vgpr 256
		.amdhsa_next_free_sgpr 102
		.amdhsa_accum_offset 256
		.amdhsa_reserve_vcc 1
		.amdhsa_float_round_mode_32 0
		.amdhsa_float_round_mode_16_64 0
		.amdhsa_float_denorm_mode_32 3
		.amdhsa_float_denorm_mode_16_64 3
		.amdhsa_dx10_clamp 1
		.amdhsa_ieee_mode 1
		.amdhsa_fp16_overflow 0
		.amdhsa_tg_split 0
		.amdhsa_exception_fp_ieee_invalid_op 0
		.amdhsa_exception_fp_denorm_src 0
		.amdhsa_exception_fp_ieee_div_zero 0
		.amdhsa_exception_fp_ieee_overflow 0
		.amdhsa_exception_fp_ieee_underflow 0
		.amdhsa_exception_fp_ieee_inexact 0
		.amdhsa_exception_int_div_zero 0
	.end_amdhsa_kernel

; __global__ void __launch_bounds__(NTHR, 2) fwd_kernel(Args args) {
amdhsa.kernels:
  - .agpr_count:     0
    .args:
      - .offset:         0
        .size:           200
        .value_kind:     by_value
      - .offset:         200
        .size:           4
        .value_kind:     hidden_block_count_x
      - .offset:         204
        .size:           4
        .value_kind:     hidden_block_count_y
      - .offset:         208
        .size:           4
        .value_kind:     hidden_block_count_z
      - .offset:         212
        .size:           2
        .value_kind:     hidden_group_size_x
      - .offset:         214
        .size:           2
        .value_kind:     hidden_group_size_y
      - .offset:         216
        .size:           2
        .value_kind:     hidden_group_size_z
      - .offset:         218
        .size:           2
        .value_kind:     hidden_remainder_x
      - .offset:         220
        .size:           2
        .value_kind:     hidden_remainder_y
      - .offset:         222
        .size:           2
        .value_kind:     hidden_remainder_z
      - .offset:         240
        .size:           8
        .value_kind:     hidden_global_offset_x
      - .offset:         248
        .size:           8
        .value_kind:     hidden_global_offset_y
      - .offset:         256
        .size:           8
        .value_kind:     hidden_global_offset_z
      - .offset:         264
        .size:           2
        .value_kind:     hidden_grid_dims
      - .offset:         320
        .size:           4
        .value_kind:     hidden_dynamic_lds_size
    .group_segment_fixed_size: 0
    .kernarg_segment_align: 8
    .kernarg_segment_size: 456
    .language:       OpenCL C
    .language_version:
      - 2
      - 0
    .max_flat_workgroup_size: 512
    .name:           _Z10fwd_kernel4Args
    .private_segment_fixed_size: 0
    .sgpr_count:     108
    .sgpr_spill_count: 261
    .symbol:         _Z10fwd_kernel4Args.kd
    .uniform_work_group_size: 1
    .uses_dynamic_stack: false
    .vgpr_count:     256
    .vgpr_spill_count: 0
    .wavefront_size: 64
